# 60 redundant s_waitcnt lgkmcnt(0) directly after s_barrier at the head of GEMM MFMA blocks removed (LGKM already drained before the barrier)
# speedup vs baseline: 1.0093x; 1.0050x over previous
.LBB0_187:
	s_ashr_i32 s15, s14, 31
	s_lshl_b64 s[16:17], s[14:15], 19
	s_add_u32 s16, s30, s16
	s_addc_u32 s17, s31, s17
	s_and_b64 s[18:19], s[0:1], exec
	s_cselect_b32 s3, s17, s25
	s_cselect_b32 s15, s16, s24
	s_ashr_i32 s13, s12, 31
	s_lshl_b64 s[18:19], s[12:13], 19
	s_add_u32 s18, s34, s18
	s_addc_u32 s19, s35, s19
	s_and_b64 s[26:27], s[0:1], exec
	s_cselect_b32 s13, s19, s23
	s_cselect_b32 s21, s18, s22
	s_add_u32 s48, s22, 0x100
	s_addc_u32 s49, s23, 0
	s_add_u32 s22, s24, 0x40080
	s_addc_u32 s23, s25, 0
	s_mov_b32 s50, -2
	s_waitcnt vmcnt(0)
	s_add_u32 s24, s22, 0xfffc0080
	s_addc_u32 s25, s23, -1
	s_add_i32 s51, 0, 0x10000
	s_cmp_eq_u32 s50, 12
	s_cselect_b32 s27, s3, s25
	s_cselect_b32 s26, s15, s24
	v_add_u32_e32 v142, s51, v144
	s_cselect_b32 s25, s13, s49
	s_cselect_b32 s24, s21, s48
	s_add_i32 s54, 0, 0x14000
	ds_read_b128 v[138:141], v142
	ds_read_b128 v[146:149], v142 offset:1024
	ds_read_b128 v[150:153], v142 offset:2048
	ds_read_b128 v[154:157], v142 offset:3072
	v_add_u32_e32 v142, s54, v144
	ds_read_b128 v[158:161], v142
	ds_read_b128 v[162:165], v142 offset:1024
	ds_read_b128 v[166:169], v142 offset:2048
	ds_read_b128 v[170:173], v142 offset:3072
	v_lshl_add_u64 v[142:143], s[22:23], 0, v[136:137]
	s_add_i32 m0, s37, 0xc000
	ds_read_b128 v[174:177], v145
	ds_read_b128 v[178:181], v145 offset:1024
	ds_read_b128 v[182:185], v145 offset:2048
	ds_read_b128 v[186:189], v145 offset:3072
	ds_read_b128 v[190:193], v145 offset:4096
	ds_read_b128 v[194:197], v145 offset:5120
	ds_read_b128 v[198:201], v145 offset:6144
	ds_read_b128 v[202:205], v145 offset:7168
	global_load_lds_dwordx4 v[142:143], off
	v_lshl_add_u64 v[142:143], s[22:23], 0, v[134:135]
	s_add_i32 m0, s37, 0xe000
	s_nop 0
	global_load_lds_dwordx4 v[142:143], off
	s_waitcnt vmcnt(8)
	s_waitcnt lgkmcnt(0)
	s_barrier
	v_mfma_f32_16x16x32_bf16 v[124:127], v[138:141], v[174:177], 0
	v_mfma_f32_16x16x32_bf16 v[120:123], v[150:153], v[174:177], 0
	v_mfma_f32_16x16x32_bf16 v[112:115], v[138:141], v[182:185], 0
	v_mfma_f32_16x16x32_bf16 v[104:107], v[150:153], v[182:185], 0
	v_mfma_f32_16x16x32_bf16 v[96:99], v[138:141], v[190:193], 0
	v_mfma_f32_16x16x32_bf16 v[88:91], v[150:153], v[190:193], 0
	v_mfma_f32_16x16x32_bf16 v[80:83], v[138:141], v[198:201], 0
	v_mfma_f32_16x16x32_bf16 v[72:75], v[150:153], v[198:201], 0
	v_mfma_f32_16x16x32_bf16 v[124:127], v[146:149], v[178:181], v[124:127]
	v_mfma_f32_16x16x32_bf16 v[120:123], v[154:157], v[178:181], v[120:123]
	v_mfma_f32_16x16x32_bf16 v[112:115], v[146:149], v[186:189], v[112:115]
	v_mfma_f32_16x16x32_bf16 v[104:107], v[154:157], v[186:189], v[104:107]
	v_mfma_f32_16x16x32_bf16 v[96:99], v[146:149], v[194:197], v[96:99]
	v_mfma_f32_16x16x32_bf16 v[88:91], v[154:157], v[194:197], v[88:91]
	v_mfma_f32_16x16x32_bf16 v[80:83], v[146:149], v[202:205], v[80:83]
	v_mfma_f32_16x16x32_bf16 v[72:75], v[154:157], v[202:205], v[72:75]
	v_mfma_f32_16x16x32_bf16 v[116:119], v[158:161], v[174:177], 0
	v_mfma_f32_16x16x32_bf16 v[108:111], v[166:169], v[174:177], 0
	v_mfma_f32_16x16x32_bf16 v[100:103], v[158:161], v[182:185], 0
	v_mfma_f32_16x16x32_bf16 v[92:95], v[166:169], v[182:185], 0
	v_mfma_f32_16x16x32_bf16 v[84:87], v[158:161], v[190:193], 0
	v_mfma_f32_16x16x32_bf16 v[76:79], v[166:169], v[190:193], 0
	v_mfma_f32_16x16x32_bf16 v[68:71], v[158:161], v[198:201], 0
	v_mfma_f32_16x16x32_bf16 v[64:67], v[166:169], v[198:201], 0
	v_mfma_f32_16x16x32_bf16 v[116:119], v[162:165], v[178:181], v[116:119]
	v_mfma_f32_16x16x32_bf16 v[108:111], v[170:173], v[178:181], v[108:111]
	v_mfma_f32_16x16x32_bf16 v[100:103], v[162:165], v[186:189], v[100:103]
	v_mfma_f32_16x16x32_bf16 v[92:95], v[170:173], v[186:189], v[92:95]
	v_mfma_f32_16x16x32_bf16 v[84:87], v[162:165], v[194:197], v[84:87]
	v_mfma_f32_16x16x32_bf16 v[76:79], v[170:173], v[194:197], v[76:79]
	v_mfma_f32_16x16x32_bf16 v[68:71], v[162:165], v[202:205], v[68:71]
	v_mfma_f32_16x16x32_bf16 v[64:67], v[170:173], v[202:205], v[64:67]
	s_barrier
	s_add_i32 s51, s51, s36
	v_lshl_add_u64 v[142:143], s[24:25], 0, v[232:233]
	s_mov_b32 m0, s51
	ds_read_b128 v[174:177], v145 offset:16384
	ds_read_b128 v[178:181], v145 offset:17408
	ds_read_b128 v[182:185], v145 offset:18432
	ds_read_b128 v[186:189], v145 offset:19456
	ds_read_b128 v[190:193], v145 offset:20480
	ds_read_b128 v[194:197], v145 offset:21504
	ds_read_b128 v[198:201], v145 offset:22528
	ds_read_b128 v[202:205], v145 offset:23552
	global_load_lds_dwordx4 v[142:143], off
	s_add_i32 m0, s51, 0x2000
	s_add_u32 s52, s24, 0x40000
	v_lshl_add_u64 v[206:207], s[24:25], 0, v[132:133]
	s_addc_u32 s53, s25, 0
	s_add_i32 s51, s54, s36
	global_load_lds_dwordx4 v[206:207], off
	v_lshl_add_u64 v[208:209], s[52:53], 0, v[232:233]
	s_mov_b32 m0, s51
	v_lshl_add_u64 v[210:211], s[26:27], 0, v[130:131]
	global_load_lds_dwordx4 v[208:209], off
	v_lshl_add_u64 v[208:209], s[52:53], 0, v[132:133]
	s_add_i32 m0, s51, 0x2000
	s_nop 0
	global_load_lds_dwordx4 v[208:209], off
	v_lshl_add_u64 v[208:209], s[26:27], 0, v[128:129]
	s_waitcnt vmcnt(6)
	s_waitcnt lgkmcnt(0)
	s_barrier
	v_mfma_f32_16x16x32_bf16 v[60:63], v[138:141], v[174:177], 0
	v_mfma_f32_16x16x32_bf16 v[56:59], v[150:153], v[174:177], 0
	v_mfma_f32_16x16x32_bf16 v[48:51], v[138:141], v[182:185], 0
	v_mfma_f32_16x16x32_bf16 v[40:43], v[150:153], v[182:185], 0
	v_mfma_f32_16x16x32_bf16 v[32:35], v[138:141], v[190:193], 0
	v_mfma_f32_16x16x32_bf16 v[24:27], v[150:153], v[190:193], 0
	v_mfma_f32_16x16x32_bf16 v[16:19], v[138:141], v[198:201], 0
	v_mfma_f32_16x16x32_bf16 v[8:11], v[150:153], v[198:201], 0
	v_mfma_f32_16x16x32_bf16 v[60:63], v[146:149], v[178:181], v[60:63]
	v_mfma_f32_16x16x32_bf16 v[56:59], v[154:157], v[178:181], v[56:59]
	v_mfma_f32_16x16x32_bf16 v[48:51], v[146:149], v[186:189], v[48:51]
	v_mfma_f32_16x16x32_bf16 v[40:43], v[154:157], v[186:189], v[40:43]
	v_mfma_f32_16x16x32_bf16 v[32:35], v[146:149], v[194:197], v[32:35]
	v_mfma_f32_16x16x32_bf16 v[24:27], v[154:157], v[194:197], v[24:27]
	v_mfma_f32_16x16x32_bf16 v[16:19], v[146:149], v[202:205], v[16:19]
	v_mfma_f32_16x16x32_bf16 v[8:11], v[154:157], v[202:205], v[8:11]
	v_mfma_f32_16x16x32_bf16 v[52:55], v[158:161], v[174:177], 0
	v_mfma_f32_16x16x32_bf16 v[44:47], v[166:169], v[174:177], 0
	v_mfma_f32_16x16x32_bf16 v[36:39], v[158:161], v[182:185], 0
	v_mfma_f32_16x16x32_bf16 v[28:31], v[166:169], v[182:185], 0
	v_mfma_f32_16x16x32_bf16 v[20:23], v[158:161], v[190:193], 0
	v_mfma_f32_16x16x32_bf16 v[12:15], v[166:169], v[190:193], 0
	v_mfma_f32_16x16x32_bf16 v[4:7], v[158:161], v[198:201], 0
	v_mfma_f32_16x16x32_bf16 v[0:3], v[166:169], v[198:201], 0
	v_mfma_f32_16x16x32_bf16 v[52:55], v[162:165], v[178:181], v[52:55]
	v_mfma_f32_16x16x32_bf16 v[44:47], v[170:173], v[178:181], v[44:47]
	v_mfma_f32_16x16x32_bf16 v[36:39], v[162:165], v[186:189], v[36:39]
	v_mfma_f32_16x16x32_bf16 v[28:31], v[170:173], v[186:189], v[28:31]
	v_mfma_f32_16x16x32_bf16 v[20:23], v[162:165], v[194:197], v[20:23]
	v_mfma_f32_16x16x32_bf16 v[12:15], v[170:173], v[194:197], v[12:15]
	v_mfma_f32_16x16x32_bf16 v[4:7], v[162:165], v[202:205], v[4:7]
	v_mfma_f32_16x16x32_bf16 v[0:3], v[170:173], v[202:205], v[0:3]
	s_barrier
	s_branch .Lzmid_1
.LBB0_188:
	s_add_u32 s24, s22, 0xfffc0080
	s_addc_u32 s25, s23, -1
	s_add_i32 s51, 0, 0x10000
	s_cmp_eq_u32 s50, 12
	s_cselect_b32 s27, s3, s25
	s_cselect_b32 s26, s15, s24
	v_add_u32_e32 v142, s51, v144
	s_cselect_b32 s25, s13, s49
	s_cselect_b32 s24, s21, s48
	s_add_i32 s54, 0, 0x14000
	ds_read_b128 v[138:141], v142
	ds_read_b128 v[146:149], v142 offset:1024
	ds_read_b128 v[150:153], v142 offset:2048
	ds_read_b128 v[154:157], v142 offset:3072
	v_add_u32_e32 v142, s54, v144
	ds_read_b128 v[158:161], v142
	ds_read_b128 v[162:165], v142 offset:1024
	ds_read_b128 v[166:169], v142 offset:2048
	ds_read_b128 v[170:173], v142 offset:3072
	v_lshl_add_u64 v[142:143], s[22:23], 0, v[136:137]
	s_add_i32 m0, s37, 0xc000
	ds_read_b128 v[174:177], v145
	ds_read_b128 v[178:181], v145 offset:1024
	ds_read_b128 v[182:185], v145 offset:2048
	ds_read_b128 v[186:189], v145 offset:3072
	ds_read_b128 v[190:193], v145 offset:4096
	ds_read_b128 v[194:197], v145 offset:5120
	ds_read_b128 v[198:201], v145 offset:6144
	ds_read_b128 v[202:205], v145 offset:7168
	global_load_lds_dwordx4 v[142:143], off
	v_lshl_add_u64 v[142:143], s[22:23], 0, v[134:135]
	s_add_i32 m0, s37, 0xe000
	s_nop 0
	global_load_lds_dwordx4 v[142:143], off
	s_waitcnt vmcnt(8)
	s_waitcnt lgkmcnt(0)
	s_barrier
	v_mfma_f32_16x16x32_bf16 v[124:127], v[138:141], v[174:177], v[124:127]
	v_mfma_f32_16x16x32_bf16 v[120:123], v[150:153], v[174:177], v[120:123]
	v_mfma_f32_16x16x32_bf16 v[112:115], v[138:141], v[182:185], v[112:115]
	v_mfma_f32_16x16x32_bf16 v[104:107], v[150:153], v[182:185], v[104:107]
	v_mfma_f32_16x16x32_bf16 v[96:99], v[138:141], v[190:193], v[96:99]
	v_mfma_f32_16x16x32_bf16 v[88:91], v[150:153], v[190:193], v[88:91]
	v_mfma_f32_16x16x32_bf16 v[80:83], v[138:141], v[198:201], v[80:83]
	v_mfma_f32_16x16x32_bf16 v[72:75], v[150:153], v[198:201], v[72:75]
	v_mfma_f32_16x16x32_bf16 v[124:127], v[146:149], v[178:181], v[124:127]
	v_mfma_f32_16x16x32_bf16 v[120:123], v[154:157], v[178:181], v[120:123]
	v_mfma_f32_16x16x32_bf16 v[112:115], v[146:149], v[186:189], v[112:115]
	v_mfma_f32_16x16x32_bf16 v[104:107], v[154:157], v[186:189], v[104:107]
	v_mfma_f32_16x16x32_bf16 v[96:99], v[146:149], v[194:197], v[96:99]
	v_mfma_f32_16x16x32_bf16 v[88:91], v[154:157], v[194:197], v[88:91]
	v_mfma_f32_16x16x32_bf16 v[80:83], v[146:149], v[202:205], v[80:83]
	v_mfma_f32_16x16x32_bf16 v[72:75], v[154:157], v[202:205], v[72:75]
	v_mfma_f32_16x16x32_bf16 v[116:119], v[158:161], v[174:177], v[116:119]
	v_mfma_f32_16x16x32_bf16 v[108:111], v[166:169], v[174:177], v[108:111]
	v_mfma_f32_16x16x32_bf16 v[100:103], v[158:161], v[182:185], v[100:103]
	v_mfma_f32_16x16x32_bf16 v[92:95], v[166:169], v[182:185], v[92:95]
	v_mfma_f32_16x16x32_bf16 v[84:87], v[158:161], v[190:193], v[84:87]
	v_mfma_f32_16x16x32_bf16 v[76:79], v[166:169], v[190:193], v[76:79]
	v_mfma_f32_16x16x32_bf16 v[68:71], v[158:161], v[198:201], v[68:71]
	v_mfma_f32_16x16x32_bf16 v[64:67], v[166:169], v[198:201], v[64:67]
	v_mfma_f32_16x16x32_bf16 v[116:119], v[162:165], v[178:181], v[116:119]
	v_mfma_f32_16x16x32_bf16 v[108:111], v[170:173], v[178:181], v[108:111]
	v_mfma_f32_16x16x32_bf16 v[100:103], v[162:165], v[186:189], v[100:103]
	v_mfma_f32_16x16x32_bf16 v[92:95], v[170:173], v[186:189], v[92:95]
	v_mfma_f32_16x16x32_bf16 v[84:87], v[162:165], v[194:197], v[84:87]
	v_mfma_f32_16x16x32_bf16 v[76:79], v[170:173], v[194:197], v[76:79]
	v_mfma_f32_16x16x32_bf16 v[68:71], v[162:165], v[202:205], v[68:71]
	v_mfma_f32_16x16x32_bf16 v[64:67], v[170:173], v[202:205], v[64:67]
	s_barrier
	s_add_i32 s51, s51, s36
	v_lshl_add_u64 v[142:143], s[24:25], 0, v[232:233]
	s_mov_b32 m0, s51
	ds_read_b128 v[174:177], v145 offset:16384
	ds_read_b128 v[178:181], v145 offset:17408
	ds_read_b128 v[182:185], v145 offset:18432
	ds_read_b128 v[186:189], v145 offset:19456
	ds_read_b128 v[190:193], v145 offset:20480
	ds_read_b128 v[194:197], v145 offset:21504
	ds_read_b128 v[198:201], v145 offset:22528
	ds_read_b128 v[202:205], v145 offset:23552
	global_load_lds_dwordx4 v[142:143], off
	s_add_i32 m0, s51, 0x2000
	s_add_u32 s52, s24, 0x40000
	v_lshl_add_u64 v[206:207], s[24:25], 0, v[132:133]
	s_addc_u32 s53, s25, 0
	s_add_i32 s51, s54, s36
	global_load_lds_dwordx4 v[206:207], off
	v_lshl_add_u64 v[208:209], s[52:53], 0, v[232:233]
	s_mov_b32 m0, s51
	v_lshl_add_u64 v[210:211], s[26:27], 0, v[130:131]
	global_load_lds_dwordx4 v[208:209], off
	v_lshl_add_u64 v[208:209], s[52:53], 0, v[132:133]
	s_add_i32 m0, s51, 0x2000
	s_nop 0
	global_load_lds_dwordx4 v[208:209], off
	v_lshl_add_u64 v[208:209], s[26:27], 0, v[128:129]
	s_waitcnt vmcnt(6)
	s_waitcnt lgkmcnt(0)
	s_barrier
	v_mfma_f32_16x16x32_bf16 v[60:63], v[138:141], v[174:177], v[60:63]
	v_mfma_f32_16x16x32_bf16 v[56:59], v[150:153], v[174:177], v[56:59]
	v_mfma_f32_16x16x32_bf16 v[48:51], v[138:141], v[182:185], v[48:51]
	v_mfma_f32_16x16x32_bf16 v[40:43], v[150:153], v[182:185], v[40:43]
	v_mfma_f32_16x16x32_bf16 v[32:35], v[138:141], v[190:193], v[32:35]
	v_mfma_f32_16x16x32_bf16 v[24:27], v[150:153], v[190:193], v[24:27]
	v_mfma_f32_16x16x32_bf16 v[16:19], v[138:141], v[198:201], v[16:19]
	v_mfma_f32_16x16x32_bf16 v[8:11], v[150:153], v[198:201], v[8:11]
	v_mfma_f32_16x16x32_bf16 v[60:63], v[146:149], v[178:181], v[60:63]
	v_mfma_f32_16x16x32_bf16 v[56:59], v[154:157], v[178:181], v[56:59]
	v_mfma_f32_16x16x32_bf16 v[48:51], v[146:149], v[186:189], v[48:51]
	v_mfma_f32_16x16x32_bf16 v[40:43], v[154:157], v[186:189], v[40:43]
	v_mfma_f32_16x16x32_bf16 v[32:35], v[146:149], v[194:197], v[32:35]
	v_mfma_f32_16x16x32_bf16 v[24:27], v[154:157], v[194:197], v[24:27]
	v_mfma_f32_16x16x32_bf16 v[16:19], v[146:149], v[202:205], v[16:19]
	v_mfma_f32_16x16x32_bf16 v[8:11], v[154:157], v[202:205], v[8:11]
	v_mfma_f32_16x16x32_bf16 v[52:55], v[158:161], v[174:177], v[52:55]
	v_mfma_f32_16x16x32_bf16 v[44:47], v[166:169], v[174:177], v[44:47]
	v_mfma_f32_16x16x32_bf16 v[36:39], v[158:161], v[182:185], v[36:39]
	v_mfma_f32_16x16x32_bf16 v[28:31], v[166:169], v[182:185], v[28:31]
	v_mfma_f32_16x16x32_bf16 v[20:23], v[158:161], v[190:193], v[20:23]
	v_mfma_f32_16x16x32_bf16 v[12:15], v[166:169], v[190:193], v[12:15]
	v_mfma_f32_16x16x32_bf16 v[4:7], v[158:161], v[198:201], v[4:7]
	v_mfma_f32_16x16x32_bf16 v[0:3], v[166:169], v[198:201], v[0:3]
	v_mfma_f32_16x16x32_bf16 v[52:55], v[162:165], v[178:181], v[52:55]
	v_mfma_f32_16x16x32_bf16 v[44:47], v[170:173], v[178:181], v[44:47]
	v_mfma_f32_16x16x32_bf16 v[36:39], v[162:165], v[186:189], v[36:39]
	v_mfma_f32_16x16x32_bf16 v[28:31], v[170:173], v[186:189], v[28:31]
	v_mfma_f32_16x16x32_bf16 v[20:23], v[162:165], v[194:197], v[20:23]
	v_mfma_f32_16x16x32_bf16 v[12:15], v[170:173], v[194:197], v[12:15]
	v_mfma_f32_16x16x32_bf16 v[4:7], v[162:165], v[202:205], v[4:7]
	v_mfma_f32_16x16x32_bf16 v[0:3], v[170:173], v[202:205], v[0:3]
	s_barrier
.Lzmid_1:
	s_add_i32 s51, 0, 0x18000
	s_add_i32 s52, 0, 0x1c000
	v_add_u32_e32 v154, s51, v144
	v_add_u32_e32 v170, s52, v144
	ds_read_b128 v[138:141], v154
	ds_read_b128 v[146:149], v154 offset:1024
	ds_read_b128 v[150:153], v154 offset:2048
	ds_read_b128 v[154:157], v154 offset:3072
	ds_read_b128 v[158:161], v170
	ds_read_b128 v[162:165], v170 offset:1024
	ds_read_b128 v[166:169], v170 offset:2048
	ds_read_b128 v[170:173], v170 offset:3072
	s_add_u32 s26, s26, 0x40000
	s_addc_u32 s27, s27, 0
	s_mov_b32 m0, s37
	s_nop 0
	global_load_lds_dwordx4 v[208:209], off
	s_mov_b32 m0, s38
	s_nop 0
	global_load_lds_dwordx4 v[210:211], off
	s_mov_b32 m0, s39
	v_lshl_add_u64 v[212:213], s[26:27], 0, v[128:129]
	ds_read_b128 v[174:177], v145 offset:32768
	ds_read_b128 v[178:181], v145 offset:33792
	ds_read_b128 v[182:185], v145 offset:34816
	ds_read_b128 v[186:189], v145 offset:35840
	ds_read_b128 v[190:193], v145 offset:36864
	ds_read_b128 v[194:197], v145 offset:37888
	ds_read_b128 v[198:201], v145 offset:38912
	ds_read_b128 v[202:205], v145 offset:39936
	global_load_lds_dwordx4 v[212:213], off
	v_lshl_add_u64 v[212:213], s[26:27], 0, v[130:131]
	s_mov_b32 m0, s40
	s_nop 0
	global_load_lds_dwordx4 v[212:213], off
	s_waitcnt vmcnt(8)
	s_waitcnt lgkmcnt(0)
	s_barrier
	v_mfma_f32_16x16x32_bf16 v[124:127], v[138:141], v[174:177], v[124:127]
	v_mfma_f32_16x16x32_bf16 v[120:123], v[150:153], v[174:177], v[120:123]
	v_mfma_f32_16x16x32_bf16 v[112:115], v[138:141], v[182:185], v[112:115]
	v_mfma_f32_16x16x32_bf16 v[104:107], v[150:153], v[182:185], v[104:107]
	v_mfma_f32_16x16x32_bf16 v[96:99], v[138:141], v[190:193], v[96:99]
	v_mfma_f32_16x16x32_bf16 v[88:91], v[150:153], v[190:193], v[88:91]
	v_mfma_f32_16x16x32_bf16 v[80:83], v[138:141], v[198:201], v[80:83]
	v_mfma_f32_16x16x32_bf16 v[72:75], v[150:153], v[198:201], v[72:75]
	v_mfma_f32_16x16x32_bf16 v[124:127], v[146:149], v[178:181], v[124:127]
	v_mfma_f32_16x16x32_bf16 v[120:123], v[154:157], v[178:181], v[120:123]
	v_mfma_f32_16x16x32_bf16 v[112:115], v[146:149], v[186:189], v[112:115]
	v_mfma_f32_16x16x32_bf16 v[104:107], v[154:157], v[186:189], v[104:107]
	v_mfma_f32_16x16x32_bf16 v[96:99], v[146:149], v[194:197], v[96:99]
	v_mfma_f32_16x16x32_bf16 v[88:91], v[154:157], v[194:197], v[88:91]
	v_mfma_f32_16x16x32_bf16 v[80:83], v[146:149], v[202:205], v[80:83]
	v_mfma_f32_16x16x32_bf16 v[72:75], v[154:157], v[202:205], v[72:75]
	v_mfma_f32_16x16x32_bf16 v[116:119], v[158:161], v[174:177], v[116:119]
	v_mfma_f32_16x16x32_bf16 v[108:111], v[166:169], v[174:177], v[108:111]
	v_mfma_f32_16x16x32_bf16 v[100:103], v[158:161], v[182:185], v[100:103]
	v_mfma_f32_16x16x32_bf16 v[92:95], v[166:169], v[182:185], v[92:95]
	v_mfma_f32_16x16x32_bf16 v[84:87], v[158:161], v[190:193], v[84:87]
	v_mfma_f32_16x16x32_bf16 v[76:79], v[166:169], v[190:193], v[76:79]
	v_mfma_f32_16x16x32_bf16 v[68:71], v[158:161], v[198:201], v[68:71]
	v_mfma_f32_16x16x32_bf16 v[64:67], v[166:169], v[198:201], v[64:67]
	v_mfma_f32_16x16x32_bf16 v[116:119], v[162:165], v[178:181], v[116:119]
	v_mfma_f32_16x16x32_bf16 v[108:111], v[170:173], v[178:181], v[108:111]
	v_mfma_f32_16x16x32_bf16 v[100:103], v[162:165], v[186:189], v[100:103]
	v_mfma_f32_16x16x32_bf16 v[92:95], v[170:173], v[186:189], v[92:95]
	v_mfma_f32_16x16x32_bf16 v[84:87], v[162:165], v[194:197], v[84:87]
	v_mfma_f32_16x16x32_bf16 v[76:79], v[170:173], v[194:197], v[76:79]
	v_mfma_f32_16x16x32_bf16 v[68:71], v[162:165], v[202:205], v[68:71]
	v_mfma_f32_16x16x32_bf16 v[64:67], v[170:173], v[202:205], v[64:67]
	s_barrier
	s_add_i32 s26, s51, s36
	v_lshl_add_u64 v[142:143], v[142:143], 0, s[94:95]
	s_mov_b32 m0, s26
	ds_read_b128 v[174:177], v145 offset:49152
	ds_read_b128 v[178:181], v145 offset:50176
	ds_read_b128 v[182:185], v145 offset:51200
	ds_read_b128 v[186:189], v145 offset:52224
	ds_read_b128 v[190:193], v145 offset:53248
	ds_read_b128 v[194:197], v145 offset:54272
	ds_read_b128 v[198:201], v145 offset:55296
	ds_read_b128 v[202:205], v145 offset:56320
	global_load_lds_dwordx4 v[142:143], off
	s_add_i32 m0, s26, 0x2000
	s_add_u32 s24, s24, 0x40080
	v_lshl_add_u64 v[142:143], v[206:207], 0, s[94:95]
	s_addc_u32 s25, s25, 0
	s_add_i32 s26, s52, s36
	global_load_lds_dwordx4 v[142:143], off
	v_lshl_add_u64 v[142:143], s[24:25], 0, v[232:233]
	s_mov_b32 m0, s26
	s_nop 0
	global_load_lds_dwordx4 v[142:143], off
	v_lshl_add_u64 v[142:143], s[24:25], 0, v[132:133]
	s_add_i32 m0, s26, 0x2000
	s_nop 0
	global_load_lds_dwordx4 v[142:143], off
	v_lshl_add_u64 v[142:143], v[208:209], 0, s[94:95]
	s_mov_b32 m0, s43
	s_nop 0
	global_load_lds_dwordx4 v[142:143], off
	v_lshl_add_u64 v[142:143], v[210:211], 0, s[94:95]
	s_mov_b32 m0, s44
	s_nop 0
	global_load_lds_dwordx4 v[142:143], off
	s_waitcnt vmcnt(8)
	s_waitcnt lgkmcnt(0)
	s_barrier
	v_mfma_f32_16x16x32_bf16 v[60:63], v[138:141], v[174:177], v[60:63]
	v_mfma_f32_16x16x32_bf16 v[56:59], v[150:153], v[174:177], v[56:59]
	v_mfma_f32_16x16x32_bf16 v[48:51], v[138:141], v[182:185], v[48:51]
	v_mfma_f32_16x16x32_bf16 v[40:43], v[150:153], v[182:185], v[40:43]
	v_mfma_f32_16x16x32_bf16 v[32:35], v[138:141], v[190:193], v[32:35]
	v_mfma_f32_16x16x32_bf16 v[24:27], v[150:153], v[190:193], v[24:27]
	v_mfma_f32_16x16x32_bf16 v[16:19], v[138:141], v[198:201], v[16:19]
	v_mfma_f32_16x16x32_bf16 v[8:11], v[150:153], v[198:201], v[8:11]
	v_mfma_f32_16x16x32_bf16 v[60:63], v[146:149], v[178:181], v[60:63]
	v_mfma_f32_16x16x32_bf16 v[56:59], v[154:157], v[178:181], v[56:59]
	v_mfma_f32_16x16x32_bf16 v[48:51], v[146:149], v[186:189], v[48:51]
	v_mfma_f32_16x16x32_bf16 v[40:43], v[154:157], v[186:189], v[40:43]
	v_mfma_f32_16x16x32_bf16 v[32:35], v[146:149], v[194:197], v[32:35]
	v_mfma_f32_16x16x32_bf16 v[24:27], v[154:157], v[194:197], v[24:27]
	v_mfma_f32_16x16x32_bf16 v[16:19], v[146:149], v[202:205], v[16:19]
	v_mfma_f32_16x16x32_bf16 v[8:11], v[154:157], v[202:205], v[8:11]
	v_mfma_f32_16x16x32_bf16 v[52:55], v[158:161], v[174:177], v[52:55]
	v_mfma_f32_16x16x32_bf16 v[44:47], v[166:169], v[174:177], v[44:47]
	v_mfma_f32_16x16x32_bf16 v[36:39], v[158:161], v[182:185], v[36:39]
	v_mfma_f32_16x16x32_bf16 v[28:31], v[166:169], v[182:185], v[28:31]
	v_mfma_f32_16x16x32_bf16 v[20:23], v[158:161], v[190:193], v[20:23]
	v_mfma_f32_16x16x32_bf16 v[12:15], v[166:169], v[190:193], v[12:15]
	v_mfma_f32_16x16x32_bf16 v[4:7], v[158:161], v[198:201], v[4:7]
	v_mfma_f32_16x16x32_bf16 v[0:3], v[166:169], v[198:201], v[0:3]
	v_mfma_f32_16x16x32_bf16 v[52:55], v[162:165], v[178:181], v[52:55]
	v_mfma_f32_16x16x32_bf16 v[44:47], v[170:173], v[178:181], v[44:47]
	v_mfma_f32_16x16x32_bf16 v[36:39], v[162:165], v[186:189], v[36:39]
	v_mfma_f32_16x16x32_bf16 v[28:31], v[170:173], v[186:189], v[28:31]
	v_mfma_f32_16x16x32_bf16 v[20:23], v[162:165], v[194:197], v[20:23]
	v_mfma_f32_16x16x32_bf16 v[12:15], v[170:173], v[194:197], v[12:15]
	v_mfma_f32_16x16x32_bf16 v[4:7], v[162:165], v[202:205], v[4:7]
	v_mfma_f32_16x16x32_bf16 v[0:3], v[170:173], v[202:205], v[0:3]
	s_barrier
	s_add_i32 s50, s50, 2
	s_add_u32 s48, s48, 0x100
	s_addc_u32 s49, s49, 0
	s_add_u32 s22, s22, 0x100
	s_addc_u32 s23, s23, 0
	s_cmp_gt_u32 s50, 13
	s_cbranch_scc0 .LBB0_188
	s_and_b64 vcc, exec, s[10:11]
	s_cbranch_vccz .LBB0_191
	s_barrier

.LBB0_311:
	s_add_u32 s35, s26, s34
	s_addc_u32 s40, s27, 0
	s_add_u32 s38, s35, 0x100
	s_addc_u32 s39, s40, 0
	s_and_b64 s[36:37], s[30:31], exec
	s_cselect_b32 s37, s5, s39
	s_cselect_b32 s36, s17, s38
	s_add_u32 s34, s24, s34
	s_addc_u32 s38, s25, 0
	s_add_u32 s34, s34, 0x100
	s_addc_u32 s38, s38, 0
	s_add_i32 s70, 0, 0x10000
	s_and_b64 s[30:31], s[30:31], exec
	s_cselect_b32 s39, s15, s38
	s_cselect_b32 s38, s23, s34
	s_add_i32 s31, 0, 0x14000
	s_add_u32 s42, s35, 0x100080
	s_addc_u32 s43, s40, 0
	s_add_i32 s69, s70, s50
	s_add_i32 m0, s51, 0xc000
	s_add_i32 s72, s51, 0xe000
	s_add_i32 s66, s69, 0x2000
	s_add_u32 s40, s38, 0x10000
	v_add_u32_e32 v146, s70, v154
	v_add_u32_e32 v164, s31, v154
	s_addc_u32 s41, s39, 0
	s_add_i32 s68, s31, s50
	ds_read_b128 v[134:137], v146
	ds_read_b128 v[138:141], v146 offset:1024
	ds_read_b128 v[142:145], v146 offset:2048
	ds_read_b128 v[146:149], v146 offset:3072
	ds_read_b128 v[150:153], v164
	ds_read_b128 v[156:159], v164 offset:1024
	ds_read_b128 v[160:163], v164 offset:2048
	ds_read_b128 v[164:167], v164 offset:3072
	s_add_i32 s67, s68, 0x2000
	s_add_i32 s65, 0, 0x18000
	s_add_i32 s64, 0, 0x1c000
	s_add_u32 s34, s36, 0x100000
	s_addc_u32 s35, s37, 0
	s_add_i32 s63, s65, s50
	s_add_i32 s62, s63, 0x2000
	s_add_u32 s30, s38, 0x10080
	s_addc_u32 s31, s39, 0
	s_add_i32 s71, s64, s50
	s_add_i32 s70, s71, 0x2000
	v_lshl_add_u64 v[200:201], s[42:43], 0, v[128:129]
	ds_read_b128 v[168:171], v155
	ds_read_b128 v[172:175], v155 offset:1024
	ds_read_b128 v[176:179], v155 offset:2048
	ds_read_b128 v[180:183], v155 offset:3072
	ds_read_b128 v[184:187], v155 offset:4096
	ds_read_b128 v[188:191], v155 offset:5120
	ds_read_b128 v[192:195], v155 offset:6144
	ds_read_b128 v[196:199], v155 offset:7168
	global_load_lds_dwordx4 v[200:201], off
	v_lshl_add_u64 v[200:201], s[42:43], 0, v[130:131]
	s_mov_b32 m0, s72
	s_nop 0
	global_load_lds_dwordx4 v[200:201], off
	s_waitcnt vmcnt(8)
	s_waitcnt lgkmcnt(0)
	s_barrier
	v_mfma_f32_16x16x32_bf16 v[124:127], v[134:137], v[168:171], v[124:127]
	v_mfma_f32_16x16x32_bf16 v[120:123], v[142:145], v[168:171], v[120:123]
	v_mfma_f32_16x16x32_bf16 v[108:111], v[134:137], v[176:179], v[108:111]
	v_mfma_f32_16x16x32_bf16 v[104:107], v[142:145], v[176:179], v[104:107]
	v_mfma_f32_16x16x32_bf16 v[92:95], v[134:137], v[184:187], v[92:95]
	v_mfma_f32_16x16x32_bf16 v[88:91], v[142:145], v[184:187], v[88:91]
	v_mfma_f32_16x16x32_bf16 v[76:79], v[134:137], v[192:195], v[76:79]
	v_mfma_f32_16x16x32_bf16 v[72:75], v[142:145], v[192:195], v[72:75]
	v_mfma_f32_16x16x32_bf16 v[124:127], v[138:141], v[172:175], v[124:127]
	v_mfma_f32_16x16x32_bf16 v[120:123], v[146:149], v[172:175], v[120:123]
	v_mfma_f32_16x16x32_bf16 v[108:111], v[138:141], v[180:183], v[108:111]
	v_mfma_f32_16x16x32_bf16 v[104:107], v[146:149], v[180:183], v[104:107]
	v_mfma_f32_16x16x32_bf16 v[92:95], v[138:141], v[188:191], v[92:95]
	v_mfma_f32_16x16x32_bf16 v[88:91], v[146:149], v[188:191], v[88:91]
	v_mfma_f32_16x16x32_bf16 v[76:79], v[138:141], v[196:199], v[76:79]
	v_mfma_f32_16x16x32_bf16 v[72:75], v[146:149], v[196:199], v[72:75]
	v_mfma_f32_16x16x32_bf16 v[116:119], v[150:153], v[168:171], v[116:119]
	v_mfma_f32_16x16x32_bf16 v[112:115], v[160:163], v[168:171], v[112:115]
	v_mfma_f32_16x16x32_bf16 v[100:103], v[150:153], v[176:179], v[100:103]
	v_mfma_f32_16x16x32_bf16 v[96:99], v[160:163], v[176:179], v[96:99]
	v_mfma_f32_16x16x32_bf16 v[84:87], v[150:153], v[184:187], v[84:87]
	v_mfma_f32_16x16x32_bf16 v[80:83], v[160:163], v[184:187], v[80:83]
	v_mfma_f32_16x16x32_bf16 v[68:71], v[150:153], v[192:195], v[68:71]
	v_mfma_f32_16x16x32_bf16 v[64:67], v[160:163], v[192:195], v[64:67]
	v_mfma_f32_16x16x32_bf16 v[116:119], v[156:159], v[172:175], v[116:119]
	v_mfma_f32_16x16x32_bf16 v[112:115], v[164:167], v[172:175], v[112:115]
	v_mfma_f32_16x16x32_bf16 v[100:103], v[156:159], v[180:183], v[100:103]
	v_mfma_f32_16x16x32_bf16 v[96:99], v[164:167], v[180:183], v[96:99]
	v_mfma_f32_16x16x32_bf16 v[84:87], v[156:159], v[188:191], v[84:87]
	v_mfma_f32_16x16x32_bf16 v[80:83], v[164:167], v[188:191], v[80:83]
	v_mfma_f32_16x16x32_bf16 v[68:71], v[156:159], v[196:199], v[68:71]
	v_mfma_f32_16x16x32_bf16 v[64:67], v[164:167], v[196:199], v[64:67]
	s_barrier
	s_mov_b32 m0, s69
	v_lshl_add_u64 v[200:201], s[38:39], 0, v[232:233]
	ds_read_b128 v[168:171], v155 offset:16384
	ds_read_b128 v[172:175], v155 offset:17408
	ds_read_b128 v[176:179], v155 offset:18432
	ds_read_b128 v[180:183], v155 offset:19456
	ds_read_b128 v[184:187], v155 offset:20480
	ds_read_b128 v[188:191], v155 offset:21504
	ds_read_b128 v[192:195], v155 offset:22528
	ds_read_b128 v[196:199], v155 offset:23552
	global_load_lds_dwordx4 v[200:201], off
	v_lshl_add_u64 v[202:203], s[38:39], 0, v[132:133]
	s_mov_b32 m0, s66
	v_lshl_add_u64 v[204:205], s[40:41], 0, v[232:233]
	global_load_lds_dwordx4 v[202:203], off
	s_mov_b32 m0, s68
	v_lshl_add_u64 v[206:207], s[36:37], 0, v[130:131]
	global_load_lds_dwordx4 v[204:205], off
	v_lshl_add_u64 v[204:205], s[40:41], 0, v[132:133]
	s_mov_b32 m0, s67
	s_nop 0
	global_load_lds_dwordx4 v[204:205], off
	v_lshl_add_u64 v[204:205], s[36:37], 0, v[128:129]
	s_mov_b32 m0, s51
	s_nop 0
	global_load_lds_dwordx4 v[204:205], off
	s_mov_b32 m0, s52
	s_nop 0
	global_load_lds_dwordx4 v[206:207], off
	s_waitcnt vmcnt(8)
	s_waitcnt lgkmcnt(0)
	s_barrier
	v_mfma_f32_16x16x32_bf16 v[60:63], v[134:137], v[168:171], v[60:63]
	v_mfma_f32_16x16x32_bf16 v[56:59], v[142:145], v[168:171], v[56:59]
	v_mfma_f32_16x16x32_bf16 v[44:47], v[134:137], v[176:179], v[44:47]
	v_mfma_f32_16x16x32_bf16 v[40:43], v[142:145], v[176:179], v[40:43]
	v_mfma_f32_16x16x32_bf16 v[28:31], v[134:137], v[184:187], v[28:31]
	v_mfma_f32_16x16x32_bf16 v[24:27], v[142:145], v[184:187], v[24:27]
	v_mfma_f32_16x16x32_bf16 v[12:15], v[134:137], v[192:195], v[12:15]
	v_mfma_f32_16x16x32_bf16 v[8:11], v[142:145], v[192:195], v[8:11]
	v_mfma_f32_16x16x32_bf16 v[60:63], v[138:141], v[172:175], v[60:63]
	v_mfma_f32_16x16x32_bf16 v[56:59], v[146:149], v[172:175], v[56:59]
	v_mfma_f32_16x16x32_bf16 v[44:47], v[138:141], v[180:183], v[44:47]
	v_mfma_f32_16x16x32_bf16 v[40:43], v[146:149], v[180:183], v[40:43]
	v_mfma_f32_16x16x32_bf16 v[28:31], v[138:141], v[188:191], v[28:31]
	v_mfma_f32_16x16x32_bf16 v[24:27], v[146:149], v[188:191], v[24:27]
	v_mfma_f32_16x16x32_bf16 v[12:15], v[138:141], v[196:199], v[12:15]
	v_mfma_f32_16x16x32_bf16 v[8:11], v[146:149], v[196:199], v[8:11]
	v_mfma_f32_16x16x32_bf16 v[52:55], v[150:153], v[168:171], v[52:55]
	v_mfma_f32_16x16x32_bf16 v[48:51], v[160:163], v[168:171], v[48:51]
	v_mfma_f32_16x16x32_bf16 v[36:39], v[150:153], v[176:179], v[36:39]
	v_mfma_f32_16x16x32_bf16 v[32:35], v[160:163], v[176:179], v[32:35]
	v_mfma_f32_16x16x32_bf16 v[20:23], v[150:153], v[184:187], v[20:23]
	v_mfma_f32_16x16x32_bf16 v[16:19], v[160:163], v[184:187], v[16:19]
	v_mfma_f32_16x16x32_bf16 v[4:7], v[150:153], v[192:195], v[4:7]
	v_mfma_f32_16x16x32_bf16 v[0:3], v[160:163], v[192:195], v[0:3]
	v_mfma_f32_16x16x32_bf16 v[52:55], v[156:159], v[172:175], v[52:55]
	v_mfma_f32_16x16x32_bf16 v[48:51], v[164:167], v[172:175], v[48:51]
	v_mfma_f32_16x16x32_bf16 v[36:39], v[156:159], v[180:183], v[36:39]
	v_mfma_f32_16x16x32_bf16 v[32:35], v[164:167], v[180:183], v[32:35]
	v_mfma_f32_16x16x32_bf16 v[20:23], v[156:159], v[188:191], v[20:23]
	v_mfma_f32_16x16x32_bf16 v[16:19], v[164:167], v[188:191], v[16:19]
	v_mfma_f32_16x16x32_bf16 v[4:7], v[156:159], v[196:199], v[4:7]
	v_mfma_f32_16x16x32_bf16 v[0:3], v[164:167], v[196:199], v[0:3]
	s_barrier
	v_add_u32_e32 v146, s65, v154
	v_add_u32_e32 v164, s64, v154
	ds_read_b128 v[134:137], v146
	ds_read_b128 v[138:141], v146 offset:1024
	ds_read_b128 v[142:145], v146 offset:2048
	ds_read_b128 v[146:149], v146 offset:3072
	ds_read_b128 v[150:153], v164
	ds_read_b128 v[156:159], v164 offset:1024
	ds_read_b128 v[160:163], v164 offset:2048
	ds_read_b128 v[164:167], v164 offset:3072
	s_mov_b32 m0, s53
	v_lshl_add_u64 v[208:209], s[34:35], 0, v[128:129]
	ds_read_b128 v[168:171], v155 offset:32768
	ds_read_b128 v[172:175], v155 offset:33792
	ds_read_b128 v[176:179], v155 offset:34816
	ds_read_b128 v[180:183], v155 offset:35840
	ds_read_b128 v[184:187], v155 offset:36864
	ds_read_b128 v[188:191], v155 offset:37888
	ds_read_b128 v[192:195], v155 offset:38912
	ds_read_b128 v[196:199], v155 offset:39936
	global_load_lds_dwordx4 v[208:209], off
	v_lshl_add_u64 v[208:209], s[34:35], 0, v[130:131]
	s_mov_b32 m0, s54
	s_nop 0
	global_load_lds_dwordx4 v[208:209], off
	s_waitcnt vmcnt(8)
	s_waitcnt lgkmcnt(0)
	s_barrier
	v_mfma_f32_16x16x32_bf16 v[124:127], v[134:137], v[168:171], v[124:127]
	v_mfma_f32_16x16x32_bf16 v[120:123], v[142:145], v[168:171], v[120:123]
	v_mfma_f32_16x16x32_bf16 v[108:111], v[134:137], v[176:179], v[108:111]
	v_mfma_f32_16x16x32_bf16 v[104:107], v[142:145], v[176:179], v[104:107]
	v_mfma_f32_16x16x32_bf16 v[92:95], v[134:137], v[184:187], v[92:95]
	v_mfma_f32_16x16x32_bf16 v[88:91], v[142:145], v[184:187], v[88:91]
	v_mfma_f32_16x16x32_bf16 v[76:79], v[134:137], v[192:195], v[76:79]
	v_mfma_f32_16x16x32_bf16 v[72:75], v[142:145], v[192:195], v[72:75]
	v_mfma_f32_16x16x32_bf16 v[124:127], v[138:141], v[172:175], v[124:127]
	v_mfma_f32_16x16x32_bf16 v[120:123], v[146:149], v[172:175], v[120:123]
	v_mfma_f32_16x16x32_bf16 v[108:111], v[138:141], v[180:183], v[108:111]
	v_mfma_f32_16x16x32_bf16 v[104:107], v[146:149], v[180:183], v[104:107]
	v_mfma_f32_16x16x32_bf16 v[92:95], v[138:141], v[188:191], v[92:95]
	v_mfma_f32_16x16x32_bf16 v[88:91], v[146:149], v[188:191], v[88:91]
	v_mfma_f32_16x16x32_bf16 v[76:79], v[138:141], v[196:199], v[76:79]
	v_mfma_f32_16x16x32_bf16 v[72:75], v[146:149], v[196:199], v[72:75]
	v_mfma_f32_16x16x32_bf16 v[116:119], v[150:153], v[168:171], v[116:119]
	v_mfma_f32_16x16x32_bf16 v[112:115], v[160:163], v[168:171], v[112:115]
	v_mfma_f32_16x16x32_bf16 v[100:103], v[150:153], v[176:179], v[100:103]
	v_mfma_f32_16x16x32_bf16 v[96:99], v[160:163], v[176:179], v[96:99]
	v_mfma_f32_16x16x32_bf16 v[84:87], v[150:153], v[184:187], v[84:87]
	v_mfma_f32_16x16x32_bf16 v[80:83], v[160:163], v[184:187], v[80:83]
	v_mfma_f32_16x16x32_bf16 v[68:71], v[150:153], v[192:195], v[68:71]
	v_mfma_f32_16x16x32_bf16 v[64:67], v[160:163], v[192:195], v[64:67]
	v_mfma_f32_16x16x32_bf16 v[116:119], v[156:159], v[172:175], v[116:119]
	v_mfma_f32_16x16x32_bf16 v[112:115], v[164:167], v[172:175], v[112:115]
	v_mfma_f32_16x16x32_bf16 v[100:103], v[156:159], v[180:183], v[100:103]
	v_mfma_f32_16x16x32_bf16 v[96:99], v[164:167], v[180:183], v[96:99]
	v_mfma_f32_16x16x32_bf16 v[84:87], v[156:159], v[188:191], v[84:87]
	v_mfma_f32_16x16x32_bf16 v[80:83], v[164:167], v[188:191], v[80:83]
	v_mfma_f32_16x16x32_bf16 v[68:71], v[156:159], v[196:199], v[68:71]
	v_mfma_f32_16x16x32_bf16 v[64:67], v[164:167], v[196:199], v[64:67]
	s_barrier
	s_mov_b32 m0, s63
	v_lshl_add_u64 v[200:201], v[200:201], 0, s[94:95]
	ds_read_b128 v[168:171], v155 offset:49152
	ds_read_b128 v[172:175], v155 offset:50176
	ds_read_b128 v[176:179], v155 offset:51200
	ds_read_b128 v[180:183], v155 offset:52224
	ds_read_b128 v[184:187], v155 offset:53248
	ds_read_b128 v[188:191], v155 offset:54272
	ds_read_b128 v[192:195], v155 offset:55296
	ds_read_b128 v[196:199], v155 offset:56320
	global_load_lds_dwordx4 v[200:201], off
	v_lshl_add_u64 v[200:201], v[202:203], 0, s[94:95]
	s_mov_b32 m0, s62
	s_nop 0
	global_load_lds_dwordx4 v[200:201], off
	v_lshl_add_u64 v[200:201], s[30:31], 0, v[232:233]
	s_mov_b32 m0, s71
	s_nop 0
	global_load_lds_dwordx4 v[200:201], off
	v_lshl_add_u64 v[200:201], s[30:31], 0, v[132:133]
	s_mov_b32 m0, s70
	s_nop 0
	global_load_lds_dwordx4 v[200:201], off
	v_lshl_add_u64 v[200:201], v[204:205], 0, s[94:95]
	s_mov_b32 m0, s57
	s_nop 0
	global_load_lds_dwordx4 v[200:201], off
	v_lshl_add_u64 v[200:201], v[206:207], 0, s[94:95]
	s_mov_b32 m0, s58
	s_nop 0
	global_load_lds_dwordx4 v[200:201], off
	s_waitcnt vmcnt(8)
	s_waitcnt lgkmcnt(0)
	s_barrier
	v_mfma_f32_16x16x32_bf16 v[60:63], v[134:137], v[168:171], v[60:63]
	v_mfma_f32_16x16x32_bf16 v[56:59], v[142:145], v[168:171], v[56:59]
	v_mfma_f32_16x16x32_bf16 v[44:47], v[134:137], v[176:179], v[44:47]
	v_mfma_f32_16x16x32_bf16 v[40:43], v[142:145], v[176:179], v[40:43]
	v_mfma_f32_16x16x32_bf16 v[28:31], v[134:137], v[184:187], v[28:31]
	v_mfma_f32_16x16x32_bf16 v[24:27], v[142:145], v[184:187], v[24:27]
	v_mfma_f32_16x16x32_bf16 v[12:15], v[134:137], v[192:195], v[12:15]
	v_mfma_f32_16x16x32_bf16 v[8:11], v[142:145], v[192:195], v[8:11]
	v_mfma_f32_16x16x32_bf16 v[60:63], v[138:141], v[172:175], v[60:63]
	v_mfma_f32_16x16x32_bf16 v[56:59], v[146:149], v[172:175], v[56:59]
	v_mfma_f32_16x16x32_bf16 v[44:47], v[138:141], v[180:183], v[44:47]
	v_mfma_f32_16x16x32_bf16 v[40:43], v[146:149], v[180:183], v[40:43]
	v_mfma_f32_16x16x32_bf16 v[28:31], v[138:141], v[188:191], v[28:31]
	v_mfma_f32_16x16x32_bf16 v[24:27], v[146:149], v[188:191], v[24:27]
	v_mfma_f32_16x16x32_bf16 v[12:15], v[138:141], v[196:199], v[12:15]
	v_mfma_f32_16x16x32_bf16 v[8:11], v[146:149], v[196:199], v[8:11]
	v_mfma_f32_16x16x32_bf16 v[52:55], v[150:153], v[168:171], v[52:55]
	v_mfma_f32_16x16x32_bf16 v[48:51], v[160:163], v[168:171], v[48:51]
	v_mfma_f32_16x16x32_bf16 v[36:39], v[150:153], v[176:179], v[36:39]
	v_mfma_f32_16x16x32_bf16 v[32:35], v[160:163], v[176:179], v[32:35]
	v_mfma_f32_16x16x32_bf16 v[20:23], v[150:153], v[184:187], v[20:23]
	v_mfma_f32_16x16x32_bf16 v[16:19], v[160:163], v[184:187], v[16:19]
	v_mfma_f32_16x16x32_bf16 v[4:7], v[150:153], v[192:195], v[4:7]
	v_mfma_f32_16x16x32_bf16 v[0:3], v[160:163], v[192:195], v[0:3]
	v_mfma_f32_16x16x32_bf16 v[52:55], v[156:159], v[172:175], v[52:55]
	v_mfma_f32_16x16x32_bf16 v[48:51], v[164:167], v[172:175], v[48:51]
	v_mfma_f32_16x16x32_bf16 v[36:39], v[156:159], v[180:183], v[36:39]
	v_mfma_f32_16x16x32_bf16 v[32:35], v[164:167], v[180:183], v[32:35]
	v_mfma_f32_16x16x32_bf16 v[20:23], v[156:159], v[188:191], v[20:23]
	v_mfma_f32_16x16x32_bf16 v[16:19], v[164:167], v[188:191], v[16:19]
	v_mfma_f32_16x16x32_bf16 v[4:7], v[156:159], v[196:199], v[4:7]
	v_mfma_f32_16x16x32_bf16 v[0:3], v[164:167], v[196:199], v[0:3]
	s_barrier
	s_movk_i32 s34, 0x100
	s_andn2_b64 vcc, exec, s[28:29]
	s_mov_b64 s[30:31], -1
	s_mov_b64 s[28:29], 0
	s_cbranch_vccz .LBB0_311
	s_and_b64 vcc, exec, s[12:13]
	s_cbranch_vccz .LBB0_314
	s_barrier

.LBB0_369:
	s_add_u32 s35, s26, s34
	s_addc_u32 s40, s27, 0
	s_add_u32 s38, s35, 0x100
	s_addc_u32 s39, s40, 0
	s_and_b64 s[36:37], s[30:31], exec
	s_cselect_b32 s37, s5, s39
	s_cselect_b32 s36, s17, s38
	s_add_u32 s34, s24, s34
	s_addc_u32 s38, s25, 0
	s_add_u32 s34, s34, 0x100
	s_addc_u32 s38, s38, 0
	s_add_i32 s70, 0, 0x10000
	s_and_b64 s[30:31], s[30:31], exec
	s_cselect_b32 s39, s15, s38
	s_cselect_b32 s38, s23, s34
	s_add_i32 s31, 0, 0x14000
	s_add_u32 s42, s35, 0x100080
	s_addc_u32 s43, s40, 0
	s_add_i32 s69, s70, s50
	s_add_i32 m0, s51, 0xc000
	s_add_i32 s72, s51, 0xe000
	s_add_i32 s66, s69, 0x2000
	s_add_u32 s40, s38, 0x10000
	v_add_u32_e32 v146, s70, v168
	v_add_u32_e32 v162, s31, v168
	s_addc_u32 s41, s39, 0
	s_add_i32 s68, s31, s50
	ds_read_b128 v[134:137], v146
	ds_read_b128 v[138:141], v146 offset:1024
	ds_read_b128 v[142:145], v146 offset:2048
	ds_read_b128 v[146:149], v146 offset:3072
	ds_read_b128 v[150:153], v162
	ds_read_b128 v[154:157], v162 offset:1024
	ds_read_b128 v[158:161], v162 offset:2048
	ds_read_b128 v[162:165], v162 offset:3072
	s_add_i32 s67, s68, 0x2000
	s_add_i32 s65, 0, 0x18000
	s_add_i32 s64, 0, 0x1c000
	s_add_u32 s34, s36, 0x100000
	s_addc_u32 s35, s37, 0
	s_add_i32 s63, s65, s50
	s_add_i32 s62, s63, 0x2000
	s_add_u32 s30, s38, 0x10080
	s_addc_u32 s31, s39, 0
	s_add_i32 s71, s64, s50
	s_add_i32 s70, s71, 0x2000
	v_lshl_add_u64 v[166:167], s[42:43], 0, v[128:129]
	ds_read_b128 v[170:173], v169
	ds_read_b128 v[174:177], v169 offset:1024
	ds_read_b128 v[178:181], v169 offset:2048
	ds_read_b128 v[182:185], v169 offset:3072
	ds_read_b128 v[186:189], v169 offset:4096
	ds_read_b128 v[190:193], v169 offset:5120
	ds_read_b128 v[194:197], v169 offset:6144
	ds_read_b128 v[198:201], v169 offset:7168
	global_load_lds_dwordx4 v[166:167], off
	v_lshl_add_u64 v[166:167], s[42:43], 0, v[130:131]
	s_mov_b32 m0, s72
	s_nop 0
	global_load_lds_dwordx4 v[166:167], off
	s_waitcnt vmcnt(8)
	s_waitcnt lgkmcnt(0)
	s_barrier
	v_mfma_f32_16x16x32_bf16 v[124:127], v[134:137], v[170:173], v[124:127]
	v_mfma_f32_16x16x32_bf16 v[120:123], v[142:145], v[170:173], v[120:123]
	v_mfma_f32_16x16x32_bf16 v[108:111], v[134:137], v[178:181], v[108:111]
	v_mfma_f32_16x16x32_bf16 v[104:107], v[142:145], v[178:181], v[104:107]
	v_mfma_f32_16x16x32_bf16 v[92:95], v[134:137], v[186:189], v[92:95]
	v_mfma_f32_16x16x32_bf16 v[88:91], v[142:145], v[186:189], v[88:91]
	v_mfma_f32_16x16x32_bf16 v[76:79], v[134:137], v[194:197], v[76:79]
	v_mfma_f32_16x16x32_bf16 v[72:75], v[142:145], v[194:197], v[72:75]
	v_mfma_f32_16x16x32_bf16 v[124:127], v[138:141], v[174:177], v[124:127]
	v_mfma_f32_16x16x32_bf16 v[120:123], v[146:149], v[174:177], v[120:123]
	v_mfma_f32_16x16x32_bf16 v[108:111], v[138:141], v[182:185], v[108:111]
	v_mfma_f32_16x16x32_bf16 v[104:107], v[146:149], v[182:185], v[104:107]
	v_mfma_f32_16x16x32_bf16 v[92:95], v[138:141], v[190:193], v[92:95]
	v_mfma_f32_16x16x32_bf16 v[88:91], v[146:149], v[190:193], v[88:91]
	v_mfma_f32_16x16x32_bf16 v[76:79], v[138:141], v[198:201], v[76:79]
	v_mfma_f32_16x16x32_bf16 v[72:75], v[146:149], v[198:201], v[72:75]
	v_mfma_f32_16x16x32_bf16 v[116:119], v[150:153], v[170:173], v[116:119]
	v_mfma_f32_16x16x32_bf16 v[112:115], v[158:161], v[170:173], v[112:115]
	v_mfma_f32_16x16x32_bf16 v[100:103], v[150:153], v[178:181], v[100:103]
	v_mfma_f32_16x16x32_bf16 v[96:99], v[158:161], v[178:181], v[96:99]
	v_mfma_f32_16x16x32_bf16 v[84:87], v[150:153], v[186:189], v[84:87]
	v_mfma_f32_16x16x32_bf16 v[80:83], v[158:161], v[186:189], v[80:83]
	v_mfma_f32_16x16x32_bf16 v[68:71], v[150:153], v[194:197], v[68:71]
	v_mfma_f32_16x16x32_bf16 v[64:67], v[158:161], v[194:197], v[64:67]
	v_mfma_f32_16x16x32_bf16 v[116:119], v[154:157], v[174:177], v[116:119]
	v_mfma_f32_16x16x32_bf16 v[112:115], v[162:165], v[174:177], v[112:115]
	v_mfma_f32_16x16x32_bf16 v[100:103], v[154:157], v[182:185], v[100:103]
	v_mfma_f32_16x16x32_bf16 v[96:99], v[162:165], v[182:185], v[96:99]
	v_mfma_f32_16x16x32_bf16 v[84:87], v[154:157], v[190:193], v[84:87]
	v_mfma_f32_16x16x32_bf16 v[80:83], v[162:165], v[190:193], v[80:83]
	v_mfma_f32_16x16x32_bf16 v[68:71], v[154:157], v[198:201], v[68:71]
	v_mfma_f32_16x16x32_bf16 v[64:67], v[162:165], v[198:201], v[64:67]
	s_barrier
	s_mov_b32 m0, s69
	v_lshl_add_u64 v[166:167], s[38:39], 0, v[232:233]
	ds_read_b128 v[170:173], v169 offset:16384
	ds_read_b128 v[174:177], v169 offset:17408
	ds_read_b128 v[178:181], v169 offset:18432
	ds_read_b128 v[182:185], v169 offset:19456
	ds_read_b128 v[186:189], v169 offset:20480
	ds_read_b128 v[190:193], v169 offset:21504
	ds_read_b128 v[194:197], v169 offset:22528
	ds_read_b128 v[198:201], v169 offset:23552
	global_load_lds_dwordx4 v[166:167], off
	v_lshl_add_u64 v[202:203], s[38:39], 0, v[132:133]
	s_mov_b32 m0, s66
	v_lshl_add_u64 v[204:205], s[40:41], 0, v[232:233]
	global_load_lds_dwordx4 v[202:203], off
	s_mov_b32 m0, s68
	v_lshl_add_u64 v[206:207], s[36:37], 0, v[130:131]
	global_load_lds_dwordx4 v[204:205], off
	v_lshl_add_u64 v[204:205], s[40:41], 0, v[132:133]
	s_mov_b32 m0, s67
	s_nop 0
	global_load_lds_dwordx4 v[204:205], off
	v_lshl_add_u64 v[204:205], s[36:37], 0, v[128:129]
	s_mov_b32 m0, s51
	s_nop 0
	global_load_lds_dwordx4 v[204:205], off
	s_mov_b32 m0, s52
	s_nop 0
	global_load_lds_dwordx4 v[206:207], off
	s_waitcnt vmcnt(8)
	s_waitcnt lgkmcnt(0)
	s_barrier
	v_mfma_f32_16x16x32_bf16 v[60:63], v[134:137], v[170:173], v[60:63]
	v_mfma_f32_16x16x32_bf16 v[56:59], v[142:145], v[170:173], v[56:59]
	v_mfma_f32_16x16x32_bf16 v[44:47], v[134:137], v[178:181], v[44:47]
	v_mfma_f32_16x16x32_bf16 v[40:43], v[142:145], v[178:181], v[40:43]
	v_mfma_f32_16x16x32_bf16 v[28:31], v[134:137], v[186:189], v[28:31]
	v_mfma_f32_16x16x32_bf16 v[24:27], v[142:145], v[186:189], v[24:27]
	v_mfma_f32_16x16x32_bf16 v[12:15], v[134:137], v[194:197], v[12:15]
	v_mfma_f32_16x16x32_bf16 v[8:11], v[142:145], v[194:197], v[8:11]
	v_mfma_f32_16x16x32_bf16 v[60:63], v[138:141], v[174:177], v[60:63]
	v_mfma_f32_16x16x32_bf16 v[56:59], v[146:149], v[174:177], v[56:59]
	v_mfma_f32_16x16x32_bf16 v[44:47], v[138:141], v[182:185], v[44:47]
	v_mfma_f32_16x16x32_bf16 v[40:43], v[146:149], v[182:185], v[40:43]
	v_mfma_f32_16x16x32_bf16 v[28:31], v[138:141], v[190:193], v[28:31]
	v_mfma_f32_16x16x32_bf16 v[24:27], v[146:149], v[190:193], v[24:27]
	v_mfma_f32_16x16x32_bf16 v[12:15], v[138:141], v[198:201], v[12:15]
	v_mfma_f32_16x16x32_bf16 v[8:11], v[146:149], v[198:201], v[8:11]
	v_mfma_f32_16x16x32_bf16 v[52:55], v[150:153], v[170:173], v[52:55]
	v_mfma_f32_16x16x32_bf16 v[48:51], v[158:161], v[170:173], v[48:51]
	v_mfma_f32_16x16x32_bf16 v[36:39], v[150:153], v[178:181], v[36:39]
	v_mfma_f32_16x16x32_bf16 v[32:35], v[158:161], v[178:181], v[32:35]
	v_mfma_f32_16x16x32_bf16 v[20:23], v[150:153], v[186:189], v[20:23]
	v_mfma_f32_16x16x32_bf16 v[16:19], v[158:161], v[186:189], v[16:19]
	v_mfma_f32_16x16x32_bf16 v[4:7], v[150:153], v[194:197], v[4:7]
	v_mfma_f32_16x16x32_bf16 v[0:3], v[158:161], v[194:197], v[0:3]
	v_mfma_f32_16x16x32_bf16 v[52:55], v[154:157], v[174:177], v[52:55]
	v_mfma_f32_16x16x32_bf16 v[48:51], v[162:165], v[174:177], v[48:51]
	v_mfma_f32_16x16x32_bf16 v[36:39], v[154:157], v[182:185], v[36:39]
	v_mfma_f32_16x16x32_bf16 v[32:35], v[162:165], v[182:185], v[32:35]
	v_mfma_f32_16x16x32_bf16 v[20:23], v[154:157], v[190:193], v[20:23]
	v_mfma_f32_16x16x32_bf16 v[16:19], v[162:165], v[190:193], v[16:19]
	v_mfma_f32_16x16x32_bf16 v[4:7], v[154:157], v[198:201], v[4:7]
	v_mfma_f32_16x16x32_bf16 v[0:3], v[162:165], v[198:201], v[0:3]
	s_barrier
	v_add_u32_e32 v146, s65, v168
	v_add_u32_e32 v162, s64, v168
	ds_read_b128 v[134:137], v146
	ds_read_b128 v[138:141], v146 offset:1024
	ds_read_b128 v[142:145], v146 offset:2048
	ds_read_b128 v[146:149], v146 offset:3072
	ds_read_b128 v[150:153], v162
	ds_read_b128 v[154:157], v162 offset:1024
	ds_read_b128 v[158:161], v162 offset:2048
	ds_read_b128 v[162:165], v162 offset:3072
	s_mov_b32 m0, s53
	v_lshl_add_u64 v[208:209], s[34:35], 0, v[128:129]
	ds_read_b128 v[170:173], v169 offset:32768
	ds_read_b128 v[174:177], v169 offset:33792
	ds_read_b128 v[178:181], v169 offset:34816
	ds_read_b128 v[182:185], v169 offset:35840
	ds_read_b128 v[186:189], v169 offset:36864
	ds_read_b128 v[190:193], v169 offset:37888
	ds_read_b128 v[194:197], v169 offset:38912
	ds_read_b128 v[198:201], v169 offset:39936
	global_load_lds_dwordx4 v[208:209], off
	v_lshl_add_u64 v[208:209], s[34:35], 0, v[130:131]
	s_mov_b32 m0, s54
	s_nop 0
	global_load_lds_dwordx4 v[208:209], off
	s_waitcnt vmcnt(8)
	s_waitcnt lgkmcnt(0)
	s_barrier
	v_mfma_f32_16x16x32_bf16 v[124:127], v[134:137], v[170:173], v[124:127]
	v_mfma_f32_16x16x32_bf16 v[120:123], v[142:145], v[170:173], v[120:123]
	v_mfma_f32_16x16x32_bf16 v[108:111], v[134:137], v[178:181], v[108:111]
	v_mfma_f32_16x16x32_bf16 v[104:107], v[142:145], v[178:181], v[104:107]
	v_mfma_f32_16x16x32_bf16 v[92:95], v[134:137], v[186:189], v[92:95]
	v_mfma_f32_16x16x32_bf16 v[88:91], v[142:145], v[186:189], v[88:91]
	v_mfma_f32_16x16x32_bf16 v[76:79], v[134:137], v[194:197], v[76:79]
	v_mfma_f32_16x16x32_bf16 v[72:75], v[142:145], v[194:197], v[72:75]
	v_mfma_f32_16x16x32_bf16 v[124:127], v[138:141], v[174:177], v[124:127]
	v_mfma_f32_16x16x32_bf16 v[120:123], v[146:149], v[174:177], v[120:123]
	v_mfma_f32_16x16x32_bf16 v[108:111], v[138:141], v[182:185], v[108:111]
	v_mfma_f32_16x16x32_bf16 v[104:107], v[146:149], v[182:185], v[104:107]
	v_mfma_f32_16x16x32_bf16 v[92:95], v[138:141], v[190:193], v[92:95]
	v_mfma_f32_16x16x32_bf16 v[88:91], v[146:149], v[190:193], v[88:91]
	v_mfma_f32_16x16x32_bf16 v[76:79], v[138:141], v[198:201], v[76:79]
	v_mfma_f32_16x16x32_bf16 v[72:75], v[146:149], v[198:201], v[72:75]
	v_mfma_f32_16x16x32_bf16 v[116:119], v[150:153], v[170:173], v[116:119]
	v_mfma_f32_16x16x32_bf16 v[112:115], v[158:161], v[170:173], v[112:115]
	v_mfma_f32_16x16x32_bf16 v[100:103], v[150:153], v[178:181], v[100:103]
	v_mfma_f32_16x16x32_bf16 v[96:99], v[158:161], v[178:181], v[96:99]
	v_mfma_f32_16x16x32_bf16 v[84:87], v[150:153], v[186:189], v[84:87]
	v_mfma_f32_16x16x32_bf16 v[80:83], v[158:161], v[186:189], v[80:83]
	v_mfma_f32_16x16x32_bf16 v[68:71], v[150:153], v[194:197], v[68:71]
	v_mfma_f32_16x16x32_bf16 v[64:67], v[158:161], v[194:197], v[64:67]
	v_mfma_f32_16x16x32_bf16 v[116:119], v[154:157], v[174:177], v[116:119]
	v_mfma_f32_16x16x32_bf16 v[112:115], v[162:165], v[174:177], v[112:115]
	v_mfma_f32_16x16x32_bf16 v[100:103], v[154:157], v[182:185], v[100:103]
	v_mfma_f32_16x16x32_bf16 v[96:99], v[162:165], v[182:185], v[96:99]
	v_mfma_f32_16x16x32_bf16 v[84:87], v[154:157], v[190:193], v[84:87]
	v_mfma_f32_16x16x32_bf16 v[80:83], v[162:165], v[190:193], v[80:83]
	v_mfma_f32_16x16x32_bf16 v[68:71], v[154:157], v[198:201], v[68:71]
	v_mfma_f32_16x16x32_bf16 v[64:67], v[162:165], v[198:201], v[64:67]
	s_barrier
	s_mov_b32 m0, s63
	v_lshl_add_u64 v[166:167], v[166:167], 0, s[94:95]
	ds_read_b128 v[170:173], v169 offset:49152
	ds_read_b128 v[174:177], v169 offset:50176
	ds_read_b128 v[178:181], v169 offset:51200
	ds_read_b128 v[182:185], v169 offset:52224
	ds_read_b128 v[186:189], v169 offset:53248
	ds_read_b128 v[190:193], v169 offset:54272
	ds_read_b128 v[194:197], v169 offset:55296
	ds_read_b128 v[198:201], v169 offset:56320
	global_load_lds_dwordx4 v[166:167], off
	v_lshl_add_u64 v[166:167], v[202:203], 0, s[94:95]
	s_mov_b32 m0, s62
	s_nop 0
	global_load_lds_dwordx4 v[166:167], off
	v_lshl_add_u64 v[166:167], s[30:31], 0, v[232:233]
	s_mov_b32 m0, s71
	s_nop 0
	global_load_lds_dwordx4 v[166:167], off
	v_lshl_add_u64 v[166:167], s[30:31], 0, v[132:133]
	s_mov_b32 m0, s70
	s_nop 0
	global_load_lds_dwordx4 v[166:167], off
	v_lshl_add_u64 v[166:167], v[204:205], 0, s[94:95]
	s_mov_b32 m0, s57
	s_nop 0
	global_load_lds_dwordx4 v[166:167], off
	v_lshl_add_u64 v[166:167], v[206:207], 0, s[94:95]
	s_mov_b32 m0, s58
	s_nop 0
	global_load_lds_dwordx4 v[166:167], off
	s_waitcnt vmcnt(8)
	s_waitcnt lgkmcnt(0)
	s_barrier
	v_mfma_f32_16x16x32_bf16 v[60:63], v[134:137], v[170:173], v[60:63]
	v_mfma_f32_16x16x32_bf16 v[56:59], v[142:145], v[170:173], v[56:59]
	v_mfma_f32_16x16x32_bf16 v[44:47], v[134:137], v[178:181], v[44:47]
	v_mfma_f32_16x16x32_bf16 v[40:43], v[142:145], v[178:181], v[40:43]
	v_mfma_f32_16x16x32_bf16 v[28:31], v[134:137], v[186:189], v[28:31]
	v_mfma_f32_16x16x32_bf16 v[24:27], v[142:145], v[186:189], v[24:27]
	v_mfma_f32_16x16x32_bf16 v[12:15], v[134:137], v[194:197], v[12:15]
	v_mfma_f32_16x16x32_bf16 v[8:11], v[142:145], v[194:197], v[8:11]
	v_mfma_f32_16x16x32_bf16 v[60:63], v[138:141], v[174:177], v[60:63]
	v_mfma_f32_16x16x32_bf16 v[56:59], v[146:149], v[174:177], v[56:59]
	v_mfma_f32_16x16x32_bf16 v[44:47], v[138:141], v[182:185], v[44:47]
	v_mfma_f32_16x16x32_bf16 v[40:43], v[146:149], v[182:185], v[40:43]
	v_mfma_f32_16x16x32_bf16 v[28:31], v[138:141], v[190:193], v[28:31]
	v_mfma_f32_16x16x32_bf16 v[24:27], v[146:149], v[190:193], v[24:27]
	v_mfma_f32_16x16x32_bf16 v[12:15], v[138:141], v[198:201], v[12:15]
	v_mfma_f32_16x16x32_bf16 v[8:11], v[146:149], v[198:201], v[8:11]
	v_mfma_f32_16x16x32_bf16 v[52:55], v[150:153], v[170:173], v[52:55]
	v_mfma_f32_16x16x32_bf16 v[48:51], v[158:161], v[170:173], v[48:51]
	v_mfma_f32_16x16x32_bf16 v[36:39], v[150:153], v[178:181], v[36:39]
	v_mfma_f32_16x16x32_bf16 v[32:35], v[158:161], v[178:181], v[32:35]
	v_mfma_f32_16x16x32_bf16 v[20:23], v[150:153], v[186:189], v[20:23]
	v_mfma_f32_16x16x32_bf16 v[16:19], v[158:161], v[186:189], v[16:19]
	v_mfma_f32_16x16x32_bf16 v[4:7], v[150:153], v[194:197], v[4:7]
	v_mfma_f32_16x16x32_bf16 v[0:3], v[158:161], v[194:197], v[0:3]
	v_mfma_f32_16x16x32_bf16 v[52:55], v[154:157], v[174:177], v[52:55]
	v_mfma_f32_16x16x32_bf16 v[48:51], v[162:165], v[174:177], v[48:51]
	v_mfma_f32_16x16x32_bf16 v[36:39], v[154:157], v[182:185], v[36:39]
	v_mfma_f32_16x16x32_bf16 v[32:35], v[162:165], v[182:185], v[32:35]
	v_mfma_f32_16x16x32_bf16 v[20:23], v[154:157], v[190:193], v[20:23]
	v_mfma_f32_16x16x32_bf16 v[16:19], v[162:165], v[190:193], v[16:19]
	v_mfma_f32_16x16x32_bf16 v[4:7], v[154:157], v[198:201], v[4:7]
	v_mfma_f32_16x16x32_bf16 v[0:3], v[162:165], v[198:201], v[0:3]
	s_barrier
	s_movk_i32 s34, 0x100
	s_andn2_b64 vcc, exec, s[28:29]
	s_mov_b64 s[30:31], -1
	s_mov_b64 s[28:29], 0
	s_cbranch_vccz .LBB0_369
	s_and_b64 vcc, exec, s[12:13]
	s_cbranch_vccz .LBB0_372
	s_barrier

.LBB0_911:
	s_ashr_i32 s15, s14, 31
	s_lshl_b64 s[16:17], s[14:15], 19
	s_add_u32 s16, s30, s16
	s_addc_u32 s17, s31, s17
	s_and_b64 s[18:19], s[2:3], exec
	s_cselect_b32 s5, s17, s25
	s_cselect_b32 s15, s16, s24
	s_ashr_i32 s13, s12, 31
	s_lshl_b64 s[18:19], s[12:13], 19
	s_add_u32 s18, s34, s18
	s_addc_u32 s19, s35, s19
	s_and_b64 s[26:27], s[2:3], exec
	s_cselect_b32 s13, s19, s23
	s_cselect_b32 s21, s18, s22
	s_add_u32 s48, s22, 0x100
	s_addc_u32 s49, s23, 0
	s_add_u32 s22, s24, 0x40080
	s_addc_u32 s23, s25, 0
	s_mov_b32 s50, -2
	s_add_u32 s24, s22, 0xfffc0080
	s_addc_u32 s25, s23, -1
	s_add_i32 s51, 0, 0x10000
	s_cmp_eq_u32 s50, 12
	s_cselect_b32 s27, s5, s25
	s_cselect_b32 s26, s15, s24
	v_add_u32_e32 v142, s51, v144
	s_cselect_b32 s25, s13, s49
	s_cselect_b32 s24, s21, s48
	s_add_i32 s54, 0, 0x14000
	ds_read_b128 v[138:141], v142
	ds_read_b128 v[146:149], v142 offset:1024
	ds_read_b128 v[150:153], v142 offset:2048
	ds_read_b128 v[154:157], v142 offset:3072
	v_add_u32_e32 v142, s54, v144
	ds_read_b128 v[158:161], v142
	ds_read_b128 v[162:165], v142 offset:1024
	ds_read_b128 v[166:169], v142 offset:2048
	ds_read_b128 v[170:173], v142 offset:3072
	v_lshl_add_u64 v[142:143], s[22:23], 0, v[136:137]
	s_add_i32 m0, s37, 0xc000
	ds_read_b128 v[174:177], v145
	ds_read_b128 v[178:181], v145 offset:1024
	ds_read_b128 v[182:185], v145 offset:2048
	ds_read_b128 v[186:189], v145 offset:3072
	ds_read_b128 v[190:193], v145 offset:4096
	ds_read_b128 v[194:197], v145 offset:5120
	ds_read_b128 v[198:201], v145 offset:6144
	ds_read_b128 v[202:205], v145 offset:7168
	global_load_lds_dwordx4 v[142:143], off
	v_lshl_add_u64 v[142:143], s[22:23], 0, v[134:135]
	s_add_i32 m0, s37, 0xe000
	s_nop 0
	global_load_lds_dwordx4 v[142:143], off
	s_waitcnt vmcnt(8)
	s_waitcnt lgkmcnt(0)
	s_barrier
	v_mfma_f32_16x16x32_bf16 v[124:127], v[138:141], v[174:177], 0
	v_mfma_f32_16x16x32_bf16 v[120:123], v[150:153], v[174:177], 0
	v_mfma_f32_16x16x32_bf16 v[108:111], v[138:141], v[182:185], 0
	v_mfma_f32_16x16x32_bf16 v[104:107], v[150:153], v[182:185], 0
	v_mfma_f32_16x16x32_bf16 v[92:95], v[138:141], v[190:193], 0
	v_mfma_f32_16x16x32_bf16 v[88:91], v[150:153], v[190:193], 0
	v_mfma_f32_16x16x32_bf16 v[76:79], v[138:141], v[198:201], 0
	v_mfma_f32_16x16x32_bf16 v[72:75], v[150:153], v[198:201], 0
	v_mfma_f32_16x16x32_bf16 v[124:127], v[146:149], v[178:181], v[124:127]
	v_mfma_f32_16x16x32_bf16 v[120:123], v[154:157], v[178:181], v[120:123]
	v_mfma_f32_16x16x32_bf16 v[108:111], v[146:149], v[186:189], v[108:111]
	v_mfma_f32_16x16x32_bf16 v[104:107], v[154:157], v[186:189], v[104:107]
	v_mfma_f32_16x16x32_bf16 v[92:95], v[146:149], v[194:197], v[92:95]
	v_mfma_f32_16x16x32_bf16 v[88:91], v[154:157], v[194:197], v[88:91]
	v_mfma_f32_16x16x32_bf16 v[76:79], v[146:149], v[202:205], v[76:79]
	v_mfma_f32_16x16x32_bf16 v[72:75], v[154:157], v[202:205], v[72:75]
	v_mfma_f32_16x16x32_bf16 v[116:119], v[158:161], v[174:177], 0
	v_mfma_f32_16x16x32_bf16 v[112:115], v[166:169], v[174:177], 0
	v_mfma_f32_16x16x32_bf16 v[100:103], v[158:161], v[182:185], 0
	v_mfma_f32_16x16x32_bf16 v[96:99], v[166:169], v[182:185], 0
	v_mfma_f32_16x16x32_bf16 v[84:87], v[158:161], v[190:193], 0
	v_mfma_f32_16x16x32_bf16 v[80:83], v[166:169], v[190:193], 0
	v_mfma_f32_16x16x32_bf16 v[68:71], v[158:161], v[198:201], 0
	v_mfma_f32_16x16x32_bf16 v[64:67], v[166:169], v[198:201], 0
	v_mfma_f32_16x16x32_bf16 v[116:119], v[162:165], v[178:181], v[116:119]
	v_mfma_f32_16x16x32_bf16 v[112:115], v[170:173], v[178:181], v[112:115]
	v_mfma_f32_16x16x32_bf16 v[100:103], v[162:165], v[186:189], v[100:103]
	v_mfma_f32_16x16x32_bf16 v[96:99], v[170:173], v[186:189], v[96:99]
	v_mfma_f32_16x16x32_bf16 v[84:87], v[162:165], v[194:197], v[84:87]
	v_mfma_f32_16x16x32_bf16 v[80:83], v[170:173], v[194:197], v[80:83]
	v_mfma_f32_16x16x32_bf16 v[68:71], v[162:165], v[202:205], v[68:71]
	v_mfma_f32_16x16x32_bf16 v[64:67], v[170:173], v[202:205], v[64:67]
	s_barrier
	s_add_i32 s51, s51, s36
	v_lshl_add_u64 v[142:143], s[24:25], 0, v[232:233]
	s_mov_b32 m0, s51
	ds_read_b128 v[174:177], v145 offset:16384
	ds_read_b128 v[178:181], v145 offset:17408
	ds_read_b128 v[182:185], v145 offset:18432
	ds_read_b128 v[186:189], v145 offset:19456
	ds_read_b128 v[190:193], v145 offset:20480
	ds_read_b128 v[194:197], v145 offset:21504
	ds_read_b128 v[198:201], v145 offset:22528
	ds_read_b128 v[202:205], v145 offset:23552
	global_load_lds_dwordx4 v[142:143], off
	s_add_i32 m0, s51, 0x2000
	s_add_u32 s52, s24, 0x40000
	v_lshl_add_u64 v[206:207], s[24:25], 0, v[132:133]
	s_addc_u32 s53, s25, 0
	s_add_i32 s51, s54, s36
	global_load_lds_dwordx4 v[206:207], off
	v_lshl_add_u64 v[208:209], s[52:53], 0, v[232:233]
	s_mov_b32 m0, s51
	v_lshl_add_u64 v[210:211], s[26:27], 0, v[130:131]
	global_load_lds_dwordx4 v[208:209], off
	v_lshl_add_u64 v[208:209], s[52:53], 0, v[132:133]
	s_add_i32 m0, s51, 0x2000
	s_nop 0
	global_load_lds_dwordx4 v[208:209], off
	v_lshl_add_u64 v[208:209], s[26:27], 0, v[128:129]
	s_waitcnt vmcnt(6)
	s_waitcnt lgkmcnt(0)
	s_barrier
	v_mfma_f32_16x16x32_bf16 v[60:63], v[138:141], v[174:177], 0
	v_mfma_f32_16x16x32_bf16 v[56:59], v[150:153], v[174:177], 0
	v_mfma_f32_16x16x32_bf16 v[44:47], v[138:141], v[182:185], 0
	v_mfma_f32_16x16x32_bf16 v[40:43], v[150:153], v[182:185], 0
	v_mfma_f32_16x16x32_bf16 v[28:31], v[138:141], v[190:193], 0
	v_mfma_f32_16x16x32_bf16 v[24:27], v[150:153], v[190:193], 0
	v_mfma_f32_16x16x32_bf16 v[12:15], v[138:141], v[198:201], 0
	v_mfma_f32_16x16x32_bf16 v[8:11], v[150:153], v[198:201], 0
	v_mfma_f32_16x16x32_bf16 v[60:63], v[146:149], v[178:181], v[60:63]
	v_mfma_f32_16x16x32_bf16 v[56:59], v[154:157], v[178:181], v[56:59]
	v_mfma_f32_16x16x32_bf16 v[44:47], v[146:149], v[186:189], v[44:47]
	v_mfma_f32_16x16x32_bf16 v[40:43], v[154:157], v[186:189], v[40:43]
	v_mfma_f32_16x16x32_bf16 v[28:31], v[146:149], v[194:197], v[28:31]
	v_mfma_f32_16x16x32_bf16 v[24:27], v[154:157], v[194:197], v[24:27]
	v_mfma_f32_16x16x32_bf16 v[12:15], v[146:149], v[202:205], v[12:15]
	v_mfma_f32_16x16x32_bf16 v[8:11], v[154:157], v[202:205], v[8:11]
	v_mfma_f32_16x16x32_bf16 v[52:55], v[158:161], v[174:177], 0
	v_mfma_f32_16x16x32_bf16 v[48:51], v[166:169], v[174:177], 0
	v_mfma_f32_16x16x32_bf16 v[36:39], v[158:161], v[182:185], 0
	v_mfma_f32_16x16x32_bf16 v[32:35], v[166:169], v[182:185], 0
	v_mfma_f32_16x16x32_bf16 v[20:23], v[158:161], v[190:193], 0
	v_mfma_f32_16x16x32_bf16 v[16:19], v[166:169], v[190:193], 0
	v_mfma_f32_16x16x32_bf16 v[4:7], v[158:161], v[198:201], 0
	v_mfma_f32_16x16x32_bf16 v[0:3], v[166:169], v[198:201], 0
	v_mfma_f32_16x16x32_bf16 v[52:55], v[162:165], v[178:181], v[52:55]
	v_mfma_f32_16x16x32_bf16 v[48:51], v[170:173], v[178:181], v[48:51]
	v_mfma_f32_16x16x32_bf16 v[36:39], v[162:165], v[186:189], v[36:39]
	v_mfma_f32_16x16x32_bf16 v[32:35], v[170:173], v[186:189], v[32:35]
	v_mfma_f32_16x16x32_bf16 v[20:23], v[162:165], v[194:197], v[20:23]
	v_mfma_f32_16x16x32_bf16 v[16:19], v[170:173], v[194:197], v[16:19]
	v_mfma_f32_16x16x32_bf16 v[4:7], v[162:165], v[202:205], v[4:7]
	v_mfma_f32_16x16x32_bf16 v[0:3], v[170:173], v[202:205], v[0:3]
	s_barrier
	s_branch .Lzmid_2
.LBB0_912:
	s_add_u32 s24, s22, 0xfffc0080
	s_addc_u32 s25, s23, -1
	s_add_i32 s51, 0, 0x10000
	s_cmp_eq_u32 s50, 12
	s_cselect_b32 s27, s5, s25
	s_cselect_b32 s26, s15, s24
	v_add_u32_e32 v142, s51, v144
	s_cselect_b32 s25, s13, s49
	s_cselect_b32 s24, s21, s48
	s_add_i32 s54, 0, 0x14000
	ds_read_b128 v[138:141], v142
	ds_read_b128 v[146:149], v142 offset:1024
	ds_read_b128 v[150:153], v142 offset:2048
	ds_read_b128 v[154:157], v142 offset:3072
	v_add_u32_e32 v142, s54, v144
	ds_read_b128 v[158:161], v142
	ds_read_b128 v[162:165], v142 offset:1024
	ds_read_b128 v[166:169], v142 offset:2048
	ds_read_b128 v[170:173], v142 offset:3072
	v_lshl_add_u64 v[142:143], s[22:23], 0, v[136:137]
	s_add_i32 m0, s37, 0xc000
	ds_read_b128 v[174:177], v145
	ds_read_b128 v[178:181], v145 offset:1024
	ds_read_b128 v[182:185], v145 offset:2048
	ds_read_b128 v[186:189], v145 offset:3072
	ds_read_b128 v[190:193], v145 offset:4096
	ds_read_b128 v[194:197], v145 offset:5120
	ds_read_b128 v[198:201], v145 offset:6144
	ds_read_b128 v[202:205], v145 offset:7168
	global_load_lds_dwordx4 v[142:143], off
	v_lshl_add_u64 v[142:143], s[22:23], 0, v[134:135]
	s_add_i32 m0, s37, 0xe000
	s_nop 0
	global_load_lds_dwordx4 v[142:143], off
	s_waitcnt vmcnt(8)
	s_waitcnt lgkmcnt(0)
	s_barrier
	v_mfma_f32_16x16x32_bf16 v[124:127], v[138:141], v[174:177], v[124:127]
	v_mfma_f32_16x16x32_bf16 v[120:123], v[150:153], v[174:177], v[120:123]
	v_mfma_f32_16x16x32_bf16 v[108:111], v[138:141], v[182:185], v[108:111]
	v_mfma_f32_16x16x32_bf16 v[104:107], v[150:153], v[182:185], v[104:107]
	v_mfma_f32_16x16x32_bf16 v[92:95], v[138:141], v[190:193], v[92:95]
	v_mfma_f32_16x16x32_bf16 v[88:91], v[150:153], v[190:193], v[88:91]
	v_mfma_f32_16x16x32_bf16 v[76:79], v[138:141], v[198:201], v[76:79]
	v_mfma_f32_16x16x32_bf16 v[72:75], v[150:153], v[198:201], v[72:75]
	v_mfma_f32_16x16x32_bf16 v[124:127], v[146:149], v[178:181], v[124:127]
	v_mfma_f32_16x16x32_bf16 v[120:123], v[154:157], v[178:181], v[120:123]
	v_mfma_f32_16x16x32_bf16 v[108:111], v[146:149], v[186:189], v[108:111]
	v_mfma_f32_16x16x32_bf16 v[104:107], v[154:157], v[186:189], v[104:107]
	v_mfma_f32_16x16x32_bf16 v[92:95], v[146:149], v[194:197], v[92:95]
	v_mfma_f32_16x16x32_bf16 v[88:91], v[154:157], v[194:197], v[88:91]
	v_mfma_f32_16x16x32_bf16 v[76:79], v[146:149], v[202:205], v[76:79]
	v_mfma_f32_16x16x32_bf16 v[72:75], v[154:157], v[202:205], v[72:75]
	v_mfma_f32_16x16x32_bf16 v[116:119], v[158:161], v[174:177], v[116:119]
	v_mfma_f32_16x16x32_bf16 v[112:115], v[166:169], v[174:177], v[112:115]
	v_mfma_f32_16x16x32_bf16 v[100:103], v[158:161], v[182:185], v[100:103]
	v_mfma_f32_16x16x32_bf16 v[96:99], v[166:169], v[182:185], v[96:99]
	v_mfma_f32_16x16x32_bf16 v[84:87], v[158:161], v[190:193], v[84:87]
	v_mfma_f32_16x16x32_bf16 v[80:83], v[166:169], v[190:193], v[80:83]
	v_mfma_f32_16x16x32_bf16 v[68:71], v[158:161], v[198:201], v[68:71]
	v_mfma_f32_16x16x32_bf16 v[64:67], v[166:169], v[198:201], v[64:67]
	v_mfma_f32_16x16x32_bf16 v[116:119], v[162:165], v[178:181], v[116:119]
	v_mfma_f32_16x16x32_bf16 v[112:115], v[170:173], v[178:181], v[112:115]
	v_mfma_f32_16x16x32_bf16 v[100:103], v[162:165], v[186:189], v[100:103]
	v_mfma_f32_16x16x32_bf16 v[96:99], v[170:173], v[186:189], v[96:99]
	v_mfma_f32_16x16x32_bf16 v[84:87], v[162:165], v[194:197], v[84:87]
	v_mfma_f32_16x16x32_bf16 v[80:83], v[170:173], v[194:197], v[80:83]
	v_mfma_f32_16x16x32_bf16 v[68:71], v[162:165], v[202:205], v[68:71]
	v_mfma_f32_16x16x32_bf16 v[64:67], v[170:173], v[202:205], v[64:67]
	s_barrier
	s_add_i32 s51, s51, s36
	v_lshl_add_u64 v[142:143], s[24:25], 0, v[232:233]
	s_mov_b32 m0, s51
	ds_read_b128 v[174:177], v145 offset:16384
	ds_read_b128 v[178:181], v145 offset:17408
	ds_read_b128 v[182:185], v145 offset:18432
	ds_read_b128 v[186:189], v145 offset:19456
	ds_read_b128 v[190:193], v145 offset:20480
	ds_read_b128 v[194:197], v145 offset:21504
	ds_read_b128 v[198:201], v145 offset:22528
	ds_read_b128 v[202:205], v145 offset:23552
	global_load_lds_dwordx4 v[142:143], off
	s_add_i32 m0, s51, 0x2000
	s_add_u32 s52, s24, 0x40000
	v_lshl_add_u64 v[206:207], s[24:25], 0, v[132:133]
	s_addc_u32 s53, s25, 0
	s_add_i32 s51, s54, s36
	global_load_lds_dwordx4 v[206:207], off
	v_lshl_add_u64 v[208:209], s[52:53], 0, v[232:233]
	s_mov_b32 m0, s51
	v_lshl_add_u64 v[210:211], s[26:27], 0, v[130:131]
	global_load_lds_dwordx4 v[208:209], off
	v_lshl_add_u64 v[208:209], s[52:53], 0, v[132:133]
	s_add_i32 m0, s51, 0x2000
	s_nop 0
	global_load_lds_dwordx4 v[208:209], off
	v_lshl_add_u64 v[208:209], s[26:27], 0, v[128:129]
	s_waitcnt vmcnt(6)
	s_waitcnt lgkmcnt(0)
	s_barrier
	v_mfma_f32_16x16x32_bf16 v[60:63], v[138:141], v[174:177], v[60:63]
	v_mfma_f32_16x16x32_bf16 v[56:59], v[150:153], v[174:177], v[56:59]
	v_mfma_f32_16x16x32_bf16 v[44:47], v[138:141], v[182:185], v[44:47]
	v_mfma_f32_16x16x32_bf16 v[40:43], v[150:153], v[182:185], v[40:43]
	v_mfma_f32_16x16x32_bf16 v[28:31], v[138:141], v[190:193], v[28:31]
	v_mfma_f32_16x16x32_bf16 v[24:27], v[150:153], v[190:193], v[24:27]
	v_mfma_f32_16x16x32_bf16 v[12:15], v[138:141], v[198:201], v[12:15]
	v_mfma_f32_16x16x32_bf16 v[8:11], v[150:153], v[198:201], v[8:11]
	v_mfma_f32_16x16x32_bf16 v[60:63], v[146:149], v[178:181], v[60:63]
	v_mfma_f32_16x16x32_bf16 v[56:59], v[154:157], v[178:181], v[56:59]
	v_mfma_f32_16x16x32_bf16 v[44:47], v[146:149], v[186:189], v[44:47]
	v_mfma_f32_16x16x32_bf16 v[40:43], v[154:157], v[186:189], v[40:43]
	v_mfma_f32_16x16x32_bf16 v[28:31], v[146:149], v[194:197], v[28:31]
	v_mfma_f32_16x16x32_bf16 v[24:27], v[154:157], v[194:197], v[24:27]
	v_mfma_f32_16x16x32_bf16 v[12:15], v[146:149], v[202:205], v[12:15]
	v_mfma_f32_16x16x32_bf16 v[8:11], v[154:157], v[202:205], v[8:11]
	v_mfma_f32_16x16x32_bf16 v[52:55], v[158:161], v[174:177], v[52:55]
	v_mfma_f32_16x16x32_bf16 v[48:51], v[166:169], v[174:177], v[48:51]
	v_mfma_f32_16x16x32_bf16 v[36:39], v[158:161], v[182:185], v[36:39]
	v_mfma_f32_16x16x32_bf16 v[32:35], v[166:169], v[182:185], v[32:35]
	v_mfma_f32_16x16x32_bf16 v[20:23], v[158:161], v[190:193], v[20:23]
	v_mfma_f32_16x16x32_bf16 v[16:19], v[166:169], v[190:193], v[16:19]
	v_mfma_f32_16x16x32_bf16 v[4:7], v[158:161], v[198:201], v[4:7]
	v_mfma_f32_16x16x32_bf16 v[0:3], v[166:169], v[198:201], v[0:3]
	v_mfma_f32_16x16x32_bf16 v[52:55], v[162:165], v[178:181], v[52:55]
	v_mfma_f32_16x16x32_bf16 v[48:51], v[170:173], v[178:181], v[48:51]
	v_mfma_f32_16x16x32_bf16 v[36:39], v[162:165], v[186:189], v[36:39]
	v_mfma_f32_16x16x32_bf16 v[32:35], v[170:173], v[186:189], v[32:35]
	v_mfma_f32_16x16x32_bf16 v[20:23], v[162:165], v[194:197], v[20:23]
	v_mfma_f32_16x16x32_bf16 v[16:19], v[170:173], v[194:197], v[16:19]
	v_mfma_f32_16x16x32_bf16 v[4:7], v[162:165], v[202:205], v[4:7]
	v_mfma_f32_16x16x32_bf16 v[0:3], v[170:173], v[202:205], v[0:3]
	s_barrier
.Lzmid_2:
	s_add_i32 s51, 0, 0x18000
	s_add_i32 s52, 0, 0x1c000
	v_add_u32_e32 v154, s51, v144
	v_add_u32_e32 v170, s52, v144
	ds_read_b128 v[138:141], v154
	ds_read_b128 v[146:149], v154 offset:1024
	ds_read_b128 v[150:153], v154 offset:2048
	ds_read_b128 v[154:157], v154 offset:3072
	ds_read_b128 v[158:161], v170
	ds_read_b128 v[162:165], v170 offset:1024
	ds_read_b128 v[166:169], v170 offset:2048
	ds_read_b128 v[170:173], v170 offset:3072
	s_add_u32 s26, s26, 0x40000
	s_addc_u32 s27, s27, 0
	s_mov_b32 m0, s37
	s_nop 0
	global_load_lds_dwordx4 v[208:209], off
	s_mov_b32 m0, s38
	s_nop 0
	global_load_lds_dwordx4 v[210:211], off
	s_mov_b32 m0, s39
	v_lshl_add_u64 v[212:213], s[26:27], 0, v[128:129]
	ds_read_b128 v[174:177], v145 offset:32768
	ds_read_b128 v[178:181], v145 offset:33792
	ds_read_b128 v[182:185], v145 offset:34816
	ds_read_b128 v[186:189], v145 offset:35840
	ds_read_b128 v[190:193], v145 offset:36864
	ds_read_b128 v[194:197], v145 offset:37888
	ds_read_b128 v[198:201], v145 offset:38912
	ds_read_b128 v[202:205], v145 offset:39936
	global_load_lds_dwordx4 v[212:213], off
	v_lshl_add_u64 v[212:213], s[26:27], 0, v[130:131]
	s_mov_b32 m0, s40
	s_nop 0
	global_load_lds_dwordx4 v[212:213], off
	s_waitcnt vmcnt(8)
	s_waitcnt lgkmcnt(0)
	s_barrier
	v_mfma_f32_16x16x32_bf16 v[124:127], v[138:141], v[174:177], v[124:127]
	v_mfma_f32_16x16x32_bf16 v[120:123], v[150:153], v[174:177], v[120:123]
	v_mfma_f32_16x16x32_bf16 v[108:111], v[138:141], v[182:185], v[108:111]
	v_mfma_f32_16x16x32_bf16 v[104:107], v[150:153], v[182:185], v[104:107]
	v_mfma_f32_16x16x32_bf16 v[92:95], v[138:141], v[190:193], v[92:95]
	v_mfma_f32_16x16x32_bf16 v[88:91], v[150:153], v[190:193], v[88:91]
	v_mfma_f32_16x16x32_bf16 v[76:79], v[138:141], v[198:201], v[76:79]
	v_mfma_f32_16x16x32_bf16 v[72:75], v[150:153], v[198:201], v[72:75]
	v_mfma_f32_16x16x32_bf16 v[124:127], v[146:149], v[178:181], v[124:127]
	v_mfma_f32_16x16x32_bf16 v[120:123], v[154:157], v[178:181], v[120:123]
	v_mfma_f32_16x16x32_bf16 v[108:111], v[146:149], v[186:189], v[108:111]
	v_mfma_f32_16x16x32_bf16 v[104:107], v[154:157], v[186:189], v[104:107]
	v_mfma_f32_16x16x32_bf16 v[92:95], v[146:149], v[194:197], v[92:95]
	v_mfma_f32_16x16x32_bf16 v[88:91], v[154:157], v[194:197], v[88:91]
	v_mfma_f32_16x16x32_bf16 v[76:79], v[146:149], v[202:205], v[76:79]
	v_mfma_f32_16x16x32_bf16 v[72:75], v[154:157], v[202:205], v[72:75]
	v_mfma_f32_16x16x32_bf16 v[116:119], v[158:161], v[174:177], v[116:119]
	v_mfma_f32_16x16x32_bf16 v[112:115], v[166:169], v[174:177], v[112:115]
	v_mfma_f32_16x16x32_bf16 v[100:103], v[158:161], v[182:185], v[100:103]
	v_mfma_f32_16x16x32_bf16 v[96:99], v[166:169], v[182:185], v[96:99]
	v_mfma_f32_16x16x32_bf16 v[84:87], v[158:161], v[190:193], v[84:87]
	v_mfma_f32_16x16x32_bf16 v[80:83], v[166:169], v[190:193], v[80:83]
	v_mfma_f32_16x16x32_bf16 v[68:71], v[158:161], v[198:201], v[68:71]
	v_mfma_f32_16x16x32_bf16 v[64:67], v[166:169], v[198:201], v[64:67]
	v_mfma_f32_16x16x32_bf16 v[116:119], v[162:165], v[178:181], v[116:119]
	v_mfma_f32_16x16x32_bf16 v[112:115], v[170:173], v[178:181], v[112:115]
	v_mfma_f32_16x16x32_bf16 v[100:103], v[162:165], v[186:189], v[100:103]
	v_mfma_f32_16x16x32_bf16 v[96:99], v[170:173], v[186:189], v[96:99]
	v_mfma_f32_16x16x32_bf16 v[84:87], v[162:165], v[194:197], v[84:87]
	v_mfma_f32_16x16x32_bf16 v[80:83], v[170:173], v[194:197], v[80:83]
	v_mfma_f32_16x16x32_bf16 v[68:71], v[162:165], v[202:205], v[68:71]
	v_mfma_f32_16x16x32_bf16 v[64:67], v[170:173], v[202:205], v[64:67]
	s_barrier
	s_add_i32 s26, s51, s36
	v_lshl_add_u64 v[142:143], v[142:143], 0, s[94:95]
	s_mov_b32 m0, s26
	ds_read_b128 v[174:177], v145 offset:49152
	ds_read_b128 v[178:181], v145 offset:50176
	ds_read_b128 v[182:185], v145 offset:51200
	ds_read_b128 v[186:189], v145 offset:52224
	ds_read_b128 v[190:193], v145 offset:53248
	ds_read_b128 v[194:197], v145 offset:54272
	ds_read_b128 v[198:201], v145 offset:55296
	ds_read_b128 v[202:205], v145 offset:56320
	global_load_lds_dwordx4 v[142:143], off
	s_add_i32 m0, s26, 0x2000
	s_add_u32 s24, s24, 0x40080
	v_lshl_add_u64 v[142:143], v[206:207], 0, s[94:95]
	s_addc_u32 s25, s25, 0
	s_add_i32 s26, s52, s36
	global_load_lds_dwordx4 v[142:143], off
	v_lshl_add_u64 v[142:143], s[24:25], 0, v[232:233]
	s_mov_b32 m0, s26
	s_nop 0
	global_load_lds_dwordx4 v[142:143], off
	v_lshl_add_u64 v[142:143], s[24:25], 0, v[132:133]
	s_add_i32 m0, s26, 0x2000
	s_nop 0
	global_load_lds_dwordx4 v[142:143], off
	v_lshl_add_u64 v[142:143], v[208:209], 0, s[94:95]
	s_mov_b32 m0, s43
	s_nop 0
	global_load_lds_dwordx4 v[142:143], off
	v_lshl_add_u64 v[142:143], v[210:211], 0, s[94:95]
	s_mov_b32 m0, s44
	s_nop 0
	global_load_lds_dwordx4 v[142:143], off
	s_waitcnt vmcnt(8)
	s_waitcnt lgkmcnt(0)
	s_barrier
	v_mfma_f32_16x16x32_bf16 v[60:63], v[138:141], v[174:177], v[60:63]
	v_mfma_f32_16x16x32_bf16 v[56:59], v[150:153], v[174:177], v[56:59]
	v_mfma_f32_16x16x32_bf16 v[44:47], v[138:141], v[182:185], v[44:47]
	v_mfma_f32_16x16x32_bf16 v[40:43], v[150:153], v[182:185], v[40:43]
	v_mfma_f32_16x16x32_bf16 v[28:31], v[138:141], v[190:193], v[28:31]
	v_mfma_f32_16x16x32_bf16 v[24:27], v[150:153], v[190:193], v[24:27]
	v_mfma_f32_16x16x32_bf16 v[12:15], v[138:141], v[198:201], v[12:15]
	v_mfma_f32_16x16x32_bf16 v[8:11], v[150:153], v[198:201], v[8:11]
	v_mfma_f32_16x16x32_bf16 v[60:63], v[146:149], v[178:181], v[60:63]
	v_mfma_f32_16x16x32_bf16 v[56:59], v[154:157], v[178:181], v[56:59]
	v_mfma_f32_16x16x32_bf16 v[44:47], v[146:149], v[186:189], v[44:47]
	v_mfma_f32_16x16x32_bf16 v[40:43], v[154:157], v[186:189], v[40:43]
	v_mfma_f32_16x16x32_bf16 v[28:31], v[146:149], v[194:197], v[28:31]
	v_mfma_f32_16x16x32_bf16 v[24:27], v[154:157], v[194:197], v[24:27]
	v_mfma_f32_16x16x32_bf16 v[12:15], v[146:149], v[202:205], v[12:15]
	v_mfma_f32_16x16x32_bf16 v[8:11], v[154:157], v[202:205], v[8:11]
	v_mfma_f32_16x16x32_bf16 v[52:55], v[158:161], v[174:177], v[52:55]
	v_mfma_f32_16x16x32_bf16 v[48:51], v[166:169], v[174:177], v[48:51]
	v_mfma_f32_16x16x32_bf16 v[36:39], v[158:161], v[182:185], v[36:39]
	v_mfma_f32_16x16x32_bf16 v[32:35], v[166:169], v[182:185], v[32:35]
	v_mfma_f32_16x16x32_bf16 v[20:23], v[158:161], v[190:193], v[20:23]
	v_mfma_f32_16x16x32_bf16 v[16:19], v[166:169], v[190:193], v[16:19]
	v_mfma_f32_16x16x32_bf16 v[4:7], v[158:161], v[198:201], v[4:7]
	v_mfma_f32_16x16x32_bf16 v[0:3], v[166:169], v[198:201], v[0:3]
	v_mfma_f32_16x16x32_bf16 v[52:55], v[162:165], v[178:181], v[52:55]
	v_mfma_f32_16x16x32_bf16 v[48:51], v[170:173], v[178:181], v[48:51]
	v_mfma_f32_16x16x32_bf16 v[36:39], v[162:165], v[186:189], v[36:39]
	v_mfma_f32_16x16x32_bf16 v[32:35], v[170:173], v[186:189], v[32:35]
	v_mfma_f32_16x16x32_bf16 v[20:23], v[162:165], v[194:197], v[20:23]
	v_mfma_f32_16x16x32_bf16 v[16:19], v[170:173], v[194:197], v[16:19]
	v_mfma_f32_16x16x32_bf16 v[4:7], v[162:165], v[202:205], v[4:7]
	v_mfma_f32_16x16x32_bf16 v[0:3], v[170:173], v[202:205], v[0:3]
	s_barrier
	s_add_i32 s50, s50, 2
	s_add_u32 s48, s48, 0x100
	s_addc_u32 s49, s49, 0
	s_add_u32 s22, s22, 0x100
	s_addc_u32 s23, s23, 0
	s_cmp_gt_u32 s50, 13
	s_cbranch_scc0 .LBB0_912
	s_and_b64 vcc, exec, s[10:11]
	s_cbranch_vccz .LBB0_915
	s_barrier

.LBB0_1018:
	s_ashr_i32 s15, s14, 31
	s_ashr_i32 s13, s12, 31
	s_lshl_b64 s[16:17], s[14:15], 19
	s_lshl_b64 s[18:19], s[12:13], 9
	s_add_u32 s13, s34, s16
	s_addc_u32 s15, s35, s17
	s_add_u32 s16, s13, s18
	s_addc_u32 s17, s15, s19
	s_and_b64 s[18:19], s[2:3], exec
	s_cselect_b32 s29, s17, s23
	s_cselect_b32 s28, s16, s22
	s_lshl_b32 s13, s12, 2
	s_add_i32 s18, s13, s51
	s_ashr_i32 s19, s18, 31
	s_lshl_b64 s[18:19], s[18:19], 17
	s_add_u32 s18, s36, s18
	s_addc_u32 s19, s37, s19
	s_and_b64 s[26:27], s[2:3], exec
	s_cselect_b32 s27, s19, s25
	s_cselect_b32 s26, s18, s24
	s_add_i32 s15, 0, 0x10000
	s_add_i32 s21, 0, 0x14000
	v_add_u32_e32 v253, 0x10000, v174
	v_add_u32_e32 v252, 0x14000, v174
	ds_read_b128 v[128:131], v253
	ds_read_b128 v[132:135], v253 offset:1024
	ds_read_b128 v[136:139], v253 offset:2048
	ds_read_b128 v[140:143], v253 offset:3072
	ds_read_b128 v[144:147], v252
	ds_read_b128 v[148:151], v252 offset:1024
	ds_read_b128 v[152:155], v252 offset:2048
	ds_read_b128 v[156:159], v252 offset:3072
	s_add_u32 s52, s22, 0x40080
	s_addc_u32 s53, s23, 0
	s_add_i32 s55, s39, 0xc000
	s_waitcnt vmcnt(0)
	s_mov_b32 m0, s55
	s_add_i32 s13, s39, 0xe000
	ds_read_b128 v[168:171], v175
	ds_read_b128 v[176:179], v175 offset:1024
	ds_read_b128 v[180:183], v175 offset:2048
	ds_read_b128 v[184:187], v175 offset:3072
	ds_read_b128 v[188:191], v175 offset:4096
	ds_read_b128 v[192:195], v175 offset:5120
	ds_read_b128 v[196:199], v175 offset:6144
	ds_read_b128 v[200:203], v175 offset:7168
	global_load_lds_dwordx4 v160, s[52:53]
	s_mov_b32 m0, s13
	s_nop 0
	global_load_lds_dwordx4 v162, s[52:53]
	s_waitcnt vmcnt(8)
	s_waitcnt lgkmcnt(0)
	s_barrier
	v_mfma_f32_16x16x32_bf16 v[0:3], v[128:131], v[168:171], 0
	v_mfma_f32_16x16x32_bf16 v[4:7], v[136:139], v[168:171], 0
	v_mfma_f32_16x16x32_bf16 v[16:19], v[128:131], v[180:183], 0
	v_mfma_f32_16x16x32_bf16 v[20:23], v[136:139], v[180:183], 0
	v_mfma_f32_16x16x32_bf16 v[32:35], v[128:131], v[188:191], 0
	v_mfma_f32_16x16x32_bf16 v[36:39], v[136:139], v[188:191], 0
	v_mfma_f32_16x16x32_bf16 v[48:51], v[128:131], v[196:199], 0
	v_mfma_f32_16x16x32_bf16 v[52:55], v[136:139], v[196:199], 0
	v_mfma_f32_16x16x32_bf16 v[0:3], v[132:135], v[176:179], v[0:3]
	v_mfma_f32_16x16x32_bf16 v[4:7], v[140:143], v[176:179], v[4:7]
	v_mfma_f32_16x16x32_bf16 v[16:19], v[132:135], v[184:187], v[16:19]
	v_mfma_f32_16x16x32_bf16 v[20:23], v[140:143], v[184:187], v[20:23]
	v_mfma_f32_16x16x32_bf16 v[32:35], v[132:135], v[192:195], v[32:35]
	v_mfma_f32_16x16x32_bf16 v[36:39], v[140:143], v[192:195], v[36:39]
	v_mfma_f32_16x16x32_bf16 v[48:51], v[132:135], v[200:203], v[48:51]
	v_mfma_f32_16x16x32_bf16 v[52:55], v[140:143], v[200:203], v[52:55]
	v_mfma_f32_16x16x32_bf16 v[8:11], v[144:147], v[168:171], 0
	v_mfma_f32_16x16x32_bf16 v[12:15], v[152:155], v[168:171], 0
	v_mfma_f32_16x16x32_bf16 v[8:11], v[148:151], v[176:179], v[8:11]
	v_mfma_f32_16x16x32_bf16 v[12:15], v[156:159], v[176:179], v[12:15]
	v_mfma_f32_16x16x32_bf16 v[24:27], v[144:147], v[180:183], 0
	v_mfma_f32_16x16x32_bf16 v[28:31], v[152:155], v[180:183], 0
	v_mfma_f32_16x16x32_bf16 v[24:27], v[148:151], v[184:187], v[24:27]
	v_mfma_f32_16x16x32_bf16 v[28:31], v[156:159], v[184:187], v[28:31]
	v_mfma_f32_16x16x32_bf16 v[40:43], v[144:147], v[188:191], 0
	v_mfma_f32_16x16x32_bf16 v[44:47], v[152:155], v[188:191], 0
	v_mfma_f32_16x16x32_bf16 v[40:43], v[148:151], v[192:195], v[40:43]
	v_mfma_f32_16x16x32_bf16 v[44:47], v[156:159], v[192:195], v[44:47]
	v_mfma_f32_16x16x32_bf16 v[56:59], v[144:147], v[196:199], 0
	v_mfma_f32_16x16x32_bf16 v[60:63], v[152:155], v[196:199], 0
	v_mfma_f32_16x16x32_bf16 v[56:59], v[148:151], v[200:203], v[56:59]
	v_mfma_f32_16x16x32_bf16 v[60:63], v[156:159], v[200:203], v[60:63]
	s_barrier
	s_add_i32 s53, s15, s38
	s_mov_b64 s[58:59], 0x100
	s_add_i32 s15, s53, 0x2000
	s_add_u32 s68, s24, s58
	s_addc_u32 s69, s25, s59
	s_mov_b32 m0, s53
	s_add_u32 s70, s24, s58
	s_addc_u32 s71, s25, s59
	s_add_u32 s56, s24, 0x10100
	ds_read_b128 v[168:171], v175 offset:16384
	ds_read_b128 v[176:179], v175 offset:17408
	ds_read_b128 v[180:183], v175 offset:18432
	ds_read_b128 v[184:187], v175 offset:19456
	ds_read_b128 v[188:191], v175 offset:20480
	ds_read_b128 v[192:195], v175 offset:21504
	ds_read_b128 v[196:199], v175 offset:22528
	ds_read_b128 v[200:203], v175 offset:23552
	global_load_lds_dwordx4 v232, s[68:69]
	s_mov_b32 m0, s15
	s_addc_u32 s57, s25, 0
	s_add_i32 s21, s21, s38
	global_load_lds_dwordx4 v164, s[70:71]
	s_mov_b32 m0, s21
	s_add_i32 s52, s21, 0x2000
	global_load_lds_dwordx4 v232, s[56:57]
	s_mov_b32 m0, s52
	global_load_lds_dwordx4 v164, s[56:57]
	s_add_u32 s68, s22, s58
	s_addc_u32 s69, s23, s59
	s_mov_b32 m0, s39
	global_load_lds_dwordx4 v160, s[68:69]
	s_add_u32 s68, s22, s58
	s_addc_u32 s69, s23, s59
	s_mov_b32 m0, s40
	s_nop 0
	global_load_lds_dwordx4 v162, s[68:69]
	s_waitcnt vmcnt(8)
	s_waitcnt lgkmcnt(0)
	s_barrier
	v_mfma_f32_16x16x32_bf16 v[64:67], v[128:131], v[168:171], 0
	v_mfma_f32_16x16x32_bf16 v[80:83], v[128:131], v[180:183], 0
	v_mfma_f32_16x16x32_bf16 v[96:99], v[128:131], v[188:191], 0
	v_mfma_f32_16x16x32_bf16 v[112:115], v[128:131], v[196:199], 0
	v_mfma_f32_16x16x32_bf16 v[64:67], v[132:135], v[176:179], v[64:67]
	v_mfma_f32_16x16x32_bf16 v[68:71], v[136:139], v[168:171], 0
	v_mfma_f32_16x16x32_bf16 v[80:83], v[132:135], v[184:187], v[80:83]
	v_mfma_f32_16x16x32_bf16 v[84:87], v[136:139], v[180:183], 0
	v_mfma_f32_16x16x32_bf16 v[96:99], v[132:135], v[192:195], v[96:99]
	v_mfma_f32_16x16x32_bf16 v[112:115], v[132:135], v[200:203], v[112:115]
	v_mfma_f32_16x16x32_bf16 v[116:119], v[136:139], v[196:199], 0
	v_mfma_f32_16x16x32_bf16 v[68:71], v[140:143], v[176:179], v[68:71]
	v_mfma_f32_16x16x32_bf16 v[84:87], v[140:143], v[184:187], v[84:87]
	v_mfma_f32_16x16x32_bf16 v[100:103], v[136:139], v[188:191], 0
	v_mfma_f32_16x16x32_bf16 v[116:119], v[140:143], v[200:203], v[116:119]
	v_mfma_f32_16x16x32_bf16 v[100:103], v[140:143], v[192:195], v[100:103]
	v_mfma_f32_16x16x32_bf16 v[72:75], v[144:147], v[168:171], 0
	v_mfma_f32_16x16x32_bf16 v[76:79], v[152:155], v[168:171], 0
	v_mfma_f32_16x16x32_bf16 v[72:75], v[148:151], v[176:179], v[72:75]
	v_mfma_f32_16x16x32_bf16 v[76:79], v[156:159], v[176:179], v[76:79]
	v_mfma_f32_16x16x32_bf16 v[88:91], v[144:147], v[180:183], 0
	v_mfma_f32_16x16x32_bf16 v[92:95], v[152:155], v[180:183], 0
	v_mfma_f32_16x16x32_bf16 v[104:107], v[144:147], v[188:191], 0
	v_mfma_f32_16x16x32_bf16 v[120:123], v[144:147], v[196:199], 0
	v_mfma_f32_16x16x32_bf16 v[88:91], v[148:151], v[184:187], v[88:91]
	v_mfma_f32_16x16x32_bf16 v[92:95], v[156:159], v[184:187], v[92:95]
	v_mfma_f32_16x16x32_bf16 v[104:107], v[148:151], v[192:195], v[104:107]
	v_mfma_f32_16x16x32_bf16 v[108:111], v[152:155], v[188:191], 0
	v_mfma_f32_16x16x32_bf16 v[120:123], v[148:151], v[200:203], v[120:123]
	v_mfma_f32_16x16x32_bf16 v[124:127], v[152:155], v[196:199], 0
	v_mfma_f32_16x16x32_bf16 v[108:111], v[156:159], v[192:195], v[108:111]
	v_mfma_f32_16x16x32_bf16 v[124:127], v[156:159], v[200:203], v[124:127]
	s_barrier
	s_add_i32 s54, 0, 0x18000
	s_add_i32 s60, 0, 0x1c000
	v_add_u32_e32 v253, 0x18000, v174
	v_add_u32_e32 v252, 0x1c000, v174
	ds_read_b128 v[128:131], v253
	ds_read_b128 v[132:135], v253 offset:1024
	ds_read_b128 v[136:139], v253 offset:2048
	ds_read_b128 v[140:143], v253 offset:3072
	ds_read_b128 v[144:147], v252
	ds_read_b128 v[148:151], v252 offset:1024
	ds_read_b128 v[152:155], v252 offset:2048
	ds_read_b128 v[156:159], v252 offset:3072
	s_add_u32 s56, s22, 0x40100
	s_addc_u32 s57, s23, 0
	s_mov_b32 m0, s41
	ds_read_b128 v[168:171], v175 offset:32768
	ds_read_b128 v[176:179], v175 offset:33792
	ds_read_b128 v[180:183], v175 offset:34816
	ds_read_b128 v[184:187], v175 offset:35840
	ds_read_b128 v[188:191], v175 offset:36864
	ds_read_b128 v[192:195], v175 offset:37888
	ds_read_b128 v[196:199], v175 offset:38912
	ds_read_b128 v[200:203], v175 offset:39936
	global_load_lds_dwordx4 v160, s[56:57]
	s_mov_b32 m0, s42
	s_nop 0
	global_load_lds_dwordx4 v162, s[56:57]
	s_waitcnt vmcnt(8)
	s_waitcnt lgkmcnt(0)
	s_barrier
	v_mfma_f32_16x16x32_bf16 v[0:3], v[128:131], v[168:171], v[0:3]
	v_mfma_f32_16x16x32_bf16 v[4:7], v[136:139], v[168:171], v[4:7]
	v_mfma_f32_16x16x32_bf16 v[16:19], v[128:131], v[180:183], v[16:19]
	v_mfma_f32_16x16x32_bf16 v[20:23], v[136:139], v[180:183], v[20:23]
	v_mfma_f32_16x16x32_bf16 v[32:35], v[128:131], v[188:191], v[32:35]
	v_mfma_f32_16x16x32_bf16 v[36:39], v[136:139], v[188:191], v[36:39]
	v_mfma_f32_16x16x32_bf16 v[48:51], v[128:131], v[196:199], v[48:51]
	v_mfma_f32_16x16x32_bf16 v[52:55], v[136:139], v[196:199], v[52:55]
	v_mfma_f32_16x16x32_bf16 v[0:3], v[132:135], v[176:179], v[0:3]
	v_mfma_f32_16x16x32_bf16 v[4:7], v[140:143], v[176:179], v[4:7]
	v_mfma_f32_16x16x32_bf16 v[16:19], v[132:135], v[184:187], v[16:19]
	v_mfma_f32_16x16x32_bf16 v[20:23], v[140:143], v[184:187], v[20:23]
	v_mfma_f32_16x16x32_bf16 v[32:35], v[132:135], v[192:195], v[32:35]
	v_mfma_f32_16x16x32_bf16 v[36:39], v[140:143], v[192:195], v[36:39]
	v_mfma_f32_16x16x32_bf16 v[48:51], v[132:135], v[200:203], v[48:51]
	v_mfma_f32_16x16x32_bf16 v[52:55], v[140:143], v[200:203], v[52:55]
	v_mfma_f32_16x16x32_bf16 v[8:11], v[144:147], v[168:171], v[8:11]
	v_mfma_f32_16x16x32_bf16 v[24:27], v[144:147], v[180:183], v[24:27]
	v_mfma_f32_16x16x32_bf16 v[28:31], v[152:155], v[180:183], v[28:31]
	v_mfma_f32_16x16x32_bf16 v[44:47], v[152:155], v[188:191], v[44:47]
	v_mfma_f32_16x16x32_bf16 v[56:59], v[144:147], v[196:199], v[56:59]
	v_mfma_f32_16x16x32_bf16 v[60:63], v[152:155], v[196:199], v[60:63]
	v_mfma_f32_16x16x32_bf16 v[8:11], v[148:151], v[176:179], v[8:11]
	v_mfma_f32_16x16x32_bf16 v[12:15], v[152:155], v[168:171], v[12:15]
	v_mfma_f32_16x16x32_bf16 v[24:27], v[148:151], v[184:187], v[24:27]
	v_mfma_f32_16x16x32_bf16 v[28:31], v[156:159], v[184:187], v[28:31]
	v_mfma_f32_16x16x32_bf16 v[40:43], v[144:147], v[188:191], v[40:43]
	v_mfma_f32_16x16x32_bf16 v[44:47], v[156:159], v[192:195], v[44:47]
	v_mfma_f32_16x16x32_bf16 v[56:59], v[148:151], v[200:203], v[56:59]
	v_mfma_f32_16x16x32_bf16 v[60:63], v[156:159], v[200:203], v[60:63]
	v_mfma_f32_16x16x32_bf16 v[12:15], v[156:159], v[176:179], v[12:15]
	v_mfma_f32_16x16x32_bf16 v[40:43], v[148:151], v[192:195], v[40:43]
	s_barrier
	s_add_i32 s56, s54, s38
	s_mov_b64 s[62:63], 0x180
	s_add_i32 s54, s56, 0x2000
	s_add_u32 s68, s24, s62
	s_addc_u32 s69, s25, s63
	s_mov_b32 m0, s56
	s_add_u32 s70, s24, s62
	s_addc_u32 s71, s25, s63
	s_add_u32 s58, s24, 0x10180
	ds_read_b128 v[168:171], v175 offset:49152
	ds_read_b128 v[176:179], v175 offset:50176
	ds_read_b128 v[180:183], v175 offset:51200
	ds_read_b128 v[184:187], v175 offset:52224
	ds_read_b128 v[188:191], v175 offset:53248
	ds_read_b128 v[192:195], v175 offset:54272
	ds_read_b128 v[196:199], v175 offset:55296
	ds_read_b128 v[200:203], v175 offset:56320
	global_load_lds_dwordx4 v232, s[68:69]
	s_mov_b32 m0, s54
	s_addc_u32 s59, s25, 0
	s_add_i32 s24, s60, s38
	global_load_lds_dwordx4 v164, s[70:71]
	s_mov_b32 m0, s24
	s_add_i32 s25, s24, 0x2000
	global_load_lds_dwordx4 v232, s[58:59]
	s_mov_b32 m0, s25
	s_nop 0
	global_load_lds_dwordx4 v164, s[58:59]
	s_add_u32 s68, s22, s62
	s_addc_u32 s69, s23, s63
	s_mov_b32 m0, s47
	s_nop 0
	global_load_lds_dwordx4 v160, s[68:69]
	s_add_u32 s68, s22, s62
	s_addc_u32 s69, s23, s63
	s_mov_b32 m0, s48
	s_nop 0
	global_load_lds_dwordx4 v162, s[68:69]
	s_waitcnt vmcnt(8)
	s_waitcnt lgkmcnt(0)
	s_barrier
	v_mfma_f32_16x16x32_bf16 v[64:67], v[128:131], v[168:171], v[64:67]
	v_mfma_f32_16x16x32_bf16 v[68:71], v[136:139], v[168:171], v[68:71]
	v_mfma_f32_16x16x32_bf16 v[84:87], v[136:139], v[180:183], v[84:87]
	v_mfma_f32_16x16x32_bf16 v[96:99], v[128:131], v[188:191], v[96:99]
	v_mfma_f32_16x16x32_bf16 v[112:115], v[128:131], v[196:199], v[112:115]
	v_mfma_f32_16x16x32_bf16 v[116:119], v[136:139], v[196:199], v[116:119]
	v_mfma_f32_16x16x32_bf16 v[64:67], v[132:135], v[176:179], v[64:67]
	v_mfma_f32_16x16x32_bf16 v[68:71], v[140:143], v[176:179], v[68:71]
	v_mfma_f32_16x16x32_bf16 v[80:83], v[128:131], v[180:183], v[80:83]
	v_mfma_f32_16x16x32_bf16 v[84:87], v[140:143], v[184:187], v[84:87]
	v_mfma_f32_16x16x32_bf16 v[96:99], v[132:135], v[192:195], v[96:99]
	v_mfma_f32_16x16x32_bf16 v[100:103], v[136:139], v[188:191], v[100:103]
	v_mfma_f32_16x16x32_bf16 v[112:115], v[132:135], v[200:203], v[112:115]
	v_mfma_f32_16x16x32_bf16 v[116:119], v[140:143], v[200:203], v[116:119]
	v_mfma_f32_16x16x32_bf16 v[80:83], v[132:135], v[184:187], v[80:83]
	v_mfma_f32_16x16x32_bf16 v[100:103], v[140:143], v[192:195], v[100:103]
	v_mfma_f32_16x16x32_bf16 v[72:75], v[144:147], v[168:171], v[72:75]
	v_mfma_f32_16x16x32_bf16 v[76:79], v[152:155], v[168:171], v[76:79]
	v_mfma_f32_16x16x32_bf16 v[88:91], v[144:147], v[180:183], v[88:91]
	v_mfma_f32_16x16x32_bf16 v[92:95], v[152:155], v[180:183], v[92:95]
	v_mfma_f32_16x16x32_bf16 v[104:107], v[144:147], v[188:191], v[104:107]
	v_mfma_f32_16x16x32_bf16 v[108:111], v[152:155], v[188:191], v[108:111]
	v_mfma_f32_16x16x32_bf16 v[124:127], v[152:155], v[196:199], v[124:127]
	v_mfma_f32_16x16x32_bf16 v[72:75], v[148:151], v[176:179], v[72:75]
	v_mfma_f32_16x16x32_bf16 v[76:79], v[156:159], v[176:179], v[76:79]
	v_mfma_f32_16x16x32_bf16 v[92:95], v[156:159], v[184:187], v[92:95]
	v_mfma_f32_16x16x32_bf16 v[104:107], v[148:151], v[192:195], v[104:107]
	v_mfma_f32_16x16x32_bf16 v[108:111], v[156:159], v[192:195], v[108:111]
	v_mfma_f32_16x16x32_bf16 v[120:123], v[144:147], v[196:199], v[120:123]
	v_mfma_f32_16x16x32_bf16 v[124:127], v[156:159], v[200:203], v[124:127]
	v_mfma_f32_16x16x32_bf16 v[88:91], v[148:151], v[184:187], v[88:91]
	v_mfma_f32_16x16x32_bf16 v[120:123], v[148:151], v[200:203], v[120:123]
	s_barrier
	v_add_u32_e32 v253, 0x10000, v174
	ds_read_b128 v[128:131], v253
	ds_read_b128 v[132:135], v253 offset:1024
	ds_read_b128 v[136:139], v253 offset:2048
	ds_read_b128 v[140:143], v253 offset:3072
	v_add_u32_e32 v253, 0x14000, v174
	ds_read_b128 v[144:147], v253
	ds_read_b128 v[148:151], v253 offset:1024
	ds_read_b128 v[152:155], v253 offset:2048
	ds_read_b128 v[156:159], v253 offset:3072
	s_add_u32 s22, s22, 0x40180
	s_addc_u32 s23, s23, 0
	s_mov_b32 m0, s55
	ds_read_b128 v[168:171], v175
	ds_read_b128 v[176:179], v175 offset:1024
	ds_read_b128 v[180:183], v175 offset:2048
	ds_read_b128 v[184:187], v175 offset:3072
	ds_read_b128 v[188:191], v175 offset:4096
	ds_read_b128 v[192:195], v175 offset:5120
	ds_read_b128 v[196:199], v175 offset:6144
	ds_read_b128 v[200:203], v175 offset:7168
	global_load_lds_dwordx4 v160, s[22:23]
	s_mov_b32 m0, s13
	s_nop 0
	global_load_lds_dwordx4 v162, s[22:23]
	s_waitcnt vmcnt(8)
	s_waitcnt lgkmcnt(0)
	s_barrier
	v_mfma_f32_16x16x32_bf16 v[0:3], v[128:131], v[168:171], v[0:3]
	v_mfma_f32_16x16x32_bf16 v[4:7], v[136:139], v[168:171], v[4:7]
	v_mfma_f32_16x16x32_bf16 v[16:19], v[128:131], v[180:183], v[16:19]
	v_mfma_f32_16x16x32_bf16 v[20:23], v[136:139], v[180:183], v[20:23]
	v_mfma_f32_16x16x32_bf16 v[32:35], v[128:131], v[188:191], v[32:35]
	v_mfma_f32_16x16x32_bf16 v[36:39], v[136:139], v[188:191], v[36:39]
	v_mfma_f32_16x16x32_bf16 v[48:51], v[128:131], v[196:199], v[48:51]
	v_mfma_f32_16x16x32_bf16 v[0:3], v[132:135], v[176:179], v[0:3]
	v_mfma_f32_16x16x32_bf16 v[4:7], v[140:143], v[176:179], v[4:7]
	v_mfma_f32_16x16x32_bf16 v[16:19], v[132:135], v[184:187], v[16:19]
	v_mfma_f32_16x16x32_bf16 v[20:23], v[140:143], v[184:187], v[20:23]
	v_mfma_f32_16x16x32_bf16 v[32:35], v[132:135], v[192:195], v[32:35]
	v_mfma_f32_16x16x32_bf16 v[36:39], v[140:143], v[192:195], v[36:39]
	v_mfma_f32_16x16x32_bf16 v[48:51], v[132:135], v[200:203], v[48:51]
	v_mfma_f32_16x16x32_bf16 v[52:55], v[136:139], v[196:199], v[52:55]
	v_mfma_f32_16x16x32_bf16 v[52:55], v[140:143], v[200:203], v[52:55]
	v_mfma_f32_16x16x32_bf16 v[8:11], v[144:147], v[168:171], v[8:11]
	v_mfma_f32_16x16x32_bf16 v[24:27], v[144:147], v[180:183], v[24:27]
	v_mfma_f32_16x16x32_bf16 v[28:31], v[152:155], v[180:183], v[28:31]
	v_mfma_f32_16x16x32_bf16 v[44:47], v[152:155], v[188:191], v[44:47]
	v_mfma_f32_16x16x32_bf16 v[56:59], v[144:147], v[196:199], v[56:59]
	v_mfma_f32_16x16x32_bf16 v[60:63], v[152:155], v[196:199], v[60:63]
	v_mfma_f32_16x16x32_bf16 v[8:11], v[148:151], v[176:179], v[8:11]
	v_mfma_f32_16x16x32_bf16 v[12:15], v[152:155], v[168:171], v[12:15]
	v_mfma_f32_16x16x32_bf16 v[24:27], v[148:151], v[184:187], v[24:27]
	v_mfma_f32_16x16x32_bf16 v[28:31], v[156:159], v[184:187], v[28:31]
	v_mfma_f32_16x16x32_bf16 v[40:43], v[144:147], v[188:191], v[40:43]
	v_mfma_f32_16x16x32_bf16 v[44:47], v[156:159], v[192:195], v[44:47]
	v_mfma_f32_16x16x32_bf16 v[56:59], v[148:151], v[200:203], v[56:59]
	v_mfma_f32_16x16x32_bf16 v[60:63], v[156:159], v[200:203], v[60:63]
	v_mfma_f32_16x16x32_bf16 v[12:15], v[156:159], v[176:179], v[12:15]
	v_mfma_f32_16x16x32_bf16 v[40:43], v[148:151], v[192:195], v[40:43]
	s_barrier
	s_mov_b32 m0, s53
	s_add_u32 s22, s26, 0x10000
	ds_read_b128 v[168:171], v175 offset:16384
	ds_read_b128 v[176:179], v175 offset:17408
	ds_read_b128 v[180:183], v175 offset:18432
	ds_read_b128 v[184:187], v175 offset:19456
	ds_read_b128 v[188:191], v175 offset:20480
	ds_read_b128 v[192:195], v175 offset:21504
	ds_read_b128 v[196:199], v175 offset:22528
	ds_read_b128 v[200:203], v175 offset:23552
	global_load_lds_dwordx4 v232, s[26:27]
	s_mov_b32 m0, s15
	s_addc_u32 s23, s27, 0
	global_load_lds_dwordx4 v164, s[26:27]
	s_mov_b32 m0, s21
	s_nop 0
	global_load_lds_dwordx4 v232, s[22:23]
	s_mov_b32 m0, s52
	s_nop 0
	global_load_lds_dwordx4 v164, s[22:23]
	s_mov_b32 m0, s39
	s_nop 0
	global_load_lds_dwordx4 v160, s[28:29]
	s_mov_b32 m0, s40
	s_nop 0
	global_load_lds_dwordx4 v162, s[28:29]
	s_waitcnt vmcnt(8)
	s_waitcnt lgkmcnt(0)
	s_barrier
	v_mfma_f32_16x16x32_bf16 v[64:67], v[128:131], v[168:171], v[64:67]
	v_mfma_f32_16x16x32_bf16 v[64:67], v[132:135], v[176:179], v[64:67]
	v_mfma_f32_16x16x32_bf16 v[68:71], v[136:139], v[168:171], v[68:71]
	v_mfma_f32_16x16x32_bf16 v[68:71], v[140:143], v[176:179], v[68:71]
	v_mfma_f32_16x16x32_bf16 v[80:83], v[128:131], v[180:183], v[80:83]
	v_mfma_f32_16x16x32_bf16 v[80:83], v[132:135], v[184:187], v[80:83]
	v_mfma_f32_16x16x32_bf16 v[84:87], v[136:139], v[180:183], v[84:87]
	v_mfma_f32_16x16x32_bf16 v[84:87], v[140:143], v[184:187], v[84:87]
	v_mfma_f32_16x16x32_bf16 v[96:99], v[128:131], v[188:191], v[96:99]
	v_mfma_f32_16x16x32_bf16 v[112:115], v[128:131], v[196:199], v[112:115]
	v_mfma_f32_16x16x32_bf16 v[116:119], v[136:139], v[196:199], v[116:119]
	v_mfma_f32_16x16x32_bf16 v[96:99], v[132:135], v[192:195], v[96:99]
	v_mfma_f32_16x16x32_bf16 v[100:103], v[136:139], v[188:191], v[100:103]
	v_mfma_f32_16x16x32_bf16 v[112:115], v[132:135], v[200:203], v[112:115]
	v_mfma_f32_16x16x32_bf16 v[116:119], v[140:143], v[200:203], v[116:119]
	v_mfma_f32_16x16x32_bf16 v[100:103], v[140:143], v[192:195], v[100:103]
	v_mfma_f32_16x16x32_bf16 v[72:75], v[144:147], v[168:171], v[72:75]
	v_mfma_f32_16x16x32_bf16 v[72:75], v[148:151], v[176:179], v[72:75]
	v_mfma_f32_16x16x32_bf16 v[76:79], v[152:155], v[168:171], v[76:79]
	v_mfma_f32_16x16x32_bf16 v[76:79], v[156:159], v[176:179], v[76:79]
	v_mfma_f32_16x16x32_bf16 v[88:91], v[144:147], v[180:183], v[88:91]
	v_mfma_f32_16x16x32_bf16 v[88:91], v[148:151], v[184:187], v[88:91]
	v_mfma_f32_16x16x32_bf16 v[92:95], v[152:155], v[180:183], v[92:95]
	v_mfma_f32_16x16x32_bf16 v[92:95], v[156:159], v[184:187], v[92:95]
	v_mfma_f32_16x16x32_bf16 v[104:107], v[144:147], v[188:191], v[104:107]
	v_mfma_f32_16x16x32_bf16 v[104:107], v[148:151], v[192:195], v[104:107]
	v_mfma_f32_16x16x32_bf16 v[108:111], v[152:155], v[188:191], v[108:111]
	v_mfma_f32_16x16x32_bf16 v[108:111], v[156:159], v[192:195], v[108:111]
	v_mfma_f32_16x16x32_bf16 v[120:123], v[144:147], v[196:199], v[120:123]
	v_mfma_f32_16x16x32_bf16 v[120:123], v[148:151], v[200:203], v[120:123]
	v_mfma_f32_16x16x32_bf16 v[124:127], v[152:155], v[196:199], v[124:127]
	v_mfma_f32_16x16x32_bf16 v[124:127], v[156:159], v[200:203], v[124:127]
	s_barrier
	s_nop 4
	v_add_u32_e32 v253, 0x18000, v174
	ds_read_b128 v[128:131], v253
	ds_read_b128 v[132:135], v253 offset:1024
	ds_read_b128 v[136:139], v253 offset:2048
	ds_read_b128 v[140:143], v253 offset:3072
	v_add_u32_e32 v253, 0x1c000, v174
	ds_read_b128 v[144:147], v253
	ds_read_b128 v[148:151], v253 offset:1024
	ds_read_b128 v[152:155], v253 offset:2048
	ds_read_b128 v[156:159], v253 offset:3072
	s_add_u32 s22, s28, 0x40000
	s_addc_u32 s23, s29, 0
	s_mov_b32 m0, s41
	ds_read_b128 v[168:171], v175 offset:32768
	ds_read_b128 v[176:179], v175 offset:33792
	ds_read_b128 v[180:183], v175 offset:34816
	ds_read_b128 v[184:187], v175 offset:35840
	ds_read_b128 v[188:191], v175 offset:36864
	ds_read_b128 v[192:195], v175 offset:37888
	ds_read_b128 v[196:199], v175 offset:38912
	ds_read_b128 v[200:203], v175 offset:39936
	global_load_lds_dwordx4 v160, s[22:23]
	s_mov_b32 m0, s42
	s_nop 0
	global_load_lds_dwordx4 v162, s[22:23]
	s_waitcnt vmcnt(8)
	s_waitcnt lgkmcnt(0)
	s_barrier
	v_mfma_f32_16x16x32_bf16 v[0:3], v[128:131], v[168:171], v[0:3]
	v_mfma_f32_16x16x32_bf16 v[0:3], v[132:135], v[176:179], v[0:3]
	v_mfma_f32_16x16x32_bf16 v[4:7], v[136:139], v[168:171], v[4:7]
	v_mfma_f32_16x16x32_bf16 v[4:7], v[140:143], v[176:179], v[4:7]
	v_mfma_f32_16x16x32_bf16 v[16:19], v[128:131], v[180:183], v[16:19]
	v_mfma_f32_16x16x32_bf16 v[16:19], v[132:135], v[184:187], v[16:19]
	v_mfma_f32_16x16x32_bf16 v[20:23], v[136:139], v[180:183], v[20:23]
	v_mfma_f32_16x16x32_bf16 v[20:23], v[140:143], v[184:187], v[20:23]
	v_mfma_f32_16x16x32_bf16 v[32:35], v[128:131], v[188:191], v[32:35]
	v_mfma_f32_16x16x32_bf16 v[32:35], v[132:135], v[192:195], v[32:35]
	v_mfma_f32_16x16x32_bf16 v[36:39], v[136:139], v[188:191], v[36:39]
	v_mfma_f32_16x16x32_bf16 v[36:39], v[140:143], v[192:195], v[36:39]
	v_mfma_f32_16x16x32_bf16 v[48:51], v[128:131], v[196:199], v[48:51]
	v_mfma_f32_16x16x32_bf16 v[48:51], v[132:135], v[200:203], v[48:51]
	v_mfma_f32_16x16x32_bf16 v[52:55], v[136:139], v[196:199], v[52:55]
	v_mfma_f32_16x16x32_bf16 v[52:55], v[140:143], v[200:203], v[52:55]
	v_mfma_f32_16x16x32_bf16 v[12:15], v[152:155], v[168:171], v[12:15]
	v_mfma_f32_16x16x32_bf16 v[12:15], v[156:159], v[176:179], v[12:15]
	v_mfma_f32_16x16x32_bf16 v[24:27], v[144:147], v[180:183], v[24:27]
	v_mfma_f32_16x16x32_bf16 v[24:27], v[148:151], v[184:187], v[24:27]
	v_mfma_f32_16x16x32_bf16 v[28:31], v[152:155], v[180:183], v[28:31]
	v_mfma_f32_16x16x32_bf16 v[8:11], v[144:147], v[168:171], v[8:11]
	v_mfma_f32_16x16x32_bf16 v[28:31], v[156:159], v[184:187], v[28:31]
	v_mfma_f32_16x16x32_bf16 v[40:43], v[144:147], v[188:191], v[40:43]
	v_mfma_f32_16x16x32_bf16 v[8:11], v[148:151], v[176:179], v[8:11]
	v_mfma_f32_16x16x32_bf16 v[40:43], v[148:151], v[192:195], v[40:43]
	v_mfma_f32_16x16x32_bf16 v[44:47], v[152:155], v[188:191], v[44:47]
	v_mfma_f32_16x16x32_bf16 v[44:47], v[156:159], v[192:195], v[44:47]
	v_mfma_f32_16x16x32_bf16 v[56:59], v[144:147], v[196:199], v[56:59]
	v_mfma_f32_16x16x32_bf16 v[56:59], v[148:151], v[200:203], v[56:59]
	v_mfma_f32_16x16x32_bf16 v[60:63], v[152:155], v[196:199], v[60:63]
	v_mfma_f32_16x16x32_bf16 v[60:63], v[156:159], v[200:203], v[60:63]
	s_barrier
	s_mov_b32 m0, s56
	s_add_u32 s68, s26, s94
	s_addc_u32 s69, s27, s95
	s_add_u32 s70, s26, s94
	s_addc_u32 s71, s27, s95
	s_add_u32 s22, s26, 0x10080
	s_nop 1
	ds_read_b128 v[168:171], v175 offset:49152
	ds_read_b128 v[176:179], v175 offset:50176
	ds_read_b128 v[180:183], v175 offset:51200
	ds_read_b128 v[184:187], v175 offset:52224
	ds_read_b128 v[188:191], v175 offset:53248
	ds_read_b128 v[192:195], v175 offset:54272
	ds_read_b128 v[196:199], v175 offset:55296
	ds_read_b128 v[200:203], v175 offset:56320
	global_load_lds_dwordx4 v232, s[68:69]
	s_mov_b32 m0, s54
	s_addc_u32 s23, s27, 0
	global_load_lds_dwordx4 v164, s[70:71]
	s_mov_b32 m0, s24
	s_nop 0
	global_load_lds_dwordx4 v232, s[22:23]
	s_mov_b32 m0, s25
	s_nop 0
	global_load_lds_dwordx4 v164, s[22:23]
	s_add_u32 s68, s28, s94
	s_addc_u32 s69, s29, s95
	s_mov_b32 m0, s47
	s_nop 0
	global_load_lds_dwordx4 v160, s[68:69]
	s_add_u32 s68, s28, s94
	s_addc_u32 s69, s29, s95
	s_mov_b32 m0, s48
	s_nop 0
	global_load_lds_dwordx4 v162, s[68:69]
	s_waitcnt vmcnt(8)
	s_waitcnt lgkmcnt(0)
	s_barrier
	v_mfma_f32_16x16x32_bf16 v[64:67], v[128:131], v[168:171], v[64:67]
	v_mfma_f32_16x16x32_bf16 v[64:67], v[132:135], v[176:179], v[64:67]
	v_mfma_f32_16x16x32_bf16 v[68:71], v[136:139], v[168:171], v[68:71]
	v_mfma_f32_16x16x32_bf16 v[68:71], v[140:143], v[176:179], v[68:71]
	v_mfma_f32_16x16x32_bf16 v[80:83], v[128:131], v[180:183], v[80:83]
	v_mfma_f32_16x16x32_bf16 v[80:83], v[132:135], v[184:187], v[80:83]
	v_mfma_f32_16x16x32_bf16 v[84:87], v[136:139], v[180:183], v[84:87]
	v_mfma_f32_16x16x32_bf16 v[84:87], v[140:143], v[184:187], v[84:87]
	v_mfma_f32_16x16x32_bf16 v[96:99], v[128:131], v[188:191], v[96:99]
	v_mfma_f32_16x16x32_bf16 v[112:115], v[128:131], v[196:199], v[112:115]
	v_mfma_f32_16x16x32_bf16 v[96:99], v[132:135], v[192:195], v[96:99]
	v_mfma_f32_16x16x32_bf16 v[100:103], v[136:139], v[188:191], v[100:103]
	v_mfma_f32_16x16x32_bf16 v[112:115], v[132:135], v[200:203], v[112:115]
	v_mfma_f32_16x16x32_bf16 v[116:119], v[136:139], v[196:199], v[116:119]
	v_mfma_f32_16x16x32_bf16 v[100:103], v[140:143], v[192:195], v[100:103]
	v_mfma_f32_16x16x32_bf16 v[116:119], v[140:143], v[200:203], v[116:119]
	v_mfma_f32_16x16x32_bf16 v[72:75], v[144:147], v[168:171], v[72:75]
	v_mfma_f32_16x16x32_bf16 v[72:75], v[148:151], v[176:179], v[72:75]
	v_mfma_f32_16x16x32_bf16 v[76:79], v[152:155], v[168:171], v[76:79]
	v_mfma_f32_16x16x32_bf16 v[76:79], v[156:159], v[176:179], v[76:79]
	v_mfma_f32_16x16x32_bf16 v[88:91], v[144:147], v[180:183], v[88:91]
	v_mfma_f32_16x16x32_bf16 v[88:91], v[148:151], v[184:187], v[88:91]
	v_mfma_f32_16x16x32_bf16 v[92:95], v[152:155], v[180:183], v[92:95]
	v_mfma_f32_16x16x32_bf16 v[92:95], v[156:159], v[184:187], v[92:95]
	v_mfma_f32_16x16x32_bf16 v[104:107], v[144:147], v[188:191], v[104:107]
	v_mfma_f32_16x16x32_bf16 v[104:107], v[148:151], v[192:195], v[104:107]
	v_mfma_f32_16x16x32_bf16 v[108:111], v[152:155], v[188:191], v[108:111]
	v_mfma_f32_16x16x32_bf16 v[108:111], v[156:159], v[192:195], v[108:111]
	v_mfma_f32_16x16x32_bf16 v[120:123], v[144:147], v[196:199], v[120:123]
	v_mfma_f32_16x16x32_bf16 v[120:123], v[148:151], v[200:203], v[120:123]
	v_mfma_f32_16x16x32_bf16 v[124:127], v[152:155], v[196:199], v[124:127]
	v_mfma_f32_16x16x32_bf16 v[124:127], v[156:159], v[200:203], v[124:127]
	s_barrier
	s_andn2_b64 vcc, exec, s[10:11]
	s_cbranch_vccnz .LBB0_1020
	s_barrier

.LBB0_1163:
	s_ashr_i32 s23, s22, 31
	s_lshl_b64 s[24:25], s[22:23], 19
	s_add_u32 s24, s42, s24
	s_addc_u32 s25, s43, s25
	s_and_b64 s[26:27], s[4:5], exec
	s_cselect_b32 s23, s25, s35
	s_cselect_b32 s56, s24, s34
	s_ashr_i32 s21, s20, 31
	s_lshl_b64 s[26:27], s[20:21], 19
	s_add_u32 s26, s44, s26
	s_addc_u32 s27, s45, s27
	s_and_b64 s[36:37], s[4:5], exec
	s_cselect_b32 s21, s27, s31
	s_cselect_b32 s57, s26, s30
	s_add_u32 s58, s30, 0x100
	s_addc_u32 s59, s31, 0
	s_add_u32 s30, s34, 0x40080
	s_addc_u32 s31, s35, 0
	s_mov_b32 s60, -2
	s_waitcnt vmcnt(0)
	s_add_u32 s34, s30, 0xfffc0080
	s_addc_u32 s35, s31, -1
	s_add_i32 s61, 0, 0x10000
	s_cmp_eq_u32 s60, 12
	s_cselect_b32 s37, s23, s35
	s_cselect_b32 s36, s56, s34
	s_cselect_b32 s35, s21, s59
	s_cselect_b32 s34, s57, s58
	s_add_i32 s64, 0, 0x14000
	v_add_u32_e32 v140, s61, v174
	v_add_u32_e32 v166, s64, v174
	ds_read_b128 v[128:131], v140
	ds_read_b128 v[132:135], v140 offset:1024
	ds_read_b128 v[136:139], v140 offset:2048
	ds_read_b128 v[140:143], v140 offset:3072
	ds_read_b128 v[154:157], v166
	ds_read_b128 v[158:161], v166 offset:1024
	ds_read_b128 v[162:165], v166 offset:2048
	ds_read_b128 v[166:169], v166 offset:3072
	v_lshl_add_u64 v[204:205], s[30:31], 0, v[152:153]
	s_add_i32 m0, s29, 0xc000
	ds_read_b128 v[170:173], v175
	ds_read_b128 v[176:179], v175 offset:1024
	ds_read_b128 v[180:183], v175 offset:2048
	ds_read_b128 v[184:187], v175 offset:3072
	ds_read_b128 v[188:191], v175 offset:4096
	ds_read_b128 v[192:195], v175 offset:5120
	ds_read_b128 v[196:199], v175 offset:6144
	ds_read_b128 v[200:203], v175 offset:7168
	global_load_lds_dwordx4 v[204:205], off
	v_lshl_add_u64 v[204:205], s[30:31], 0, v[150:151]
	s_add_i32 m0, s29, 0xe000
	s_nop 0
	global_load_lds_dwordx4 v[204:205], off
	s_waitcnt vmcnt(8)
	s_waitcnt lgkmcnt(0)
	s_barrier
	v_mfma_f32_16x16x32_bf16 v[124:127], v[128:131], v[170:173], 0
	v_mfma_f32_16x16x32_bf16 v[120:123], v[136:139], v[170:173], 0
	v_mfma_f32_16x16x32_bf16 v[108:111], v[128:131], v[180:183], 0
	v_mfma_f32_16x16x32_bf16 v[104:107], v[136:139], v[180:183], 0
	v_mfma_f32_16x16x32_bf16 v[92:95], v[128:131], v[188:191], 0
	v_mfma_f32_16x16x32_bf16 v[88:91], v[136:139], v[188:191], 0
	v_mfma_f32_16x16x32_bf16 v[80:83], v[128:131], v[196:199], 0
	v_mfma_f32_16x16x32_bf16 v[72:75], v[136:139], v[196:199], 0
	v_mfma_f32_16x16x32_bf16 v[124:127], v[132:135], v[176:179], v[124:127]
	v_mfma_f32_16x16x32_bf16 v[120:123], v[140:143], v[176:179], v[120:123]
	v_mfma_f32_16x16x32_bf16 v[108:111], v[132:135], v[184:187], v[108:111]
	v_mfma_f32_16x16x32_bf16 v[104:107], v[140:143], v[184:187], v[104:107]
	v_mfma_f32_16x16x32_bf16 v[92:95], v[132:135], v[192:195], v[92:95]
	v_mfma_f32_16x16x32_bf16 v[88:91], v[140:143], v[192:195], v[88:91]
	v_mfma_f32_16x16x32_bf16 v[80:83], v[132:135], v[200:203], v[80:83]
	v_mfma_f32_16x16x32_bf16 v[72:75], v[140:143], v[200:203], v[72:75]
	v_mfma_f32_16x16x32_bf16 v[116:119], v[154:157], v[170:173], 0
	v_mfma_f32_16x16x32_bf16 v[112:115], v[162:165], v[170:173], 0
	v_mfma_f32_16x16x32_bf16 v[100:103], v[154:157], v[180:183], 0
	v_mfma_f32_16x16x32_bf16 v[96:99], v[162:165], v[180:183], 0
	v_mfma_f32_16x16x32_bf16 v[84:87], v[154:157], v[188:191], 0
	v_mfma_f32_16x16x32_bf16 v[76:79], v[162:165], v[188:191], 0
	v_mfma_f32_16x16x32_bf16 v[68:71], v[154:157], v[196:199], 0
	v_mfma_f32_16x16x32_bf16 v[64:67], v[162:165], v[196:199], 0
	v_mfma_f32_16x16x32_bf16 v[116:119], v[158:161], v[176:179], v[116:119]
	v_mfma_f32_16x16x32_bf16 v[112:115], v[166:169], v[176:179], v[112:115]
	v_mfma_f32_16x16x32_bf16 v[100:103], v[158:161], v[184:187], v[100:103]
	v_mfma_f32_16x16x32_bf16 v[96:99], v[166:169], v[184:187], v[96:99]
	v_mfma_f32_16x16x32_bf16 v[84:87], v[158:161], v[192:195], v[84:87]
	v_mfma_f32_16x16x32_bf16 v[76:79], v[166:169], v[192:195], v[76:79]
	v_mfma_f32_16x16x32_bf16 v[68:71], v[158:161], v[200:203], v[68:71]
	v_mfma_f32_16x16x32_bf16 v[64:67], v[166:169], v[200:203], v[64:67]
	s_barrier
	s_add_i32 s61, s61, s41
	v_lshl_add_u64 v[204:205], s[34:35], 0, v[232:233]
	s_mov_b32 m0, s61
	ds_read_b128 v[170:173], v175 offset:16384
	ds_read_b128 v[176:179], v175 offset:17408
	ds_read_b128 v[180:183], v175 offset:18432
	ds_read_b128 v[184:187], v175 offset:19456
	ds_read_b128 v[188:191], v175 offset:20480
	ds_read_b128 v[192:195], v175 offset:21504
	ds_read_b128 v[196:199], v175 offset:22528
	ds_read_b128 v[200:203], v175 offset:23552
	global_load_lds_dwordx4 v[204:205], off
	s_add_i32 m0, s61, 0x2000
	s_add_u32 s62, s34, 0x40000
	v_lshl_add_u64 v[206:207], s[34:35], 0, v[148:149]
	s_addc_u32 s63, s35, 0
	s_add_i32 s61, s64, s41
	global_load_lds_dwordx4 v[206:207], off
	v_lshl_add_u64 v[208:209], s[62:63], 0, v[232:233]
	s_mov_b32 m0, s61
	v_lshl_add_u64 v[210:211], s[36:37], 0, v[146:147]
	global_load_lds_dwordx4 v[208:209], off
	v_lshl_add_u64 v[208:209], s[62:63], 0, v[148:149]
	s_add_i32 m0, s61, 0x2000
	s_nop 0
	global_load_lds_dwordx4 v[208:209], off
	v_lshl_add_u64 v[208:209], s[36:37], 0, v[144:145]
	s_waitcnt vmcnt(6)
	s_waitcnt lgkmcnt(0)
	s_barrier
	v_mfma_f32_16x16x32_bf16 v[60:63], v[128:131], v[170:173], 0
	v_mfma_f32_16x16x32_bf16 v[56:59], v[136:139], v[170:173], 0
	v_mfma_f32_16x16x32_bf16 v[48:51], v[128:131], v[180:183], 0
	v_mfma_f32_16x16x32_bf16 v[40:43], v[136:139], v[180:183], 0
	v_mfma_f32_16x16x32_bf16 v[28:31], v[128:131], v[188:191], 0
	v_mfma_f32_16x16x32_bf16 v[24:27], v[136:139], v[188:191], 0
	v_mfma_f32_16x16x32_bf16 v[16:19], v[128:131], v[196:199], 0
	v_mfma_f32_16x16x32_bf16 v[8:11], v[136:139], v[196:199], 0
	v_mfma_f32_16x16x32_bf16 v[60:63], v[132:135], v[176:179], v[60:63]
	v_mfma_f32_16x16x32_bf16 v[56:59], v[140:143], v[176:179], v[56:59]
	v_mfma_f32_16x16x32_bf16 v[48:51], v[132:135], v[184:187], v[48:51]
	v_mfma_f32_16x16x32_bf16 v[40:43], v[140:143], v[184:187], v[40:43]
	v_mfma_f32_16x16x32_bf16 v[28:31], v[132:135], v[192:195], v[28:31]
	v_mfma_f32_16x16x32_bf16 v[24:27], v[140:143], v[192:195], v[24:27]
	v_mfma_f32_16x16x32_bf16 v[16:19], v[132:135], v[200:203], v[16:19]
	v_mfma_f32_16x16x32_bf16 v[8:11], v[140:143], v[200:203], v[8:11]
	v_mfma_f32_16x16x32_bf16 v[52:55], v[154:157], v[170:173], 0
	v_mfma_f32_16x16x32_bf16 v[44:47], v[162:165], v[170:173], 0
	v_mfma_f32_16x16x32_bf16 v[36:39], v[154:157], v[180:183], 0
	v_mfma_f32_16x16x32_bf16 v[32:35], v[162:165], v[180:183], 0
	v_mfma_f32_16x16x32_bf16 v[20:23], v[154:157], v[188:191], 0
	v_mfma_f32_16x16x32_bf16 v[12:15], v[162:165], v[188:191], 0
	v_mfma_f32_16x16x32_bf16 v[4:7], v[154:157], v[196:199], 0
	v_mfma_f32_16x16x32_bf16 v[0:3], v[162:165], v[196:199], 0
	v_mfma_f32_16x16x32_bf16 v[52:55], v[158:161], v[176:179], v[52:55]
	v_mfma_f32_16x16x32_bf16 v[44:47], v[166:169], v[176:179], v[44:47]
	v_mfma_f32_16x16x32_bf16 v[36:39], v[158:161], v[184:187], v[36:39]
	v_mfma_f32_16x16x32_bf16 v[32:35], v[166:169], v[184:187], v[32:35]
	v_mfma_f32_16x16x32_bf16 v[20:23], v[158:161], v[192:195], v[20:23]
	v_mfma_f32_16x16x32_bf16 v[12:15], v[166:169], v[192:195], v[12:15]
	v_mfma_f32_16x16x32_bf16 v[4:7], v[158:161], v[200:203], v[4:7]
	v_mfma_f32_16x16x32_bf16 v[0:3], v[166:169], v[200:203], v[0:3]
	s_barrier
	s_branch .Lzmid_3
.LBB0_1164:
	s_add_u32 s34, s30, 0xfffc0080
	s_addc_u32 s35, s31, -1
	s_add_i32 s61, 0, 0x10000
	s_cmp_eq_u32 s60, 12
	s_cselect_b32 s37, s23, s35
	s_cselect_b32 s36, s56, s34
	s_cselect_b32 s35, s21, s59
	s_cselect_b32 s34, s57, s58
	s_add_i32 s64, 0, 0x14000
	v_add_u32_e32 v140, s61, v174
	v_add_u32_e32 v166, s64, v174
	ds_read_b128 v[128:131], v140
	ds_read_b128 v[132:135], v140 offset:1024
	ds_read_b128 v[136:139], v140 offset:2048
	ds_read_b128 v[140:143], v140 offset:3072
	ds_read_b128 v[154:157], v166
	ds_read_b128 v[158:161], v166 offset:1024
	ds_read_b128 v[162:165], v166 offset:2048
	ds_read_b128 v[166:169], v166 offset:3072
	v_lshl_add_u64 v[204:205], s[30:31], 0, v[152:153]
	s_add_i32 m0, s29, 0xc000
	ds_read_b128 v[170:173], v175
	ds_read_b128 v[176:179], v175 offset:1024
	ds_read_b128 v[180:183], v175 offset:2048
	ds_read_b128 v[184:187], v175 offset:3072
	ds_read_b128 v[188:191], v175 offset:4096
	ds_read_b128 v[192:195], v175 offset:5120
	ds_read_b128 v[196:199], v175 offset:6144
	ds_read_b128 v[200:203], v175 offset:7168
	global_load_lds_dwordx4 v[204:205], off
	v_lshl_add_u64 v[204:205], s[30:31], 0, v[150:151]
	s_add_i32 m0, s29, 0xe000
	s_nop 0
	global_load_lds_dwordx4 v[204:205], off
	s_waitcnt vmcnt(8)
	s_waitcnt lgkmcnt(0)
	s_barrier
	v_mfma_f32_16x16x32_bf16 v[124:127], v[128:131], v[170:173], v[124:127]
	v_mfma_f32_16x16x32_bf16 v[120:123], v[136:139], v[170:173], v[120:123]
	v_mfma_f32_16x16x32_bf16 v[108:111], v[128:131], v[180:183], v[108:111]
	v_mfma_f32_16x16x32_bf16 v[104:107], v[136:139], v[180:183], v[104:107]
	v_mfma_f32_16x16x32_bf16 v[92:95], v[128:131], v[188:191], v[92:95]
	v_mfma_f32_16x16x32_bf16 v[88:91], v[136:139], v[188:191], v[88:91]
	v_mfma_f32_16x16x32_bf16 v[80:83], v[128:131], v[196:199], v[80:83]
	v_mfma_f32_16x16x32_bf16 v[72:75], v[136:139], v[196:199], v[72:75]
	v_mfma_f32_16x16x32_bf16 v[124:127], v[132:135], v[176:179], v[124:127]
	v_mfma_f32_16x16x32_bf16 v[120:123], v[140:143], v[176:179], v[120:123]
	v_mfma_f32_16x16x32_bf16 v[108:111], v[132:135], v[184:187], v[108:111]
	v_mfma_f32_16x16x32_bf16 v[104:107], v[140:143], v[184:187], v[104:107]
	v_mfma_f32_16x16x32_bf16 v[92:95], v[132:135], v[192:195], v[92:95]
	v_mfma_f32_16x16x32_bf16 v[88:91], v[140:143], v[192:195], v[88:91]
	v_mfma_f32_16x16x32_bf16 v[80:83], v[132:135], v[200:203], v[80:83]
	v_mfma_f32_16x16x32_bf16 v[72:75], v[140:143], v[200:203], v[72:75]
	v_mfma_f32_16x16x32_bf16 v[116:119], v[154:157], v[170:173], v[116:119]
	v_mfma_f32_16x16x32_bf16 v[112:115], v[162:165], v[170:173], v[112:115]
	v_mfma_f32_16x16x32_bf16 v[100:103], v[154:157], v[180:183], v[100:103]
	v_mfma_f32_16x16x32_bf16 v[96:99], v[162:165], v[180:183], v[96:99]
	v_mfma_f32_16x16x32_bf16 v[84:87], v[154:157], v[188:191], v[84:87]
	v_mfma_f32_16x16x32_bf16 v[76:79], v[162:165], v[188:191], v[76:79]
	v_mfma_f32_16x16x32_bf16 v[68:71], v[154:157], v[196:199], v[68:71]
	v_mfma_f32_16x16x32_bf16 v[64:67], v[162:165], v[196:199], v[64:67]
	v_mfma_f32_16x16x32_bf16 v[116:119], v[158:161], v[176:179], v[116:119]
	v_mfma_f32_16x16x32_bf16 v[112:115], v[166:169], v[176:179], v[112:115]
	v_mfma_f32_16x16x32_bf16 v[100:103], v[158:161], v[184:187], v[100:103]
	v_mfma_f32_16x16x32_bf16 v[96:99], v[166:169], v[184:187], v[96:99]
	v_mfma_f32_16x16x32_bf16 v[84:87], v[158:161], v[192:195], v[84:87]
	v_mfma_f32_16x16x32_bf16 v[76:79], v[166:169], v[192:195], v[76:79]
	v_mfma_f32_16x16x32_bf16 v[68:71], v[158:161], v[200:203], v[68:71]
	v_mfma_f32_16x16x32_bf16 v[64:67], v[166:169], v[200:203], v[64:67]
	s_barrier
	s_add_i32 s61, s61, s41
	v_lshl_add_u64 v[204:205], s[34:35], 0, v[232:233]
	s_mov_b32 m0, s61
	ds_read_b128 v[170:173], v175 offset:16384
	ds_read_b128 v[176:179], v175 offset:17408
	ds_read_b128 v[180:183], v175 offset:18432
	ds_read_b128 v[184:187], v175 offset:19456
	ds_read_b128 v[188:191], v175 offset:20480
	ds_read_b128 v[192:195], v175 offset:21504
	ds_read_b128 v[196:199], v175 offset:22528
	ds_read_b128 v[200:203], v175 offset:23552
	global_load_lds_dwordx4 v[204:205], off
	s_add_i32 m0, s61, 0x2000
	s_add_u32 s62, s34, 0x40000
	v_lshl_add_u64 v[206:207], s[34:35], 0, v[148:149]
	s_addc_u32 s63, s35, 0
	s_add_i32 s61, s64, s41
	global_load_lds_dwordx4 v[206:207], off
	v_lshl_add_u64 v[208:209], s[62:63], 0, v[232:233]
	s_mov_b32 m0, s61
	v_lshl_add_u64 v[210:211], s[36:37], 0, v[146:147]
	global_load_lds_dwordx4 v[208:209], off
	v_lshl_add_u64 v[208:209], s[62:63], 0, v[148:149]
	s_add_i32 m0, s61, 0x2000
	s_nop 0
	global_load_lds_dwordx4 v[208:209], off
	v_lshl_add_u64 v[208:209], s[36:37], 0, v[144:145]
	s_waitcnt vmcnt(6)
	s_waitcnt lgkmcnt(0)
	s_barrier
	v_mfma_f32_16x16x32_bf16 v[60:63], v[128:131], v[170:173], v[60:63]
	v_mfma_f32_16x16x32_bf16 v[56:59], v[136:139], v[170:173], v[56:59]
	v_mfma_f32_16x16x32_bf16 v[48:51], v[128:131], v[180:183], v[48:51]
	v_mfma_f32_16x16x32_bf16 v[40:43], v[136:139], v[180:183], v[40:43]
	v_mfma_f32_16x16x32_bf16 v[28:31], v[128:131], v[188:191], v[28:31]
	v_mfma_f32_16x16x32_bf16 v[24:27], v[136:139], v[188:191], v[24:27]
	v_mfma_f32_16x16x32_bf16 v[16:19], v[128:131], v[196:199], v[16:19]
	v_mfma_f32_16x16x32_bf16 v[8:11], v[136:139], v[196:199], v[8:11]
	v_mfma_f32_16x16x32_bf16 v[60:63], v[132:135], v[176:179], v[60:63]
	v_mfma_f32_16x16x32_bf16 v[56:59], v[140:143], v[176:179], v[56:59]
	v_mfma_f32_16x16x32_bf16 v[48:51], v[132:135], v[184:187], v[48:51]
	v_mfma_f32_16x16x32_bf16 v[40:43], v[140:143], v[184:187], v[40:43]
	v_mfma_f32_16x16x32_bf16 v[28:31], v[132:135], v[192:195], v[28:31]
	v_mfma_f32_16x16x32_bf16 v[24:27], v[140:143], v[192:195], v[24:27]
	v_mfma_f32_16x16x32_bf16 v[16:19], v[132:135], v[200:203], v[16:19]
	v_mfma_f32_16x16x32_bf16 v[8:11], v[140:143], v[200:203], v[8:11]
	v_mfma_f32_16x16x32_bf16 v[52:55], v[154:157], v[170:173], v[52:55]
	v_mfma_f32_16x16x32_bf16 v[44:47], v[162:165], v[170:173], v[44:47]
	v_mfma_f32_16x16x32_bf16 v[36:39], v[154:157], v[180:183], v[36:39]
	v_mfma_f32_16x16x32_bf16 v[32:35], v[162:165], v[180:183], v[32:35]
	v_mfma_f32_16x16x32_bf16 v[20:23], v[154:157], v[188:191], v[20:23]
	v_mfma_f32_16x16x32_bf16 v[12:15], v[162:165], v[188:191], v[12:15]
	v_mfma_f32_16x16x32_bf16 v[4:7], v[154:157], v[196:199], v[4:7]
	v_mfma_f32_16x16x32_bf16 v[0:3], v[162:165], v[196:199], v[0:3]
	v_mfma_f32_16x16x32_bf16 v[52:55], v[158:161], v[176:179], v[52:55]
	v_mfma_f32_16x16x32_bf16 v[44:47], v[166:169], v[176:179], v[44:47]
	v_mfma_f32_16x16x32_bf16 v[36:39], v[158:161], v[184:187], v[36:39]
	v_mfma_f32_16x16x32_bf16 v[32:35], v[166:169], v[184:187], v[32:35]
	v_mfma_f32_16x16x32_bf16 v[20:23], v[158:161], v[192:195], v[20:23]
	v_mfma_f32_16x16x32_bf16 v[12:15], v[166:169], v[192:195], v[12:15]
	v_mfma_f32_16x16x32_bf16 v[4:7], v[158:161], v[200:203], v[4:7]
	v_mfma_f32_16x16x32_bf16 v[0:3], v[166:169], v[200:203], v[0:3]
	s_barrier
.Lzmid_3:
	s_add_i32 s61, 0, 0x18000
	s_add_i32 s62, 0, 0x1c000
	v_add_u32_e32 v140, s61, v174
	v_add_u32_e32 v166, s62, v174
	ds_read_b128 v[128:131], v140
	ds_read_b128 v[132:135], v140 offset:1024
	ds_read_b128 v[136:139], v140 offset:2048
	ds_read_b128 v[140:143], v140 offset:3072
	ds_read_b128 v[154:157], v166
	ds_read_b128 v[158:161], v166 offset:1024
	ds_read_b128 v[162:165], v166 offset:2048
	ds_read_b128 v[166:169], v166 offset:3072
	s_add_u32 s36, s36, 0x40000
	s_addc_u32 s37, s37, 0
	s_mov_b32 m0, s29
	s_nop 0
	global_load_lds_dwordx4 v[208:209], off
	s_mov_b32 m0, s46
	s_nop 0
	global_load_lds_dwordx4 v[210:211], off
	s_mov_b32 m0, s47
	v_lshl_add_u64 v[212:213], s[36:37], 0, v[144:145]
	ds_read_b128 v[170:173], v175 offset:32768
	ds_read_b128 v[176:179], v175 offset:33792
	ds_read_b128 v[180:183], v175 offset:34816
	ds_read_b128 v[184:187], v175 offset:35840
	ds_read_b128 v[188:191], v175 offset:36864
	ds_read_b128 v[192:195], v175 offset:37888
	ds_read_b128 v[196:199], v175 offset:38912
	ds_read_b128 v[200:203], v175 offset:39936
	global_load_lds_dwordx4 v[212:213], off
	v_lshl_add_u64 v[212:213], s[36:37], 0, v[146:147]
	s_mov_b32 m0, s48
	s_nop 0
	global_load_lds_dwordx4 v[212:213], off
	s_waitcnt vmcnt(8)
	s_waitcnt lgkmcnt(0)
	s_barrier
	v_mfma_f32_16x16x32_bf16 v[124:127], v[128:131], v[170:173], v[124:127]
	v_mfma_f32_16x16x32_bf16 v[120:123], v[136:139], v[170:173], v[120:123]
	v_mfma_f32_16x16x32_bf16 v[108:111], v[128:131], v[180:183], v[108:111]
	v_mfma_f32_16x16x32_bf16 v[104:107], v[136:139], v[180:183], v[104:107]
	v_mfma_f32_16x16x32_bf16 v[92:95], v[128:131], v[188:191], v[92:95]
	v_mfma_f32_16x16x32_bf16 v[88:91], v[136:139], v[188:191], v[88:91]
	v_mfma_f32_16x16x32_bf16 v[80:83], v[128:131], v[196:199], v[80:83]
	v_mfma_f32_16x16x32_bf16 v[72:75], v[136:139], v[196:199], v[72:75]
	v_mfma_f32_16x16x32_bf16 v[124:127], v[132:135], v[176:179], v[124:127]
	v_mfma_f32_16x16x32_bf16 v[120:123], v[140:143], v[176:179], v[120:123]
	v_mfma_f32_16x16x32_bf16 v[108:111], v[132:135], v[184:187], v[108:111]
	v_mfma_f32_16x16x32_bf16 v[104:107], v[140:143], v[184:187], v[104:107]
	v_mfma_f32_16x16x32_bf16 v[92:95], v[132:135], v[192:195], v[92:95]
	v_mfma_f32_16x16x32_bf16 v[88:91], v[140:143], v[192:195], v[88:91]
	v_mfma_f32_16x16x32_bf16 v[80:83], v[132:135], v[200:203], v[80:83]
	v_mfma_f32_16x16x32_bf16 v[72:75], v[140:143], v[200:203], v[72:75]
	v_mfma_f32_16x16x32_bf16 v[116:119], v[154:157], v[170:173], v[116:119]
	v_mfma_f32_16x16x32_bf16 v[112:115], v[162:165], v[170:173], v[112:115]
	v_mfma_f32_16x16x32_bf16 v[100:103], v[154:157], v[180:183], v[100:103]
	v_mfma_f32_16x16x32_bf16 v[96:99], v[162:165], v[180:183], v[96:99]
	v_mfma_f32_16x16x32_bf16 v[84:87], v[154:157], v[188:191], v[84:87]
	v_mfma_f32_16x16x32_bf16 v[76:79], v[162:165], v[188:191], v[76:79]
	v_mfma_f32_16x16x32_bf16 v[68:71], v[154:157], v[196:199], v[68:71]
	v_mfma_f32_16x16x32_bf16 v[64:67], v[162:165], v[196:199], v[64:67]
	v_mfma_f32_16x16x32_bf16 v[116:119], v[158:161], v[176:179], v[116:119]
	v_mfma_f32_16x16x32_bf16 v[112:115], v[166:169], v[176:179], v[112:115]
	v_mfma_f32_16x16x32_bf16 v[100:103], v[158:161], v[184:187], v[100:103]
	v_mfma_f32_16x16x32_bf16 v[96:99], v[166:169], v[184:187], v[96:99]
	v_mfma_f32_16x16x32_bf16 v[84:87], v[158:161], v[192:195], v[84:87]
	v_mfma_f32_16x16x32_bf16 v[76:79], v[166:169], v[192:195], v[76:79]
	v_mfma_f32_16x16x32_bf16 v[68:71], v[158:161], v[200:203], v[68:71]
	v_mfma_f32_16x16x32_bf16 v[64:67], v[166:169], v[200:203], v[64:67]
	s_barrier
	s_add_i32 s36, s61, s41
	v_lshl_add_u64 v[204:205], v[204:205], 0, s[94:95]
	s_mov_b32 m0, s36
	ds_read_b128 v[170:173], v175 offset:49152
	ds_read_b128 v[176:179], v175 offset:50176
	ds_read_b128 v[180:183], v175 offset:51200
	ds_read_b128 v[184:187], v175 offset:52224
	ds_read_b128 v[188:191], v175 offset:53248
	ds_read_b128 v[192:195], v175 offset:54272
	ds_read_b128 v[196:199], v175 offset:55296
	ds_read_b128 v[200:203], v175 offset:56320
	global_load_lds_dwordx4 v[204:205], off
	s_add_i32 m0, s36, 0x2000
	s_add_u32 s34, s34, 0x40080
	v_lshl_add_u64 v[204:205], v[206:207], 0, s[94:95]
	s_addc_u32 s35, s35, 0
	s_add_i32 s36, s62, s41
	global_load_lds_dwordx4 v[204:205], off
	v_lshl_add_u64 v[204:205], s[34:35], 0, v[232:233]
	s_mov_b32 m0, s36
	s_nop 0
	global_load_lds_dwordx4 v[204:205], off
	v_lshl_add_u64 v[204:205], s[34:35], 0, v[148:149]
	s_add_i32 m0, s36, 0x2000
	s_nop 0
	global_load_lds_dwordx4 v[204:205], off
	v_lshl_add_u64 v[204:205], v[208:209], 0, s[94:95]
	s_mov_b32 m0, s51
	s_nop 0
	global_load_lds_dwordx4 v[204:205], off
	v_lshl_add_u64 v[204:205], v[210:211], 0, s[94:95]
	s_mov_b32 m0, s52
	s_nop 0
	global_load_lds_dwordx4 v[204:205], off
	s_waitcnt vmcnt(8)
	s_waitcnt lgkmcnt(0)
	s_barrier
	v_mfma_f32_16x16x32_bf16 v[60:63], v[128:131], v[170:173], v[60:63]
	v_mfma_f32_16x16x32_bf16 v[56:59], v[136:139], v[170:173], v[56:59]
	v_mfma_f32_16x16x32_bf16 v[48:51], v[128:131], v[180:183], v[48:51]
	v_mfma_f32_16x16x32_bf16 v[40:43], v[136:139], v[180:183], v[40:43]
	v_mfma_f32_16x16x32_bf16 v[28:31], v[128:131], v[188:191], v[28:31]
	v_mfma_f32_16x16x32_bf16 v[24:27], v[136:139], v[188:191], v[24:27]
	v_mfma_f32_16x16x32_bf16 v[16:19], v[128:131], v[196:199], v[16:19]
	v_mfma_f32_16x16x32_bf16 v[8:11], v[136:139], v[196:199], v[8:11]
	v_mfma_f32_16x16x32_bf16 v[60:63], v[132:135], v[176:179], v[60:63]
	v_mfma_f32_16x16x32_bf16 v[56:59], v[140:143], v[176:179], v[56:59]
	v_mfma_f32_16x16x32_bf16 v[48:51], v[132:135], v[184:187], v[48:51]
	v_mfma_f32_16x16x32_bf16 v[40:43], v[140:143], v[184:187], v[40:43]
	v_mfma_f32_16x16x32_bf16 v[28:31], v[132:135], v[192:195], v[28:31]
	v_mfma_f32_16x16x32_bf16 v[24:27], v[140:143], v[192:195], v[24:27]
	v_mfma_f32_16x16x32_bf16 v[16:19], v[132:135], v[200:203], v[16:19]
	v_mfma_f32_16x16x32_bf16 v[8:11], v[140:143], v[200:203], v[8:11]
	v_mfma_f32_16x16x32_bf16 v[52:55], v[154:157], v[170:173], v[52:55]
	v_mfma_f32_16x16x32_bf16 v[44:47], v[162:165], v[170:173], v[44:47]
	v_mfma_f32_16x16x32_bf16 v[36:39], v[154:157], v[180:183], v[36:39]
	v_mfma_f32_16x16x32_bf16 v[32:35], v[162:165], v[180:183], v[32:35]
	v_mfma_f32_16x16x32_bf16 v[20:23], v[154:157], v[188:191], v[20:23]
	v_mfma_f32_16x16x32_bf16 v[12:15], v[162:165], v[188:191], v[12:15]
	v_mfma_f32_16x16x32_bf16 v[4:7], v[154:157], v[196:199], v[4:7]
	v_mfma_f32_16x16x32_bf16 v[0:3], v[162:165], v[196:199], v[0:3]
	v_mfma_f32_16x16x32_bf16 v[52:55], v[158:161], v[176:179], v[52:55]
	v_mfma_f32_16x16x32_bf16 v[44:47], v[166:169], v[176:179], v[44:47]
	v_mfma_f32_16x16x32_bf16 v[36:39], v[158:161], v[184:187], v[36:39]
	v_mfma_f32_16x16x32_bf16 v[32:35], v[166:169], v[184:187], v[32:35]
	v_mfma_f32_16x16x32_bf16 v[20:23], v[158:161], v[192:195], v[20:23]
	v_mfma_f32_16x16x32_bf16 v[12:15], v[166:169], v[192:195], v[12:15]
	v_mfma_f32_16x16x32_bf16 v[4:7], v[158:161], v[200:203], v[4:7]
	v_mfma_f32_16x16x32_bf16 v[0:3], v[166:169], v[200:203], v[0:3]
	s_barrier
	s_add_i32 s60, s60, 2
	s_add_u32 s58, s58, 0x100
	s_addc_u32 s59, s59, 0
	s_add_u32 s30, s30, 0x100
	s_addc_u32 s31, s31, 0
	s_cmp_gt_u32 s60, 13
	s_cbranch_scc0 .LBB0_1164
	s_and_b64 vcc, exec, s[18:19]
	s_cbranch_vccz .LBB0_1167
	s_barrier

.LBB0_1306:
	s_ashr_i32 s17, s16, 31
	s_lshl_b64 s[18:19], s[16:17], 19
	s_add_u32 s18, s34, s18
	s_addc_u32 s19, s35, s19
	s_and_b64 s[20:21], s[4:5], exec
	s_cselect_b32 s7, s19, s27
	s_cselect_b32 s17, s18, s26
	s_ashr_i32 s15, s14, 31
	s_lshl_b64 s[20:21], s[14:15], 19
	s_add_u32 s20, s36, s20
	s_addc_u32 s21, s37, s21
	s_and_b64 s[28:29], s[4:5], exec
	s_cselect_b32 s15, s21, s25
	s_cselect_b32 s23, s20, s24
	s_add_u32 s50, s24, 0x100
	s_addc_u32 s51, s25, 0
	s_add_u32 s24, s26, 0x40080
	s_addc_u32 s25, s27, 0
	s_mov_b32 s52, -2
	s_add_u32 s26, s24, 0xfffc0080
	s_addc_u32 s27, s25, -1
	s_add_i32 s53, 0, 0x10000
	s_cmp_eq_u32 s52, 12
	s_cselect_b32 s29, s7, s27
	s_cselect_b32 s28, s17, s26
	v_add_u32_e32 v142, s53, v144
	s_cselect_b32 s27, s15, s51
	s_cselect_b32 s26, s23, s50
	s_add_i32 s56, 0, 0x14000
	ds_read_b128 v[138:141], v142
	ds_read_b128 v[146:149], v142 offset:1024
	ds_read_b128 v[150:153], v142 offset:2048
	ds_read_b128 v[154:157], v142 offset:3072
	v_add_u32_e32 v142, s56, v144
	ds_read_b128 v[158:161], v142
	ds_read_b128 v[162:165], v142 offset:1024
	ds_read_b128 v[166:169], v142 offset:2048
	ds_read_b128 v[170:173], v142 offset:3072
	v_lshl_add_u64 v[142:143], s[24:25], 0, v[136:137]
	s_add_i32 m0, s39, 0xc000
	ds_read_b128 v[174:177], v145
	ds_read_b128 v[178:181], v145 offset:1024
	ds_read_b128 v[182:185], v145 offset:2048
	ds_read_b128 v[186:189], v145 offset:3072
	ds_read_b128 v[190:193], v145 offset:4096
	ds_read_b128 v[194:197], v145 offset:5120
	ds_read_b128 v[198:201], v145 offset:6144
	ds_read_b128 v[202:205], v145 offset:7168
	global_load_lds_dwordx4 v[142:143], off
	v_lshl_add_u64 v[142:143], s[24:25], 0, v[134:135]
	s_add_i32 m0, s39, 0xe000
	s_nop 0
	global_load_lds_dwordx4 v[142:143], off
	s_waitcnt vmcnt(8)
	s_waitcnt lgkmcnt(0)
	s_barrier
	v_mfma_f32_16x16x32_bf16 v[124:127], v[138:141], v[174:177], 0
	v_mfma_f32_16x16x32_bf16 v[120:123], v[150:153], v[174:177], 0
	v_mfma_f32_16x16x32_bf16 v[108:111], v[138:141], v[182:185], 0
	v_mfma_f32_16x16x32_bf16 v[104:107], v[150:153], v[182:185], 0
	v_mfma_f32_16x16x32_bf16 v[92:95], v[138:141], v[190:193], 0
	v_mfma_f32_16x16x32_bf16 v[88:91], v[150:153], v[190:193], 0
	v_mfma_f32_16x16x32_bf16 v[76:79], v[138:141], v[198:201], 0
	v_mfma_f32_16x16x32_bf16 v[72:75], v[150:153], v[198:201], 0
	v_mfma_f32_16x16x32_bf16 v[124:127], v[146:149], v[178:181], v[124:127]
	v_mfma_f32_16x16x32_bf16 v[120:123], v[154:157], v[178:181], v[120:123]
	v_mfma_f32_16x16x32_bf16 v[108:111], v[146:149], v[186:189], v[108:111]
	v_mfma_f32_16x16x32_bf16 v[104:107], v[154:157], v[186:189], v[104:107]
	v_mfma_f32_16x16x32_bf16 v[92:95], v[146:149], v[194:197], v[92:95]
	v_mfma_f32_16x16x32_bf16 v[88:91], v[154:157], v[194:197], v[88:91]
	v_mfma_f32_16x16x32_bf16 v[76:79], v[146:149], v[202:205], v[76:79]
	v_mfma_f32_16x16x32_bf16 v[72:75], v[154:157], v[202:205], v[72:75]
	v_mfma_f32_16x16x32_bf16 v[116:119], v[158:161], v[174:177], 0
	v_mfma_f32_16x16x32_bf16 v[112:115], v[166:169], v[174:177], 0
	v_mfma_f32_16x16x32_bf16 v[100:103], v[158:161], v[182:185], 0
	v_mfma_f32_16x16x32_bf16 v[96:99], v[166:169], v[182:185], 0
	v_mfma_f32_16x16x32_bf16 v[84:87], v[158:161], v[190:193], 0
	v_mfma_f32_16x16x32_bf16 v[80:83], v[166:169], v[190:193], 0
	v_mfma_f32_16x16x32_bf16 v[68:71], v[158:161], v[198:201], 0
	v_mfma_f32_16x16x32_bf16 v[64:67], v[166:169], v[198:201], 0
	v_mfma_f32_16x16x32_bf16 v[116:119], v[162:165], v[178:181], v[116:119]
	v_mfma_f32_16x16x32_bf16 v[112:115], v[170:173], v[178:181], v[112:115]
	v_mfma_f32_16x16x32_bf16 v[100:103], v[162:165], v[186:189], v[100:103]
	v_mfma_f32_16x16x32_bf16 v[96:99], v[170:173], v[186:189], v[96:99]
	v_mfma_f32_16x16x32_bf16 v[84:87], v[162:165], v[194:197], v[84:87]
	v_mfma_f32_16x16x32_bf16 v[80:83], v[170:173], v[194:197], v[80:83]
	v_mfma_f32_16x16x32_bf16 v[68:71], v[162:165], v[202:205], v[68:71]
	v_mfma_f32_16x16x32_bf16 v[64:67], v[170:173], v[202:205], v[64:67]
	s_barrier
	s_add_i32 s53, s53, s38
	v_lshl_add_u64 v[142:143], s[26:27], 0, v[232:233]
	s_mov_b32 m0, s53
	ds_read_b128 v[174:177], v145 offset:16384
	ds_read_b128 v[178:181], v145 offset:17408
	ds_read_b128 v[182:185], v145 offset:18432
	ds_read_b128 v[186:189], v145 offset:19456
	ds_read_b128 v[190:193], v145 offset:20480
	ds_read_b128 v[194:197], v145 offset:21504
	ds_read_b128 v[198:201], v145 offset:22528
	ds_read_b128 v[202:205], v145 offset:23552
	global_load_lds_dwordx4 v[142:143], off
	s_add_i32 m0, s53, 0x2000
	s_add_u32 s54, s26, 0x40000
	v_lshl_add_u64 v[206:207], s[26:27], 0, v[132:133]
	s_addc_u32 s55, s27, 0
	s_add_i32 s53, s56, s38
	global_load_lds_dwordx4 v[206:207], off
	v_lshl_add_u64 v[208:209], s[54:55], 0, v[232:233]
	s_mov_b32 m0, s53
	v_lshl_add_u64 v[210:211], s[28:29], 0, v[130:131]
	global_load_lds_dwordx4 v[208:209], off
	v_lshl_add_u64 v[208:209], s[54:55], 0, v[132:133]
	s_add_i32 m0, s53, 0x2000
	s_nop 0
	global_load_lds_dwordx4 v[208:209], off
	v_lshl_add_u64 v[208:209], s[28:29], 0, v[128:129]
	s_waitcnt vmcnt(6)
	s_waitcnt lgkmcnt(0)
	s_barrier
	v_mfma_f32_16x16x32_bf16 v[60:63], v[138:141], v[174:177], 0
	v_mfma_f32_16x16x32_bf16 v[56:59], v[150:153], v[174:177], 0
	v_mfma_f32_16x16x32_bf16 v[44:47], v[138:141], v[182:185], 0
	v_mfma_f32_16x16x32_bf16 v[40:43], v[150:153], v[182:185], 0
	v_mfma_f32_16x16x32_bf16 v[28:31], v[138:141], v[190:193], 0
	v_mfma_f32_16x16x32_bf16 v[24:27], v[150:153], v[190:193], 0
	v_mfma_f32_16x16x32_bf16 v[12:15], v[138:141], v[198:201], 0
	v_mfma_f32_16x16x32_bf16 v[8:11], v[150:153], v[198:201], 0
	v_mfma_f32_16x16x32_bf16 v[60:63], v[146:149], v[178:181], v[60:63]
	v_mfma_f32_16x16x32_bf16 v[56:59], v[154:157], v[178:181], v[56:59]
	v_mfma_f32_16x16x32_bf16 v[44:47], v[146:149], v[186:189], v[44:47]
	v_mfma_f32_16x16x32_bf16 v[40:43], v[154:157], v[186:189], v[40:43]
	v_mfma_f32_16x16x32_bf16 v[28:31], v[146:149], v[194:197], v[28:31]
	v_mfma_f32_16x16x32_bf16 v[24:27], v[154:157], v[194:197], v[24:27]
	v_mfma_f32_16x16x32_bf16 v[12:15], v[146:149], v[202:205], v[12:15]
	v_mfma_f32_16x16x32_bf16 v[8:11], v[154:157], v[202:205], v[8:11]
	v_mfma_f32_16x16x32_bf16 v[52:55], v[158:161], v[174:177], 0
	v_mfma_f32_16x16x32_bf16 v[48:51], v[166:169], v[174:177], 0
	v_mfma_f32_16x16x32_bf16 v[36:39], v[158:161], v[182:185], 0
	v_mfma_f32_16x16x32_bf16 v[32:35], v[166:169], v[182:185], 0
	v_mfma_f32_16x16x32_bf16 v[20:23], v[158:161], v[190:193], 0
	v_mfma_f32_16x16x32_bf16 v[16:19], v[166:169], v[190:193], 0
	v_mfma_f32_16x16x32_bf16 v[4:7], v[158:161], v[198:201], 0
	v_mfma_f32_16x16x32_bf16 v[0:3], v[166:169], v[198:201], 0
	v_mfma_f32_16x16x32_bf16 v[52:55], v[162:165], v[178:181], v[52:55]
	v_mfma_f32_16x16x32_bf16 v[48:51], v[170:173], v[178:181], v[48:51]
	v_mfma_f32_16x16x32_bf16 v[36:39], v[162:165], v[186:189], v[36:39]
	v_mfma_f32_16x16x32_bf16 v[32:35], v[170:173], v[186:189], v[32:35]
	v_mfma_f32_16x16x32_bf16 v[20:23], v[162:165], v[194:197], v[20:23]
	v_mfma_f32_16x16x32_bf16 v[16:19], v[170:173], v[194:197], v[16:19]
	v_mfma_f32_16x16x32_bf16 v[4:7], v[162:165], v[202:205], v[4:7]
	v_mfma_f32_16x16x32_bf16 v[0:3], v[170:173], v[202:205], v[0:3]
	s_barrier
	s_branch .Lzmid_4
.LBB0_1307:
	s_add_u32 s26, s24, 0xfffc0080
	s_addc_u32 s27, s25, -1
	s_add_i32 s53, 0, 0x10000
	s_cmp_eq_u32 s52, 12
	s_cselect_b32 s29, s7, s27
	s_cselect_b32 s28, s17, s26
	v_add_u32_e32 v142, s53, v144
	s_cselect_b32 s27, s15, s51
	s_cselect_b32 s26, s23, s50
	s_add_i32 s56, 0, 0x14000
	ds_read_b128 v[138:141], v142
	ds_read_b128 v[146:149], v142 offset:1024
	ds_read_b128 v[150:153], v142 offset:2048
	ds_read_b128 v[154:157], v142 offset:3072
	v_add_u32_e32 v142, s56, v144
	ds_read_b128 v[158:161], v142
	ds_read_b128 v[162:165], v142 offset:1024
	ds_read_b128 v[166:169], v142 offset:2048
	ds_read_b128 v[170:173], v142 offset:3072
	v_lshl_add_u64 v[142:143], s[24:25], 0, v[136:137]
	s_add_i32 m0, s39, 0xc000
	ds_read_b128 v[174:177], v145
	ds_read_b128 v[178:181], v145 offset:1024
	ds_read_b128 v[182:185], v145 offset:2048
	ds_read_b128 v[186:189], v145 offset:3072
	ds_read_b128 v[190:193], v145 offset:4096
	ds_read_b128 v[194:197], v145 offset:5120
	ds_read_b128 v[198:201], v145 offset:6144
	ds_read_b128 v[202:205], v145 offset:7168
	global_load_lds_dwordx4 v[142:143], off
	v_lshl_add_u64 v[142:143], s[24:25], 0, v[134:135]
	s_add_i32 m0, s39, 0xe000
	s_nop 0
	global_load_lds_dwordx4 v[142:143], off
	s_waitcnt vmcnt(8)
	s_waitcnt lgkmcnt(0)
	s_barrier
	v_mfma_f32_16x16x32_bf16 v[124:127], v[138:141], v[174:177], v[124:127]
	v_mfma_f32_16x16x32_bf16 v[120:123], v[150:153], v[174:177], v[120:123]
	v_mfma_f32_16x16x32_bf16 v[108:111], v[138:141], v[182:185], v[108:111]
	v_mfma_f32_16x16x32_bf16 v[104:107], v[150:153], v[182:185], v[104:107]
	v_mfma_f32_16x16x32_bf16 v[92:95], v[138:141], v[190:193], v[92:95]
	v_mfma_f32_16x16x32_bf16 v[88:91], v[150:153], v[190:193], v[88:91]
	v_mfma_f32_16x16x32_bf16 v[76:79], v[138:141], v[198:201], v[76:79]
	v_mfma_f32_16x16x32_bf16 v[72:75], v[150:153], v[198:201], v[72:75]
	v_mfma_f32_16x16x32_bf16 v[124:127], v[146:149], v[178:181], v[124:127]
	v_mfma_f32_16x16x32_bf16 v[120:123], v[154:157], v[178:181], v[120:123]
	v_mfma_f32_16x16x32_bf16 v[108:111], v[146:149], v[186:189], v[108:111]
	v_mfma_f32_16x16x32_bf16 v[104:107], v[154:157], v[186:189], v[104:107]
	v_mfma_f32_16x16x32_bf16 v[92:95], v[146:149], v[194:197], v[92:95]
	v_mfma_f32_16x16x32_bf16 v[88:91], v[154:157], v[194:197], v[88:91]
	v_mfma_f32_16x16x32_bf16 v[76:79], v[146:149], v[202:205], v[76:79]
	v_mfma_f32_16x16x32_bf16 v[72:75], v[154:157], v[202:205], v[72:75]
	v_mfma_f32_16x16x32_bf16 v[116:119], v[158:161], v[174:177], v[116:119]
	v_mfma_f32_16x16x32_bf16 v[112:115], v[166:169], v[174:177], v[112:115]
	v_mfma_f32_16x16x32_bf16 v[100:103], v[158:161], v[182:185], v[100:103]
	v_mfma_f32_16x16x32_bf16 v[96:99], v[166:169], v[182:185], v[96:99]
	v_mfma_f32_16x16x32_bf16 v[84:87], v[158:161], v[190:193], v[84:87]
	v_mfma_f32_16x16x32_bf16 v[80:83], v[166:169], v[190:193], v[80:83]
	v_mfma_f32_16x16x32_bf16 v[68:71], v[158:161], v[198:201], v[68:71]
	v_mfma_f32_16x16x32_bf16 v[64:67], v[166:169], v[198:201], v[64:67]
	v_mfma_f32_16x16x32_bf16 v[116:119], v[162:165], v[178:181], v[116:119]
	v_mfma_f32_16x16x32_bf16 v[112:115], v[170:173], v[178:181], v[112:115]
	v_mfma_f32_16x16x32_bf16 v[100:103], v[162:165], v[186:189], v[100:103]
	v_mfma_f32_16x16x32_bf16 v[96:99], v[170:173], v[186:189], v[96:99]
	v_mfma_f32_16x16x32_bf16 v[84:87], v[162:165], v[194:197], v[84:87]
	v_mfma_f32_16x16x32_bf16 v[80:83], v[170:173], v[194:197], v[80:83]
	v_mfma_f32_16x16x32_bf16 v[68:71], v[162:165], v[202:205], v[68:71]
	v_mfma_f32_16x16x32_bf16 v[64:67], v[170:173], v[202:205], v[64:67]
	s_barrier
	s_add_i32 s53, s53, s38
	v_lshl_add_u64 v[142:143], s[26:27], 0, v[232:233]
	s_mov_b32 m0, s53
	ds_read_b128 v[174:177], v145 offset:16384
	ds_read_b128 v[178:181], v145 offset:17408
	ds_read_b128 v[182:185], v145 offset:18432
	ds_read_b128 v[186:189], v145 offset:19456
	ds_read_b128 v[190:193], v145 offset:20480
	ds_read_b128 v[194:197], v145 offset:21504
	ds_read_b128 v[198:201], v145 offset:22528
	ds_read_b128 v[202:205], v145 offset:23552
	global_load_lds_dwordx4 v[142:143], off
	s_add_i32 m0, s53, 0x2000
	s_add_u32 s54, s26, 0x40000
	v_lshl_add_u64 v[206:207], s[26:27], 0, v[132:133]
	s_addc_u32 s55, s27, 0
	s_add_i32 s53, s56, s38
	global_load_lds_dwordx4 v[206:207], off
	v_lshl_add_u64 v[208:209], s[54:55], 0, v[232:233]
	s_mov_b32 m0, s53
	v_lshl_add_u64 v[210:211], s[28:29], 0, v[130:131]
	global_load_lds_dwordx4 v[208:209], off
	v_lshl_add_u64 v[208:209], s[54:55], 0, v[132:133]
	s_add_i32 m0, s53, 0x2000
	s_nop 0
	global_load_lds_dwordx4 v[208:209], off
	v_lshl_add_u64 v[208:209], s[28:29], 0, v[128:129]
	s_waitcnt vmcnt(6)
	s_waitcnt lgkmcnt(0)
	s_barrier
	v_mfma_f32_16x16x32_bf16 v[60:63], v[138:141], v[174:177], v[60:63]
	v_mfma_f32_16x16x32_bf16 v[56:59], v[150:153], v[174:177], v[56:59]
	v_mfma_f32_16x16x32_bf16 v[44:47], v[138:141], v[182:185], v[44:47]
	v_mfma_f32_16x16x32_bf16 v[40:43], v[150:153], v[182:185], v[40:43]
	v_mfma_f32_16x16x32_bf16 v[28:31], v[138:141], v[190:193], v[28:31]
	v_mfma_f32_16x16x32_bf16 v[24:27], v[150:153], v[190:193], v[24:27]
	v_mfma_f32_16x16x32_bf16 v[12:15], v[138:141], v[198:201], v[12:15]
	v_mfma_f32_16x16x32_bf16 v[8:11], v[150:153], v[198:201], v[8:11]
	v_mfma_f32_16x16x32_bf16 v[60:63], v[146:149], v[178:181], v[60:63]
	v_mfma_f32_16x16x32_bf16 v[56:59], v[154:157], v[178:181], v[56:59]
	v_mfma_f32_16x16x32_bf16 v[44:47], v[146:149], v[186:189], v[44:47]
	v_mfma_f32_16x16x32_bf16 v[40:43], v[154:157], v[186:189], v[40:43]
	v_mfma_f32_16x16x32_bf16 v[28:31], v[146:149], v[194:197], v[28:31]
	v_mfma_f32_16x16x32_bf16 v[24:27], v[154:157], v[194:197], v[24:27]
	v_mfma_f32_16x16x32_bf16 v[12:15], v[146:149], v[202:205], v[12:15]
	v_mfma_f32_16x16x32_bf16 v[8:11], v[154:157], v[202:205], v[8:11]
	v_mfma_f32_16x16x32_bf16 v[52:55], v[158:161], v[174:177], v[52:55]
	v_mfma_f32_16x16x32_bf16 v[48:51], v[166:169], v[174:177], v[48:51]
	v_mfma_f32_16x16x32_bf16 v[36:39], v[158:161], v[182:185], v[36:39]
	v_mfma_f32_16x16x32_bf16 v[32:35], v[166:169], v[182:185], v[32:35]
	v_mfma_f32_16x16x32_bf16 v[20:23], v[158:161], v[190:193], v[20:23]
	v_mfma_f32_16x16x32_bf16 v[16:19], v[166:169], v[190:193], v[16:19]
	v_mfma_f32_16x16x32_bf16 v[4:7], v[158:161], v[198:201], v[4:7]
	v_mfma_f32_16x16x32_bf16 v[0:3], v[166:169], v[198:201], v[0:3]
	v_mfma_f32_16x16x32_bf16 v[52:55], v[162:165], v[178:181], v[52:55]
	v_mfma_f32_16x16x32_bf16 v[48:51], v[170:173], v[178:181], v[48:51]
	v_mfma_f32_16x16x32_bf16 v[36:39], v[162:165], v[186:189], v[36:39]
	v_mfma_f32_16x16x32_bf16 v[32:35], v[170:173], v[186:189], v[32:35]
	v_mfma_f32_16x16x32_bf16 v[20:23], v[162:165], v[194:197], v[20:23]
	v_mfma_f32_16x16x32_bf16 v[16:19], v[170:173], v[194:197], v[16:19]
	v_mfma_f32_16x16x32_bf16 v[4:7], v[162:165], v[202:205], v[4:7]
	v_mfma_f32_16x16x32_bf16 v[0:3], v[170:173], v[202:205], v[0:3]
	s_barrier
.Lzmid_4:
	s_add_i32 s53, 0, 0x18000
	s_add_i32 s54, 0, 0x1c000
	v_add_u32_e32 v154, s53, v144
	v_add_u32_e32 v170, s54, v144
	ds_read_b128 v[138:141], v154
	ds_read_b128 v[146:149], v154 offset:1024
	ds_read_b128 v[150:153], v154 offset:2048
	ds_read_b128 v[154:157], v154 offset:3072
	ds_read_b128 v[158:161], v170
	ds_read_b128 v[162:165], v170 offset:1024
	ds_read_b128 v[166:169], v170 offset:2048
	ds_read_b128 v[170:173], v170 offset:3072
	s_add_u32 s28, s28, 0x40000
	s_addc_u32 s29, s29, 0
	s_mov_b32 m0, s39
	s_nop 0
	global_load_lds_dwordx4 v[208:209], off
	s_mov_b32 m0, s40
	s_nop 0
	global_load_lds_dwordx4 v[210:211], off
	s_mov_b32 m0, s41
	v_lshl_add_u64 v[212:213], s[28:29], 0, v[128:129]
	ds_read_b128 v[174:177], v145 offset:32768
	ds_read_b128 v[178:181], v145 offset:33792
	ds_read_b128 v[182:185], v145 offset:34816
	ds_read_b128 v[186:189], v145 offset:35840
	ds_read_b128 v[190:193], v145 offset:36864
	ds_read_b128 v[194:197], v145 offset:37888
	ds_read_b128 v[198:201], v145 offset:38912
	ds_read_b128 v[202:205], v145 offset:39936
	global_load_lds_dwordx4 v[212:213], off
	v_lshl_add_u64 v[212:213], s[28:29], 0, v[130:131]
	s_mov_b32 m0, s42
	s_nop 0
	global_load_lds_dwordx4 v[212:213], off
	s_waitcnt vmcnt(8)
	s_waitcnt lgkmcnt(0)
	s_barrier
	v_mfma_f32_16x16x32_bf16 v[124:127], v[138:141], v[174:177], v[124:127]
	v_mfma_f32_16x16x32_bf16 v[120:123], v[150:153], v[174:177], v[120:123]
	v_mfma_f32_16x16x32_bf16 v[108:111], v[138:141], v[182:185], v[108:111]
	v_mfma_f32_16x16x32_bf16 v[104:107], v[150:153], v[182:185], v[104:107]
	v_mfma_f32_16x16x32_bf16 v[92:95], v[138:141], v[190:193], v[92:95]
	v_mfma_f32_16x16x32_bf16 v[88:91], v[150:153], v[190:193], v[88:91]
	v_mfma_f32_16x16x32_bf16 v[76:79], v[138:141], v[198:201], v[76:79]
	v_mfma_f32_16x16x32_bf16 v[72:75], v[150:153], v[198:201], v[72:75]
	v_mfma_f32_16x16x32_bf16 v[124:127], v[146:149], v[178:181], v[124:127]
	v_mfma_f32_16x16x32_bf16 v[120:123], v[154:157], v[178:181], v[120:123]
	v_mfma_f32_16x16x32_bf16 v[108:111], v[146:149], v[186:189], v[108:111]
	v_mfma_f32_16x16x32_bf16 v[104:107], v[154:157], v[186:189], v[104:107]
	v_mfma_f32_16x16x32_bf16 v[92:95], v[146:149], v[194:197], v[92:95]
	v_mfma_f32_16x16x32_bf16 v[88:91], v[154:157], v[194:197], v[88:91]
	v_mfma_f32_16x16x32_bf16 v[76:79], v[146:149], v[202:205], v[76:79]
	v_mfma_f32_16x16x32_bf16 v[72:75], v[154:157], v[202:205], v[72:75]
	v_mfma_f32_16x16x32_bf16 v[116:119], v[158:161], v[174:177], v[116:119]
	v_mfma_f32_16x16x32_bf16 v[112:115], v[166:169], v[174:177], v[112:115]
	v_mfma_f32_16x16x32_bf16 v[100:103], v[158:161], v[182:185], v[100:103]
	v_mfma_f32_16x16x32_bf16 v[96:99], v[166:169], v[182:185], v[96:99]
	v_mfma_f32_16x16x32_bf16 v[84:87], v[158:161], v[190:193], v[84:87]
	v_mfma_f32_16x16x32_bf16 v[80:83], v[166:169], v[190:193], v[80:83]
	v_mfma_f32_16x16x32_bf16 v[68:71], v[158:161], v[198:201], v[68:71]
	v_mfma_f32_16x16x32_bf16 v[64:67], v[166:169], v[198:201], v[64:67]
	v_mfma_f32_16x16x32_bf16 v[116:119], v[162:165], v[178:181], v[116:119]
	v_mfma_f32_16x16x32_bf16 v[112:115], v[170:173], v[178:181], v[112:115]
	v_mfma_f32_16x16x32_bf16 v[100:103], v[162:165], v[186:189], v[100:103]
	v_mfma_f32_16x16x32_bf16 v[96:99], v[170:173], v[186:189], v[96:99]
	v_mfma_f32_16x16x32_bf16 v[84:87], v[162:165], v[194:197], v[84:87]
	v_mfma_f32_16x16x32_bf16 v[80:83], v[170:173], v[194:197], v[80:83]
	v_mfma_f32_16x16x32_bf16 v[68:71], v[162:165], v[202:205], v[68:71]
	v_mfma_f32_16x16x32_bf16 v[64:67], v[170:173], v[202:205], v[64:67]
	s_barrier
	s_add_i32 s28, s53, s38
	v_lshl_add_u64 v[142:143], v[142:143], 0, s[94:95]
	s_mov_b32 m0, s28
	ds_read_b128 v[174:177], v145 offset:49152
	ds_read_b128 v[178:181], v145 offset:50176
	ds_read_b128 v[182:185], v145 offset:51200
	ds_read_b128 v[186:189], v145 offset:52224
	ds_read_b128 v[190:193], v145 offset:53248
	ds_read_b128 v[194:197], v145 offset:54272
	ds_read_b128 v[198:201], v145 offset:55296
	ds_read_b128 v[202:205], v145 offset:56320
	global_load_lds_dwordx4 v[142:143], off
	s_add_i32 m0, s28, 0x2000
	s_add_u32 s26, s26, 0x40080
	v_lshl_add_u64 v[142:143], v[206:207], 0, s[94:95]
	s_addc_u32 s27, s27, 0
	s_add_i32 s28, s54, s38
	global_load_lds_dwordx4 v[142:143], off
	v_lshl_add_u64 v[142:143], s[26:27], 0, v[232:233]
	s_mov_b32 m0, s28
	s_nop 0
	global_load_lds_dwordx4 v[142:143], off
	v_lshl_add_u64 v[142:143], s[26:27], 0, v[132:133]
	s_add_i32 m0, s28, 0x2000
	s_nop 0
	global_load_lds_dwordx4 v[142:143], off
	v_lshl_add_u64 v[142:143], v[208:209], 0, s[94:95]
	s_mov_b32 m0, s45
	s_nop 0
	global_load_lds_dwordx4 v[142:143], off
	v_lshl_add_u64 v[142:143], v[210:211], 0, s[94:95]
	s_mov_b32 m0, s46
	s_nop 0
	global_load_lds_dwordx4 v[142:143], off
	s_waitcnt vmcnt(8)
	s_waitcnt lgkmcnt(0)
	s_barrier
	v_mfma_f32_16x16x32_bf16 v[60:63], v[138:141], v[174:177], v[60:63]
	v_mfma_f32_16x16x32_bf16 v[56:59], v[150:153], v[174:177], v[56:59]
	v_mfma_f32_16x16x32_bf16 v[44:47], v[138:141], v[182:185], v[44:47]
	v_mfma_f32_16x16x32_bf16 v[40:43], v[150:153], v[182:185], v[40:43]
	v_mfma_f32_16x16x32_bf16 v[28:31], v[138:141], v[190:193], v[28:31]
	v_mfma_f32_16x16x32_bf16 v[24:27], v[150:153], v[190:193], v[24:27]
	v_mfma_f32_16x16x32_bf16 v[12:15], v[138:141], v[198:201], v[12:15]
	v_mfma_f32_16x16x32_bf16 v[8:11], v[150:153], v[198:201], v[8:11]
	v_mfma_f32_16x16x32_bf16 v[60:63], v[146:149], v[178:181], v[60:63]
	v_mfma_f32_16x16x32_bf16 v[56:59], v[154:157], v[178:181], v[56:59]
	v_mfma_f32_16x16x32_bf16 v[44:47], v[146:149], v[186:189], v[44:47]
	v_mfma_f32_16x16x32_bf16 v[40:43], v[154:157], v[186:189], v[40:43]
	v_mfma_f32_16x16x32_bf16 v[28:31], v[146:149], v[194:197], v[28:31]
	v_mfma_f32_16x16x32_bf16 v[24:27], v[154:157], v[194:197], v[24:27]
	v_mfma_f32_16x16x32_bf16 v[12:15], v[146:149], v[202:205], v[12:15]
	v_mfma_f32_16x16x32_bf16 v[8:11], v[154:157], v[202:205], v[8:11]
	v_mfma_f32_16x16x32_bf16 v[52:55], v[158:161], v[174:177], v[52:55]
	v_mfma_f32_16x16x32_bf16 v[48:51], v[166:169], v[174:177], v[48:51]
	v_mfma_f32_16x16x32_bf16 v[36:39], v[158:161], v[182:185], v[36:39]
	v_mfma_f32_16x16x32_bf16 v[32:35], v[166:169], v[182:185], v[32:35]
	v_mfma_f32_16x16x32_bf16 v[20:23], v[158:161], v[190:193], v[20:23]
	v_mfma_f32_16x16x32_bf16 v[16:19], v[166:169], v[190:193], v[16:19]
	v_mfma_f32_16x16x32_bf16 v[4:7], v[158:161], v[198:201], v[4:7]
	v_mfma_f32_16x16x32_bf16 v[0:3], v[166:169], v[198:201], v[0:3]
	v_mfma_f32_16x16x32_bf16 v[52:55], v[162:165], v[178:181], v[52:55]
	v_mfma_f32_16x16x32_bf16 v[48:51], v[170:173], v[178:181], v[48:51]
	v_mfma_f32_16x16x32_bf16 v[36:39], v[162:165], v[186:189], v[36:39]
	v_mfma_f32_16x16x32_bf16 v[32:35], v[170:173], v[186:189], v[32:35]
	v_mfma_f32_16x16x32_bf16 v[20:23], v[162:165], v[194:197], v[20:23]
	v_mfma_f32_16x16x32_bf16 v[16:19], v[170:173], v[194:197], v[16:19]
	v_mfma_f32_16x16x32_bf16 v[4:7], v[162:165], v[202:205], v[4:7]
	v_mfma_f32_16x16x32_bf16 v[0:3], v[170:173], v[202:205], v[0:3]
	s_barrier
	s_add_i32 s52, s52, 2
	s_add_u32 s50, s50, 0x100
	s_addc_u32 s51, s51, 0
	s_add_u32 s24, s24, 0x100
	s_addc_u32 s25, s25, 0
	s_cmp_gt_u32 s52, 13
	s_cbranch_scc0 .LBB0_1307
	s_and_b64 vcc, exec, s[12:13]
	s_cbranch_vccz .LBB0_1310
	s_barrier

.LBB0_1420:
	s_ashr_i32 s17, s16, 31
	s_lshl_b64 s[18:19], s[16:17], 17
	s_add_u32 s18, s35, s18
	s_addc_u32 s19, s36, s19
	s_and_b64 s[20:21], s[4:5], exec
	s_cselect_b32 s31, s19, s25
	s_cselect_b32 s30, s18, s24
	s_ashr_i32 s15, s14, 31
	s_lshl_b64 s[20:21], s[14:15], 17
	s_add_u32 s20, s37, s20
	s_addc_u32 s21, s38, s21
	s_and_b64 s[28:29], s[4:5], exec
	s_cselect_b32 s29, s21, s27
	s_cselect_b32 s28, s20, s26
	s_add_i32 s17, 0, 0x10000
	s_add_i32 s49, 0, 0x14000
	v_add_u32_e32 v210, s17, v164
	v_add_u32_e32 v211, s49, v164
	ds_read_b128 v[0:3], v210
	ds_read_b128 v[4:7], v210 offset:1024
	ds_read_b128 v[8:11], v210 offset:2048
	ds_read_b128 v[12:15], v210 offset:3072
	ds_read_b128 v[16:19], v211
	ds_read_b128 v[20:23], v211 offset:1024
	ds_read_b128 v[24:27], v211 offset:2048
	ds_read_b128 v[28:31], v211 offset:3072
	v_mov_b64_e32 v[246:247], 0xff
	v_mov_b32_e32 v250, 0x3727c5ac
	s_add_u32 s50, s24, 0x10080
	s_addc_u32 s51, s25, 0
	s_add_i32 s53, s40, 0xc000
	s_waitcnt vmcnt(0)
	v_lshl_add_u64 v[64:65], s[50:51], 0, v[148:149]
	s_mov_b32 m0, s53
	s_add_i32 s15, s40, 0xe000
	ds_read_b128 v[32:35], v165
	ds_read_b128 v[36:39], v165 offset:1024
	ds_read_b128 v[40:43], v165 offset:2048
	ds_read_b128 v[44:47], v165 offset:3072
	ds_read_b128 v[48:51], v165 offset:4096
	ds_read_b128 v[52:55], v165 offset:5120
	ds_read_b128 v[56:59], v165 offset:6144
	ds_read_b128 v[60:63], v165 offset:7168
	global_load_lds_dwordx4 v[64:65], off
	v_lshl_add_u64 v[64:65], s[50:51], 0, v[150:151]
	s_mov_b32 m0, s15
	s_nop 0
	global_load_lds_dwordx4 v[64:65], off
	s_waitcnt vmcnt(8)
	s_waitcnt lgkmcnt(0)
	s_barrier
	v_mfma_f32_16x16x32_bf16 v[64:67], v[0:3], v[32:35], 0
	v_mfma_f32_16x16x32_bf16 v[68:71], v[8:11], v[32:35], 0
	v_mfma_f32_16x16x32_bf16 v[72:75], v[0:3], v[40:43], 0
	v_mfma_f32_16x16x32_bf16 v[76:79], v[8:11], v[40:43], 0
	v_mfma_f32_16x16x32_bf16 v[80:83], v[0:3], v[48:51], 0
	v_mfma_f32_16x16x32_bf16 v[84:87], v[8:11], v[48:51], 0
	v_mfma_f32_16x16x32_bf16 v[88:91], v[0:3], v[56:59], 0
	v_mfma_f32_16x16x32_bf16 v[92:95], v[8:11], v[56:59], 0
	v_mfma_f32_16x16x32_bf16 v[64:67], v[4:7], v[36:39], v[64:67]
	v_mfma_f32_16x16x32_bf16 v[68:71], v[12:15], v[36:39], v[68:71]
	v_mfma_f32_16x16x32_bf16 v[72:75], v[4:7], v[44:47], v[72:75]
	v_mfma_f32_16x16x32_bf16 v[76:79], v[12:15], v[44:47], v[76:79]
	v_mfma_f32_16x16x32_bf16 v[80:83], v[4:7], v[52:55], v[80:83]
	v_mfma_f32_16x16x32_bf16 v[84:87], v[12:15], v[52:55], v[84:87]
	v_mfma_f32_16x16x32_bf16 v[88:91], v[4:7], v[60:63], v[88:91]
	v_mfma_f32_16x16x32_bf16 v[92:95], v[12:15], v[60:63], v[92:95]
	v_mfma_f32_16x16x32_bf16 v[96:99], v[16:19], v[32:35], 0
	v_mfma_f32_16x16x32_bf16 v[32:35], v[24:27], v[32:35], 0
	v_mfma_f32_16x16x32_bf16 v[96:99], v[20:23], v[36:39], v[96:99]
	v_mfma_f32_16x16x32_bf16 v[32:35], v[28:31], v[36:39], v[32:35]
	v_mfma_f32_16x16x32_bf16 v[36:39], v[16:19], v[40:43], 0
	v_mfma_f32_16x16x32_bf16 v[40:43], v[24:27], v[40:43], 0
	v_mfma_f32_16x16x32_bf16 v[36:39], v[20:23], v[44:47], v[36:39]
	v_mfma_f32_16x16x32_bf16 v[40:43], v[28:31], v[44:47], v[40:43]
	v_mfma_f32_16x16x32_bf16 v[44:47], v[16:19], v[48:51], 0
	v_mfma_f32_16x16x32_bf16 v[48:51], v[24:27], v[48:51], 0
	v_mfma_f32_16x16x32_bf16 v[44:47], v[20:23], v[52:55], v[44:47]
	v_mfma_f32_16x16x32_bf16 v[48:51], v[28:31], v[52:55], v[48:51]
	v_mfma_f32_16x16x32_bf16 v[52:55], v[16:19], v[56:59], 0
	v_mfma_f32_16x16x32_bf16 v[56:59], v[24:27], v[56:59], 0
	v_mfma_f32_16x16x32_bf16 v[52:55], v[20:23], v[60:63], v[52:55]
	v_mfma_f32_16x16x32_bf16 v[56:59], v[28:31], v[60:63], v[56:59]
	s_barrier
	s_add_i32 s51, s17, s39
	v_lshl_add_u64 v[162:163], s[26:27], 0, v[232:233]
	s_mov_b64 s[56:57], 0x100
	s_add_i32 s17, s51, 0x2000
	v_lshl_add_u64 v[128:129], v[162:163], 0, s[56:57]
	s_mov_b32 m0, s51
	v_lshl_add_u64 v[202:203], s[26:27], 0, v[152:153]
	s_add_u32 s54, s26, 0x10100
	ds_read_b128 v[60:63], v165 offset:16384
	ds_read_b128 v[100:103], v165 offset:17408
	ds_read_b128 v[104:107], v165 offset:18432
	ds_read_b128 v[108:111], v165 offset:19456
	ds_read_b128 v[112:115], v165 offset:20480
	ds_read_b128 v[116:119], v165 offset:21504
	ds_read_b128 v[120:123], v165 offset:22528
	ds_read_b128 v[124:127], v165 offset:23552
	global_load_lds_dwordx4 v[128:129], off
	v_lshl_add_u64 v[128:129], v[202:203], 0, s[56:57]
	s_mov_b32 m0, s17
	s_addc_u32 s55, s27, 0
	s_add_i32 s49, s49, s39
	global_load_lds_dwordx4 v[128:129], off
	v_lshl_add_u64 v[128:129], s[54:55], 0, v[232:233]
	s_mov_b32 m0, s49
	s_add_i32 s50, s49, 0x2000
	global_load_lds_dwordx4 v[128:129], off
	v_lshl_add_u64 v[128:129], s[54:55], 0, v[152:153]
	s_mov_b32 m0, s50
	v_lshl_add_u64 v[204:205], s[24:25], 0, v[148:149]
	global_load_lds_dwordx4 v[128:129], off
	v_lshl_add_u64 v[128:129], v[204:205], 0, s[56:57]
	s_mov_b32 m0, s40
	v_lshl_add_u64 v[206:207], s[24:25], 0, v[150:151]
	global_load_lds_dwordx4 v[128:129], off
	v_lshl_add_u64 v[128:129], v[206:207], 0, s[56:57]
	s_mov_b32 m0, s41
	s_nop 0
	global_load_lds_dwordx4 v[128:129], off
	s_waitcnt vmcnt(8)
	s_waitcnt lgkmcnt(0)
	s_barrier
	v_mfma_f32_16x16x32_bf16 v[128:131], v[0:3], v[60:63], 0
	v_mfma_f32_16x16x32_bf16 v[136:139], v[0:3], v[104:107], 0
	v_mfma_f32_16x16x32_bf16 v[144:147], v[0:3], v[112:115], 0
	v_mfma_f32_16x16x32_bf16 v[0:3], v[0:3], v[120:123], 0
	v_mfma_f32_16x16x32_bf16 v[128:131], v[4:7], v[100:103], v[128:131]
	v_mfma_f32_16x16x32_bf16 v[132:135], v[8:11], v[60:63], 0
	v_mfma_f32_16x16x32_bf16 v[136:139], v[4:7], v[108:111], v[136:139]
	v_mfma_f32_16x16x32_bf16 v[140:143], v[8:11], v[104:107], 0
	v_mfma_f32_16x16x32_bf16 v[144:147], v[4:7], v[116:119], v[144:147]
	v_mfma_f32_16x16x32_bf16 v[0:3], v[4:7], v[124:127], v[0:3]
	v_mfma_f32_16x16x32_bf16 v[4:7], v[8:11], v[120:123], 0
	v_mfma_f32_16x16x32_bf16 v[132:135], v[12:15], v[100:103], v[132:135]
	v_mfma_f32_16x16x32_bf16 v[140:143], v[12:15], v[108:111], v[140:143]
	v_mfma_f32_16x16x32_bf16 v[154:157], v[8:11], v[112:115], 0
	v_mfma_f32_16x16x32_bf16 v[4:7], v[12:15], v[124:127], v[4:7]
	v_mfma_f32_16x16x32_bf16 v[154:157], v[12:15], v[116:119], v[154:157]
	v_mfma_f32_16x16x32_bf16 v[8:11], v[16:19], v[60:63], 0
	v_mfma_f32_16x16x32_bf16 v[12:15], v[24:27], v[60:63], 0
	v_mfma_f32_16x16x32_bf16 v[8:11], v[20:23], v[100:103], v[8:11]
	v_mfma_f32_16x16x32_bf16 v[12:15], v[28:31], v[100:103], v[12:15]
	v_mfma_f32_16x16x32_bf16 v[60:63], v[16:19], v[104:107], 0
	v_mfma_f32_16x16x32_bf16 v[100:103], v[24:27], v[104:107], 0
	v_mfma_f32_16x16x32_bf16 v[104:107], v[16:19], v[112:115], 0
	v_mfma_f32_16x16x32_bf16 v[16:19], v[16:19], v[120:123], 0
	v_mfma_f32_16x16x32_bf16 v[60:63], v[20:23], v[108:111], v[60:63]
	v_mfma_f32_16x16x32_bf16 v[104:107], v[20:23], v[116:119], v[104:107]
	v_mfma_f32_16x16x32_bf16 v[16:19], v[20:23], v[124:127], v[16:19]
	v_mfma_f32_16x16x32_bf16 v[20:23], v[24:27], v[120:123], 0
	v_mfma_f32_16x16x32_bf16 v[100:103], v[28:31], v[108:111], v[100:103]
	v_mfma_f32_16x16x32_bf16 v[108:111], v[24:27], v[112:115], 0
	v_mfma_f32_16x16x32_bf16 v[20:23], v[28:31], v[124:127], v[20:23]
	v_mfma_f32_16x16x32_bf16 v[108:111], v[28:31], v[116:119], v[108:111]
	s_barrier
	s_add_i32 s52, 0, 0x18000
	s_add_i32 s58, 0, 0x1c000
	v_add_u32_e32 v222, s52, v164
	v_add_u32_e32 v223, s58, v164
	ds_read_b128 v[24:27], v222
	ds_read_b128 v[28:31], v222 offset:1024
	ds_read_b128 v[112:115], v222 offset:2048
	ds_read_b128 v[116:119], v222 offset:3072
	ds_read_b128 v[120:123], v223
	ds_read_b128 v[124:127], v223 offset:1024
	ds_read_b128 v[158:161], v223 offset:2048
	ds_read_b128 v[166:169], v223 offset:3072
	s_add_u32 s54, s24, 0x10100
	s_addc_u32 s55, s25, 0
	s_mov_b32 m0, s42
	v_lshl_add_u64 v[208:209], s[54:55], 0, v[148:149]
	ds_read_b128 v[170:173], v165 offset:32768
	ds_read_b128 v[174:177], v165 offset:33792
	ds_read_b128 v[178:181], v165 offset:34816
	ds_read_b128 v[182:185], v165 offset:35840
	ds_read_b128 v[186:189], v165 offset:36864
	ds_read_b128 v[190:193], v165 offset:37888
	ds_read_b128 v[194:197], v165 offset:38912
	ds_read_b128 v[198:201], v165 offset:39936
	global_load_lds_dwordx4 v[208:209], off
	v_lshl_add_u64 v[208:209], s[54:55], 0, v[150:151]
	s_mov_b32 m0, s43
	s_nop 0
	global_load_lds_dwordx4 v[208:209], off
	s_waitcnt vmcnt(8)
	s_waitcnt lgkmcnt(0)
	s_barrier
	v_mfma_f32_16x16x32_bf16 v[64:67], v[24:27], v[170:173], v[64:67]
	v_mfma_f32_16x16x32_bf16 v[68:71], v[112:115], v[170:173], v[68:71]
	v_mfma_f32_16x16x32_bf16 v[72:75], v[24:27], v[178:181], v[72:75]
	v_mfma_f32_16x16x32_bf16 v[76:79], v[112:115], v[178:181], v[76:79]
	v_mfma_f32_16x16x32_bf16 v[80:83], v[24:27], v[186:189], v[80:83]
	v_mfma_f32_16x16x32_bf16 v[84:87], v[112:115], v[186:189], v[84:87]
	v_mfma_f32_16x16x32_bf16 v[88:91], v[24:27], v[194:197], v[88:91]
	v_mfma_f32_16x16x32_bf16 v[92:95], v[112:115], v[194:197], v[92:95]
	v_mfma_f32_16x16x32_bf16 v[64:67], v[28:31], v[174:177], v[64:67]
	v_mfma_f32_16x16x32_bf16 v[68:71], v[116:119], v[174:177], v[68:71]
	v_mfma_f32_16x16x32_bf16 v[72:75], v[28:31], v[182:185], v[72:75]
	v_mfma_f32_16x16x32_bf16 v[76:79], v[116:119], v[182:185], v[76:79]
	v_mfma_f32_16x16x32_bf16 v[80:83], v[28:31], v[190:193], v[80:83]
	v_mfma_f32_16x16x32_bf16 v[84:87], v[116:119], v[190:193], v[84:87]
	v_mfma_f32_16x16x32_bf16 v[88:91], v[28:31], v[198:201], v[88:91]
	v_mfma_f32_16x16x32_bf16 v[92:95], v[116:119], v[198:201], v[92:95]
	v_mfma_f32_16x16x32_bf16 v[96:99], v[120:123], v[170:173], v[96:99]
	v_mfma_f32_16x16x32_bf16 v[32:35], v[158:161], v[170:173], v[32:35]
	v_mfma_f32_16x16x32_bf16 v[36:39], v[120:123], v[178:181], v[36:39]
	v_mfma_f32_16x16x32_bf16 v[40:43], v[158:161], v[178:181], v[40:43]
	v_mfma_f32_16x16x32_bf16 v[44:47], v[120:123], v[186:189], v[44:47]
	v_mfma_f32_16x16x32_bf16 v[48:51], v[158:161], v[186:189], v[48:51]
	v_mfma_f32_16x16x32_bf16 v[52:55], v[120:123], v[194:197], v[52:55]
	v_mfma_f32_16x16x32_bf16 v[56:59], v[158:161], v[194:197], v[56:59]
	v_mfma_f32_16x16x32_bf16 v[96:99], v[124:127], v[174:177], v[96:99]
	v_mfma_f32_16x16x32_bf16 v[32:35], v[166:169], v[174:177], v[32:35]
	v_mfma_f32_16x16x32_bf16 v[36:39], v[124:127], v[182:185], v[36:39]
	v_mfma_f32_16x16x32_bf16 v[40:43], v[166:169], v[182:185], v[40:43]
	v_mfma_f32_16x16x32_bf16 v[44:47], v[124:127], v[190:193], v[44:47]
	v_mfma_f32_16x16x32_bf16 v[48:51], v[166:169], v[190:193], v[48:51]
	v_mfma_f32_16x16x32_bf16 v[52:55], v[124:127], v[198:201], v[52:55]
	v_mfma_f32_16x16x32_bf16 v[56:59], v[166:169], v[198:201], v[56:59]
	s_barrier
	s_add_i32 s54, s52, s39
	s_mov_b64 s[60:61], 0x180
	s_add_i32 s52, s54, 0x2000
	v_lshl_add_u64 v[162:163], v[162:163], 0, s[60:61]
	s_mov_b32 m0, s54
	s_add_u32 s56, s26, 0x10180
	ds_read_b128 v[170:173], v165 offset:49152
	ds_read_b128 v[174:177], v165 offset:50176
	ds_read_b128 v[178:181], v165 offset:51200
	ds_read_b128 v[182:185], v165 offset:52224
	ds_read_b128 v[186:189], v165 offset:53248
	ds_read_b128 v[190:193], v165 offset:54272
	ds_read_b128 v[194:197], v165 offset:55296
	ds_read_b128 v[198:201], v165 offset:56320
	global_load_lds_dwordx4 v[162:163], off
	v_lshl_add_u64 v[162:163], v[202:203], 0, s[60:61]
	s_mov_b32 m0, s52
	s_addc_u32 s57, s27, 0
	s_add_i32 s26, s58, s39
	global_load_lds_dwordx4 v[162:163], off
	v_lshl_add_u64 v[162:163], s[56:57], 0, v[232:233]
	s_mov_b32 m0, s26
	s_add_i32 s27, s26, 0x2000
	global_load_lds_dwordx4 v[162:163], off
	v_lshl_add_u64 v[162:163], s[56:57], 0, v[152:153]
	s_mov_b32 m0, s27
	s_nop 0
	global_load_lds_dwordx4 v[162:163], off
	v_lshl_add_u64 v[162:163], v[204:205], 0, s[60:61]
	s_mov_b32 m0, s46
	s_nop 0
	global_load_lds_dwordx4 v[162:163], off
	v_lshl_add_u64 v[162:163], v[206:207], 0, s[60:61]
	s_mov_b32 m0, s47
	s_nop 0
	global_load_lds_dwordx4 v[162:163], off
	s_waitcnt vmcnt(8)
	s_waitcnt lgkmcnt(0)
	s_barrier
	v_mfma_f32_16x16x32_bf16 v[128:131], v[24:27], v[170:173], v[128:131]
	v_mfma_f32_16x16x32_bf16 v[132:135], v[112:115], v[170:173], v[132:135]
	v_mfma_f32_16x16x32_bf16 v[136:139], v[24:27], v[178:181], v[136:139]
	v_mfma_f32_16x16x32_bf16 v[140:143], v[112:115], v[178:181], v[140:143]
	v_mfma_f32_16x16x32_bf16 v[144:147], v[24:27], v[186:189], v[144:147]
	v_mfma_f32_16x16x32_bf16 v[0:3], v[24:27], v[194:197], v[0:3]
	v_mfma_f32_16x16x32_bf16 v[4:7], v[112:115], v[194:197], v[4:7]
	v_mfma_f32_16x16x32_bf16 v[128:131], v[28:31], v[174:177], v[128:131]
	v_mfma_f32_16x16x32_bf16 v[132:135], v[116:119], v[174:177], v[132:135]
	v_mfma_f32_16x16x32_bf16 v[136:139], v[28:31], v[182:185], v[136:139]
	v_mfma_f32_16x16x32_bf16 v[140:143], v[116:119], v[182:185], v[140:143]
	v_mfma_f32_16x16x32_bf16 v[144:147], v[28:31], v[190:193], v[144:147]
	v_mfma_f32_16x16x32_bf16 v[154:157], v[112:115], v[186:189], v[154:157]
	v_mfma_f32_16x16x32_bf16 v[0:3], v[28:31], v[198:201], v[0:3]
	v_mfma_f32_16x16x32_bf16 v[4:7], v[116:119], v[198:201], v[4:7]
	v_mfma_f32_16x16x32_bf16 v[154:157], v[116:119], v[190:193], v[154:157]
	v_mfma_f32_16x16x32_bf16 v[8:11], v[120:123], v[170:173], v[8:11]
	v_mfma_f32_16x16x32_bf16 v[12:15], v[158:161], v[170:173], v[12:15]
	v_mfma_f32_16x16x32_bf16 v[24:27], v[120:123], v[178:181], v[60:63]
	v_mfma_f32_16x16x32_bf16 v[28:31], v[158:161], v[178:181], v[100:103]
	v_mfma_f32_16x16x32_bf16 v[60:63], v[120:123], v[186:189], v[104:107]
	v_mfma_f32_16x16x32_bf16 v[100:103], v[158:161], v[186:189], v[108:111]
	v_mfma_f32_16x16x32_bf16 v[16:19], v[120:123], v[194:197], v[16:19]
	v_mfma_f32_16x16x32_bf16 v[20:23], v[158:161], v[194:197], v[20:23]
	v_mfma_f32_16x16x32_bf16 v[8:11], v[124:127], v[174:177], v[8:11]
	v_mfma_f32_16x16x32_bf16 v[12:15], v[166:169], v[174:177], v[12:15]
	v_mfma_f32_16x16x32_bf16 v[24:27], v[124:127], v[182:185], v[24:27]
	v_mfma_f32_16x16x32_bf16 v[28:31], v[166:169], v[182:185], v[28:31]
	v_mfma_f32_16x16x32_bf16 v[60:63], v[124:127], v[190:193], v[60:63]
	v_mfma_f32_16x16x32_bf16 v[100:103], v[166:169], v[190:193], v[100:103]
	v_mfma_f32_16x16x32_bf16 v[16:19], v[124:127], v[198:201], v[16:19]
	v_mfma_f32_16x16x32_bf16 v[20:23], v[166:169], v[198:201], v[20:23]
	s_barrier
	ds_read_b128 v[104:107], v210
	ds_read_b128 v[108:111], v210 offset:1024
	ds_read_b128 v[112:115], v210 offset:2048
	ds_read_b128 v[116:119], v210 offset:3072
	ds_read_b128 v[120:123], v211
	ds_read_b128 v[124:127], v211 offset:1024
	ds_read_b128 v[158:161], v211 offset:2048
	ds_read_b128 v[166:169], v211 offset:3072
	s_add_u32 s24, s24, 0x10180
	s_addc_u32 s25, s25, 0
	s_mov_b32 m0, s53
	v_lshl_add_u64 v[162:163], s[24:25], 0, v[148:149]
	ds_read_b128 v[170:173], v165
	ds_read_b128 v[174:177], v165 offset:1024
	ds_read_b128 v[178:181], v165 offset:2048
	ds_read_b128 v[182:185], v165 offset:3072
	ds_read_b128 v[186:189], v165 offset:4096
	ds_read_b128 v[190:193], v165 offset:5120
	ds_read_b128 v[194:197], v165 offset:6144
	ds_read_b128 v[198:201], v165 offset:7168
	global_load_lds_dwordx4 v[162:163], off
	v_lshl_add_u64 v[162:163], s[24:25], 0, v[150:151]
	s_mov_b32 m0, s15
	s_nop 0
	global_load_lds_dwordx4 v[162:163], off
	s_waitcnt vmcnt(8)
	s_waitcnt lgkmcnt(0)
	s_barrier
	v_mfma_f32_16x16x32_bf16 v[64:67], v[104:107], v[170:173], v[64:67]
	v_mfma_f32_16x16x32_bf16 v[68:71], v[112:115], v[170:173], v[68:71]
	v_mfma_f32_16x16x32_bf16 v[72:75], v[104:107], v[178:181], v[72:75]
	v_mfma_f32_16x16x32_bf16 v[76:79], v[112:115], v[178:181], v[76:79]
	v_mfma_f32_16x16x32_bf16 v[80:83], v[104:107], v[186:189], v[80:83]
	v_mfma_f32_16x16x32_bf16 v[84:87], v[112:115], v[186:189], v[84:87]
	v_mfma_f32_16x16x32_bf16 v[88:91], v[104:107], v[194:197], v[88:91]
	v_mfma_f32_16x16x32_bf16 v[64:67], v[108:111], v[174:177], v[64:67]
	v_mfma_f32_16x16x32_bf16 v[68:71], v[116:119], v[174:177], v[68:71]
	v_mfma_f32_16x16x32_bf16 v[72:75], v[108:111], v[182:185], v[72:75]
	v_mfma_f32_16x16x32_bf16 v[76:79], v[116:119], v[182:185], v[76:79]
	v_mfma_f32_16x16x32_bf16 v[80:83], v[108:111], v[190:193], v[80:83]
	v_mfma_f32_16x16x32_bf16 v[84:87], v[116:119], v[190:193], v[84:87]
	v_mfma_f32_16x16x32_bf16 v[202:205], v[108:111], v[198:201], v[88:91]
	v_mfma_f32_16x16x32_bf16 v[88:91], v[112:115], v[194:197], v[92:95]
	v_mfma_f32_16x16x32_bf16 v[206:209], v[116:119], v[198:201], v[88:91]
	v_mfma_f32_16x16x32_bf16 v[88:91], v[120:123], v[170:173], v[96:99]
	v_mfma_f32_16x16x32_bf16 v[32:35], v[158:161], v[170:173], v[32:35]
	v_mfma_f32_16x16x32_bf16 v[36:39], v[120:123], v[178:181], v[36:39]
	v_mfma_f32_16x16x32_bf16 v[40:43], v[158:161], v[178:181], v[40:43]
	v_mfma_f32_16x16x32_bf16 v[44:47], v[120:123], v[186:189], v[44:47]
	v_mfma_f32_16x16x32_bf16 v[48:51], v[158:161], v[186:189], v[48:51]
	v_mfma_f32_16x16x32_bf16 v[52:55], v[120:123], v[194:197], v[52:55]
	v_mfma_f32_16x16x32_bf16 v[56:59], v[158:161], v[194:197], v[56:59]
	v_mfma_f32_16x16x32_bf16 v[96:99], v[124:127], v[174:177], v[88:91]
	v_mfma_f32_16x16x32_bf16 v[32:35], v[166:169], v[174:177], v[32:35]
	v_mfma_f32_16x16x32_bf16 v[36:39], v[124:127], v[182:185], v[36:39]
	v_mfma_f32_16x16x32_bf16 v[40:43], v[166:169], v[182:185], v[40:43]
	v_mfma_f32_16x16x32_bf16 v[44:47], v[124:127], v[190:193], v[44:47]
	v_mfma_f32_16x16x32_bf16 v[48:51], v[166:169], v[190:193], v[48:51]
	v_mfma_f32_16x16x32_bf16 v[52:55], v[124:127], v[198:201], v[52:55]
	v_mfma_f32_16x16x32_bf16 v[56:59], v[166:169], v[198:201], v[56:59]
	s_barrier
	s_mov_b32 m0, s51
	v_lshl_add_u64 v[162:163], s[28:29], 0, v[232:233]
	s_add_u32 s24, s28, 0x10000
	ds_read_b128 v[88:91], v165 offset:16384
	ds_read_b128 v[92:95], v165 offset:17408
	ds_read_b128 v[170:173], v165 offset:18432
	ds_read_b128 v[174:177], v165 offset:19456
	ds_read_b128 v[178:181], v165 offset:20480
	ds_read_b128 v[182:185], v165 offset:21504
	ds_read_b128 v[186:189], v165 offset:22528
	ds_read_b128 v[190:193], v165 offset:23552
	global_load_lds_dwordx4 v[162:163], off
	v_lshl_add_u64 v[230:231], s[28:29], 0, v[152:153]
	s_mov_b32 m0, s17
	s_addc_u32 s25, s29, 0
	global_load_lds_dwordx4 v[230:231], off
	v_lshl_add_u64 v[194:195], s[24:25], 0, v[232:233]
	s_mov_b32 m0, s49
	v_lshl_add_u64 v[242:243], s[30:31], 0, v[148:149]
	global_load_lds_dwordx4 v[194:195], off
	v_lshl_add_u64 v[194:195], s[24:25], 0, v[152:153]
	s_mov_b32 m0, s50
	v_lshl_add_u64 v[244:245], s[30:31], 0, v[150:151]
	global_load_lds_dwordx4 v[194:195], off
	s_mov_b32 m0, s40
	s_nop 0
	global_load_lds_dwordx4 v[242:243], off
	s_mov_b32 m0, s41
	s_nop 0
	global_load_lds_dwordx4 v[244:245], off
	s_waitcnt vmcnt(8)
	s_waitcnt lgkmcnt(0)
	s_barrier
	v_mfma_f32_16x16x32_bf16 v[128:131], v[104:107], v[88:91], v[128:131]
	v_mfma_f32_16x16x32_bf16 v[194:197], v[108:111], v[92:95], v[128:131]
	v_mfma_f32_16x16x32_bf16 v[128:131], v[112:115], v[88:91], v[132:135]
	v_mfma_f32_16x16x32_bf16 v[198:201], v[116:119], v[92:95], v[128:131]
	v_mfma_f32_16x16x32_bf16 v[128:131], v[104:107], v[170:173], v[136:139]
	v_mfma_f32_16x16x32_bf16 v[210:213], v[108:111], v[174:177], v[128:131]
	v_mfma_f32_16x16x32_bf16 v[128:131], v[112:115], v[170:173], v[140:143]
	v_mfma_f32_16x16x32_bf16 v[214:217], v[116:119], v[174:177], v[128:131]
	v_mfma_f32_16x16x32_bf16 v[128:131], v[104:107], v[178:181], v[144:147]
	v_mfma_f32_16x16x32_bf16 v[0:3], v[104:107], v[186:189], v[0:3]
	v_mfma_f32_16x16x32_bf16 v[4:7], v[112:115], v[186:189], v[4:7]
	v_mfma_f32_16x16x32_bf16 v[218:221], v[108:111], v[182:185], v[128:131]
	v_mfma_f32_16x16x32_bf16 v[128:131], v[112:115], v[178:181], v[154:157]
	v_mfma_f32_16x16x32_bf16 v[0:3], v[108:111], v[190:193], v[0:3]
	v_mfma_f32_16x16x32_bf16 v[4:7], v[116:119], v[190:193], v[4:7]
	v_mfma_f32_16x16x32_bf16 v[154:157], v[116:119], v[182:185], v[128:131]
	v_mfma_f32_16x16x32_bf16 v[8:11], v[120:123], v[88:91], v[8:11]
	v_mfma_f32_16x16x32_bf16 v[104:107], v[124:127], v[92:95], v[8:11]
	v_mfma_f32_16x16x32_bf16 v[8:11], v[158:161], v[88:91], v[12:15]
	v_mfma_f32_16x16x32_bf16 v[108:111], v[166:169], v[92:95], v[8:11]
	v_mfma_f32_16x16x32_bf16 v[8:11], v[120:123], v[170:173], v[24:27]
	v_mfma_f32_16x16x32_bf16 v[112:115], v[124:127], v[174:177], v[8:11]
	v_mfma_f32_16x16x32_bf16 v[8:11], v[158:161], v[170:173], v[28:31]
	v_mfma_f32_16x16x32_bf16 v[116:119], v[166:169], v[174:177], v[8:11]
	v_mfma_f32_16x16x32_bf16 v[8:11], v[120:123], v[178:181], v[60:63]
	v_mfma_f32_16x16x32_bf16 v[170:173], v[124:127], v[182:185], v[8:11]
	v_mfma_f32_16x16x32_bf16 v[8:11], v[158:161], v[178:181], v[100:103]
	v_mfma_f32_16x16x32_bf16 v[174:177], v[166:169], v[182:185], v[8:11]
	v_mfma_f32_16x16x32_bf16 v[8:11], v[120:123], v[186:189], v[16:19]
	v_mfma_f32_16x16x32_bf16 v[124:127], v[124:127], v[190:193], v[8:11]
	v_mfma_f32_16x16x32_bf16 v[8:11], v[158:161], v[186:189], v[20:23]
	v_mfma_f32_16x16x32_bf16 v[158:161], v[166:169], v[190:193], v[8:11]
	s_barrier
	s_nop 4
	ds_read_b128 v[8:11], v222
	ds_read_b128 v[12:15], v222 offset:1024
	ds_read_b128 v[16:19], v222 offset:2048
	ds_read_b128 v[20:23], v222 offset:3072
	ds_read_b128 v[166:169], v223
	ds_read_b128 v[178:181], v223 offset:1024
	ds_read_b128 v[182:185], v223 offset:2048
	ds_read_b128 v[186:189], v223 offset:3072
	s_add_u32 s24, s30, 0x10000
	s_addc_u32 s25, s31, 0
	s_mov_b32 m0, s42
	v_lshl_add_u64 v[88:89], s[24:25], 0, v[148:149]
	ds_read_b128 v[24:27], v165 offset:32768
	ds_read_b128 v[28:31], v165 offset:33792
	ds_read_b128 v[60:63], v165 offset:34816
	ds_read_b128 v[190:193], v165 offset:35840
	ds_read_b128 v[222:225], v165 offset:36864
	ds_read_b128 v[226:229], v165 offset:37888
	ds_read_b128 v[234:237], v165 offset:38912
	ds_read_b128 v[238:241], v165 offset:39936
	global_load_lds_dwordx4 v[88:89], off
	v_lshl_add_u64 v[88:89], s[24:25], 0, v[150:151]
	s_mov_b32 m0, s43
	s_nop 0
	global_load_lds_dwordx4 v[88:89], off
	s_waitcnt vmcnt(8)
	s_waitcnt lgkmcnt(0)
	s_barrier
	v_mfma_f32_16x16x32_bf16 v[64:67], v[8:11], v[24:27], v[64:67]
	v_mfma_f32_16x16x32_bf16 v[144:147], v[12:15], v[28:31], v[64:67]
	v_mfma_f32_16x16x32_bf16 v[64:67], v[16:19], v[24:27], v[68:71]
	v_mfma_f32_16x16x32_bf16 v[140:143], v[20:23], v[28:31], v[64:67]
	v_mfma_f32_16x16x32_bf16 v[64:67], v[8:11], v[60:63], v[72:75]
	v_mfma_f32_16x16x32_bf16 v[128:131], v[12:15], v[190:193], v[64:67]
	v_mfma_f32_16x16x32_bf16 v[64:67], v[16:19], v[60:63], v[76:79]
	v_mfma_f32_16x16x32_bf16 v[120:123], v[20:23], v[190:193], v[64:67]
	v_mfma_f32_16x16x32_bf16 v[64:67], v[8:11], v[222:225], v[80:83]
	v_mfma_f32_16x16x32_bf16 v[92:95], v[12:15], v[226:229], v[64:67]
	v_mfma_f32_16x16x32_bf16 v[64:67], v[16:19], v[222:225], v[84:87]
	v_mfma_f32_16x16x32_bf16 v[88:91], v[20:23], v[226:229], v[64:67]
	v_mfma_f32_16x16x32_bf16 v[64:67], v[8:11], v[234:237], v[202:205]
	v_mfma_f32_16x16x32_bf16 v[76:79], v[12:15], v[238:241], v[64:67]
	v_mfma_f32_16x16x32_bf16 v[64:67], v[16:19], v[234:237], v[206:209]
	v_mfma_f32_16x16x32_bf16 v[72:75], v[20:23], v[238:241], v[64:67]
	v_mfma_f32_16x16x32_bf16 v[64:67], v[166:169], v[24:27], v[96:99]
	v_mfma_f32_16x16x32_bf16 v[24:27], v[182:185], v[24:27], v[32:35]
	v_mfma_f32_16x16x32_bf16 v[132:135], v[186:189], v[28:31], v[24:27]
	v_mfma_f32_16x16x32_bf16 v[24:27], v[166:169], v[60:63], v[36:39]
	v_mfma_f32_16x16x32_bf16 v[100:103], v[178:181], v[190:193], v[24:27]
	v_mfma_f32_16x16x32_bf16 v[24:27], v[182:185], v[60:63], v[40:43]
	v_mfma_f32_16x16x32_bf16 v[96:99], v[186:189], v[190:193], v[24:27]
	v_mfma_f32_16x16x32_bf16 v[24:27], v[166:169], v[222:225], v[44:47]
	v_mfma_f32_16x16x32_bf16 v[84:87], v[178:181], v[226:229], v[24:27]
	v_mfma_f32_16x16x32_bf16 v[24:27], v[182:185], v[222:225], v[48:51]
	v_mfma_f32_16x16x32_bf16 v[80:83], v[186:189], v[226:229], v[24:27]
	v_mfma_f32_16x16x32_bf16 v[24:27], v[166:169], v[234:237], v[52:55]
	v_mfma_f32_16x16x32_bf16 v[68:71], v[178:181], v[238:241], v[24:27]
	v_mfma_f32_16x16x32_bf16 v[24:27], v[182:185], v[234:237], v[56:59]
	v_mfma_f32_16x16x32_bf16 v[136:139], v[178:181], v[28:31], v[64:67]
	v_mfma_f32_16x16x32_bf16 v[64:67], v[186:189], v[238:241], v[24:27]
	s_barrier
	s_mov_b32 m0, s54
	s_nop 2
	v_lshl_add_u64 v[24:25], v[162:163], 0, s[94:95]
	s_add_u32 s24, s28, 0x10080
	ds_read_b128 v[32:35], v165 offset:49152
	ds_read_b128 v[36:39], v165 offset:50176
	ds_read_b128 v[190:193], v165 offset:51200
	ds_read_b128 v[202:205], v165 offset:52224
	ds_read_b128 v[206:209], v165 offset:53248
	ds_read_b128 v[222:225], v165 offset:54272
	ds_read_b128 v[226:229], v165 offset:55296
	ds_read_b128 v[234:237], v165 offset:56320
	global_load_lds_dwordx4 v[24:25], off
	v_lshl_add_u64 v[24:25], v[230:231], 0, s[94:95]
	s_mov_b32 m0, s52
	s_addc_u32 s25, s29, 0
	global_load_lds_dwordx4 v[24:25], off
	v_lshl_add_u64 v[24:25], s[24:25], 0, v[232:233]
	s_mov_b32 m0, s26
	s_nop 0
	global_load_lds_dwordx4 v[24:25], off
	v_lshl_add_u64 v[24:25], s[24:25], 0, v[152:153]
	s_mov_b32 m0, s27
	s_nop 0
	global_load_lds_dwordx4 v[24:25], off
	v_lshl_add_u64 v[24:25], v[242:243], 0, s[94:95]
	s_mov_b32 m0, s46
	s_nop 0
	global_load_lds_dwordx4 v[24:25], off
	v_lshl_add_u64 v[24:25], v[244:245], 0, s[94:95]
	s_mov_b32 m0, s47
	s_nop 0
	global_load_lds_dwordx4 v[24:25], off
	s_waitcnt vmcnt(8)
	s_waitcnt lgkmcnt(0)
	s_barrier
	v_mfma_f32_16x16x32_bf16 v[24:27], v[8:11], v[32:35], v[194:197]
	v_mfma_f32_16x16x32_bf16 v[60:63], v[12:15], v[36:39], v[24:27]
	v_mfma_f32_16x16x32_bf16 v[24:27], v[16:19], v[32:35], v[198:201]
	v_mfma_f32_16x16x32_bf16 v[56:59], v[20:23], v[36:39], v[24:27]
	v_mfma_f32_16x16x32_bf16 v[24:27], v[8:11], v[190:193], v[210:213]
	v_mfma_f32_16x16x32_bf16 v[44:47], v[12:15], v[202:205], v[24:27]
	v_mfma_f32_16x16x32_bf16 v[24:27], v[16:19], v[190:193], v[214:217]
	v_mfma_f32_16x16x32_bf16 v[40:43], v[20:23], v[202:205], v[24:27]
	v_mfma_f32_16x16x32_bf16 v[24:27], v[8:11], v[206:209], v[218:221]
	v_mfma_f32_16x16x32_bf16 v[0:3], v[8:11], v[226:229], v[0:3]
	v_mfma_f32_16x16x32_bf16 v[28:31], v[12:15], v[222:225], v[24:27]
	v_mfma_f32_16x16x32_bf16 v[24:27], v[16:19], v[206:209], v[154:157]
	v_mfma_f32_16x16x32_bf16 v[12:15], v[12:15], v[234:237], v[0:3]
	v_mfma_f32_16x16x32_bf16 v[0:3], v[16:19], v[226:229], v[4:7]
	v_mfma_f32_16x16x32_bf16 v[24:27], v[20:23], v[222:225], v[24:27]
	v_mfma_f32_16x16x32_bf16 v[8:11], v[20:23], v[234:237], v[0:3]
	v_mfma_f32_16x16x32_bf16 v[0:3], v[166:169], v[32:35], v[104:107]
	v_mfma_f32_16x16x32_bf16 v[52:55], v[178:181], v[36:39], v[0:3]
	v_mfma_f32_16x16x32_bf16 v[0:3], v[182:185], v[32:35], v[108:111]
	v_mfma_f32_16x16x32_bf16 v[48:51], v[186:189], v[36:39], v[0:3]
	v_mfma_f32_16x16x32_bf16 v[0:3], v[166:169], v[190:193], v[112:115]
	v_mfma_f32_16x16x32_bf16 v[36:39], v[178:181], v[202:205], v[0:3]
	v_mfma_f32_16x16x32_bf16 v[0:3], v[182:185], v[190:193], v[116:119]
	v_mfma_f32_16x16x32_bf16 v[32:35], v[186:189], v[202:205], v[0:3]
	v_mfma_f32_16x16x32_bf16 v[0:3], v[166:169], v[206:209], v[170:173]
	v_mfma_f32_16x16x32_bf16 v[20:23], v[178:181], v[222:225], v[0:3]
	v_mfma_f32_16x16x32_bf16 v[0:3], v[182:185], v[206:209], v[174:177]
	v_mfma_f32_16x16x32_bf16 v[16:19], v[186:189], v[222:225], v[0:3]
	v_mfma_f32_16x16x32_bf16 v[0:3], v[166:169], v[226:229], v[124:127]
	v_mfma_f32_16x16x32_bf16 v[4:7], v[178:181], v[234:237], v[0:3]
	v_mfma_f32_16x16x32_bf16 v[0:3], v[182:185], v[226:229], v[158:161]
	v_mfma_f32_16x16x32_bf16 v[0:3], v[186:189], v[234:237], v[0:3]
	s_barrier
	s_andn2_b64 vcc, exec, s[10:11]
	s_cbranch_vccnz .LBB0_1422
	s_barrier

.LBB0_1491:
	s_ashr_i32 s23, s22, 31
	s_lshl_b64 s[24:25], s[22:23], 21
	s_add_u32 s24, s70, s24
	s_addc_u32 s25, s71, s25
	s_and_b64 s[26:27], s[4:5], exec
	s_cselect_b32 s23, s25, s35
	s_cselect_b32 s56, s24, s34
	s_ashr_i32 s21, s20, 31
	s_lshl_b64 s[26:27], s[20:21], 21
	s_add_u32 s26, s72, s26
	s_addc_u32 s27, s76, s27
	s_and_b64 s[36:37], s[4:5], exec
	s_cselect_b32 s21, s27, s31
	s_cselect_b32 s57, s26, s30
	s_add_u32 s58, s30, 0x100
	s_addc_u32 s59, s31, 0
	s_add_u32 s30, s34, 0x100080
	s_addc_u32 s31, s35, 0
	s_mov_b32 s60, -2
	s_waitcnt vmcnt(0)
	s_add_u32 s34, s30, 0xfff00080
	s_addc_u32 s35, s31, -1
	s_add_i32 s61, 0, 0x10000
	s_cmp_eq_u32 s60, 60
	s_cselect_b32 s37, s23, s35
	s_cselect_b32 s36, s56, s34
	s_cselect_b32 s35, s21, s59
	s_cselect_b32 s34, s57, s58
	s_add_i32 s64, 0, 0x14000
	v_add_u32_e32 v100, s61, v220
	v_add_u32_e32 v156, s64, v220
	ds_read_b128 v[88:91], v100
	ds_read_b128 v[92:95], v100 offset:1024
	ds_read_b128 v[96:99], v100 offset:2048
	ds_read_b128 v[100:103], v100 offset:3072
	ds_read_b128 v[144:147], v156
	ds_read_b128 v[148:151], v156 offset:1024
	ds_read_b128 v[152:155], v156 offset:2048
	ds_read_b128 v[156:159], v156 offset:3072
	v_lshl_add_u64 v[202:203], s[30:31], 0, v[188:189]
	s_add_i32 m0, s78, 0xc000
	ds_read_b128 v[160:163], v221
	ds_read_b128 v[164:167], v221 offset:1024
	ds_read_b128 v[168:171], v221 offset:2048
	ds_read_b128 v[172:175], v221 offset:3072
	ds_read_b128 v[176:179], v221 offset:4096
	ds_read_b128 v[190:193], v221 offset:5120
	ds_read_b128 v[194:197], v221 offset:6144
	ds_read_b128 v[198:201], v221 offset:7168
	global_load_lds_dwordx4 v[202:203], off
	v_lshl_add_u64 v[202:203], s[30:31], 0, v[186:187]
	s_add_i32 m0, s78, 0xe000
	s_nop 0
	global_load_lds_dwordx4 v[202:203], off
	s_waitcnt vmcnt(8)
	s_waitcnt lgkmcnt(0)
	s_barrier
	v_mfma_f32_16x16x32_bf16 v[140:143], v[88:91], v[160:163], 0
	v_mfma_f32_16x16x32_bf16 v[136:139], v[96:99], v[160:163], 0
	v_mfma_f32_16x16x32_bf16 v[124:127], v[88:91], v[168:171], 0
	v_mfma_f32_16x16x32_bf16 v[120:123], v[96:99], v[168:171], 0
	v_mfma_f32_16x16x32_bf16 v[108:111], v[88:91], v[176:179], 0
	v_mfma_f32_16x16x32_bf16 v[104:107], v[96:99], v[176:179], 0
	v_mfma_f32_16x16x32_bf16 v[76:79], v[88:91], v[194:197], 0
	v_mfma_f32_16x16x32_bf16 v[72:75], v[96:99], v[194:197], 0
	v_mfma_f32_16x16x32_bf16 v[140:143], v[92:95], v[164:167], v[140:143]
	v_mfma_f32_16x16x32_bf16 v[136:139], v[100:103], v[164:167], v[136:139]
	v_mfma_f32_16x16x32_bf16 v[124:127], v[92:95], v[172:175], v[124:127]
	v_mfma_f32_16x16x32_bf16 v[120:123], v[100:103], v[172:175], v[120:123]
	v_mfma_f32_16x16x32_bf16 v[108:111], v[92:95], v[190:193], v[108:111]
	v_mfma_f32_16x16x32_bf16 v[104:107], v[100:103], v[190:193], v[104:107]
	v_mfma_f32_16x16x32_bf16 v[76:79], v[92:95], v[198:201], v[76:79]
	v_mfma_f32_16x16x32_bf16 v[72:75], v[100:103], v[198:201], v[72:75]
	v_mfma_f32_16x16x32_bf16 v[132:135], v[144:147], v[160:163], 0
	v_mfma_f32_16x16x32_bf16 v[128:131], v[152:155], v[160:163], 0
	v_mfma_f32_16x16x32_bf16 v[116:119], v[144:147], v[168:171], 0
	v_mfma_f32_16x16x32_bf16 v[112:115], v[152:155], v[168:171], 0
	v_mfma_f32_16x16x32_bf16 v[84:87], v[144:147], v[176:179], 0
	v_mfma_f32_16x16x32_bf16 v[80:83], v[152:155], v[176:179], 0
	v_mfma_f32_16x16x32_bf16 v[68:71], v[144:147], v[194:197], 0
	v_mfma_f32_16x16x32_bf16 v[64:67], v[152:155], v[194:197], 0
	v_mfma_f32_16x16x32_bf16 v[132:135], v[148:151], v[164:167], v[132:135]
	v_mfma_f32_16x16x32_bf16 v[128:131], v[156:159], v[164:167], v[128:131]
	v_mfma_f32_16x16x32_bf16 v[116:119], v[148:151], v[172:175], v[116:119]
	v_mfma_f32_16x16x32_bf16 v[112:115], v[156:159], v[172:175], v[112:115]
	v_mfma_f32_16x16x32_bf16 v[84:87], v[148:151], v[190:193], v[84:87]
	v_mfma_f32_16x16x32_bf16 v[80:83], v[156:159], v[190:193], v[80:83]
	v_mfma_f32_16x16x32_bf16 v[68:71], v[148:151], v[198:201], v[68:71]
	v_mfma_f32_16x16x32_bf16 v[64:67], v[156:159], v[198:201], v[64:67]
	s_barrier
	s_add_i32 s61, s61, s77
	v_lshl_add_u64 v[202:203], s[34:35], 0, v[232:233]
	s_mov_b32 m0, s61
	ds_read_b128 v[160:163], v221 offset:16384
	ds_read_b128 v[164:167], v221 offset:17408
	ds_read_b128 v[168:171], v221 offset:18432
	ds_read_b128 v[172:175], v221 offset:19456
	ds_read_b128 v[176:179], v221 offset:20480
	ds_read_b128 v[190:193], v221 offset:21504
	ds_read_b128 v[194:197], v221 offset:22528
	ds_read_b128 v[198:201], v221 offset:23552
	global_load_lds_dwordx4 v[202:203], off
	s_add_i32 m0, s61, 0x2000
	s_add_u32 s62, s34, 0x100000
	v_lshl_add_u64 v[204:205], s[34:35], 0, v[184:185]
	s_addc_u32 s63, s35, 0
	s_add_i32 s61, s64, s77
	global_load_lds_dwordx4 v[204:205], off
	v_lshl_add_u64 v[206:207], s[62:63], 0, v[232:233]
	s_mov_b32 m0, s61
	v_lshl_add_u64 v[208:209], s[36:37], 0, v[182:183]
	global_load_lds_dwordx4 v[206:207], off
	v_lshl_add_u64 v[206:207], s[62:63], 0, v[184:185]
	s_add_i32 m0, s61, 0x2000
	s_nop 0
	global_load_lds_dwordx4 v[206:207], off
	v_lshl_add_u64 v[206:207], s[36:37], 0, v[180:181]
	s_waitcnt vmcnt(6)
	s_waitcnt lgkmcnt(0)
	s_barrier
	v_mfma_f32_16x16x32_bf16 v[60:63], v[88:91], v[160:163], 0
	v_mfma_f32_16x16x32_bf16 v[56:59], v[96:99], v[160:163], 0
	v_mfma_f32_16x16x32_bf16 v[44:47], v[88:91], v[168:171], 0
	v_mfma_f32_16x16x32_bf16 v[40:43], v[96:99], v[168:171], 0
	v_mfma_f32_16x16x32_bf16 v[28:31], v[88:91], v[176:179], 0
	v_mfma_f32_16x16x32_bf16 v[24:27], v[96:99], v[176:179], 0
	v_mfma_f32_16x16x32_bf16 v[12:15], v[88:91], v[194:197], 0
	v_mfma_f32_16x16x32_bf16 v[8:11], v[96:99], v[194:197], 0
	v_mfma_f32_16x16x32_bf16 v[60:63], v[92:95], v[164:167], v[60:63]
	v_mfma_f32_16x16x32_bf16 v[56:59], v[100:103], v[164:167], v[56:59]
	v_mfma_f32_16x16x32_bf16 v[44:47], v[92:95], v[172:175], v[44:47]
	v_mfma_f32_16x16x32_bf16 v[40:43], v[100:103], v[172:175], v[40:43]
	v_mfma_f32_16x16x32_bf16 v[28:31], v[92:95], v[190:193], v[28:31]
	v_mfma_f32_16x16x32_bf16 v[24:27], v[100:103], v[190:193], v[24:27]
	v_mfma_f32_16x16x32_bf16 v[12:15], v[92:95], v[198:201], v[12:15]
	v_mfma_f32_16x16x32_bf16 v[8:11], v[100:103], v[198:201], v[8:11]
	v_mfma_f32_16x16x32_bf16 v[52:55], v[144:147], v[160:163], 0
	v_mfma_f32_16x16x32_bf16 v[48:51], v[152:155], v[160:163], 0
	v_mfma_f32_16x16x32_bf16 v[36:39], v[144:147], v[168:171], 0
	v_mfma_f32_16x16x32_bf16 v[32:35], v[152:155], v[168:171], 0
	v_mfma_f32_16x16x32_bf16 v[20:23], v[144:147], v[176:179], 0
	v_mfma_f32_16x16x32_bf16 v[16:19], v[152:155], v[176:179], 0
	v_mfma_f32_16x16x32_bf16 v[4:7], v[144:147], v[194:197], 0
	v_mfma_f32_16x16x32_bf16 v[0:3], v[152:155], v[194:197], 0
	v_mfma_f32_16x16x32_bf16 v[52:55], v[148:151], v[164:167], v[52:55]
	v_mfma_f32_16x16x32_bf16 v[48:51], v[156:159], v[164:167], v[48:51]
	v_mfma_f32_16x16x32_bf16 v[36:39], v[148:151], v[172:175], v[36:39]
	v_mfma_f32_16x16x32_bf16 v[32:35], v[156:159], v[172:175], v[32:35]
	v_mfma_f32_16x16x32_bf16 v[20:23], v[148:151], v[190:193], v[20:23]
	v_mfma_f32_16x16x32_bf16 v[16:19], v[156:159], v[190:193], v[16:19]
	v_mfma_f32_16x16x32_bf16 v[4:7], v[148:151], v[198:201], v[4:7]
	v_mfma_f32_16x16x32_bf16 v[0:3], v[156:159], v[198:201], v[0:3]
	s_barrier
	s_branch .Lzmid_6
.LBB0_1492:
	s_add_u32 s34, s30, 0xfff00080
	s_addc_u32 s35, s31, -1
	s_add_i32 s61, 0, 0x10000
	s_cmp_eq_u32 s60, 60
	s_cselect_b32 s37, s23, s35
	s_cselect_b32 s36, s56, s34
	s_cselect_b32 s35, s21, s59
	s_cselect_b32 s34, s57, s58
	s_add_i32 s64, 0, 0x14000
	v_add_u32_e32 v100, s61, v220
	v_add_u32_e32 v156, s64, v220
	ds_read_b128 v[88:91], v100
	ds_read_b128 v[92:95], v100 offset:1024
	ds_read_b128 v[96:99], v100 offset:2048
	ds_read_b128 v[100:103], v100 offset:3072
	ds_read_b128 v[144:147], v156
	ds_read_b128 v[148:151], v156 offset:1024
	ds_read_b128 v[152:155], v156 offset:2048
	ds_read_b128 v[156:159], v156 offset:3072
	v_lshl_add_u64 v[202:203], s[30:31], 0, v[188:189]
	s_add_i32 m0, s78, 0xc000
	ds_read_b128 v[160:163], v221
	ds_read_b128 v[164:167], v221 offset:1024
	ds_read_b128 v[168:171], v221 offset:2048
	ds_read_b128 v[172:175], v221 offset:3072
	ds_read_b128 v[176:179], v221 offset:4096
	ds_read_b128 v[190:193], v221 offset:5120
	ds_read_b128 v[194:197], v221 offset:6144
	ds_read_b128 v[198:201], v221 offset:7168
	global_load_lds_dwordx4 v[202:203], off
	v_lshl_add_u64 v[202:203], s[30:31], 0, v[186:187]
	s_add_i32 m0, s78, 0xe000
	s_nop 0
	global_load_lds_dwordx4 v[202:203], off
	s_waitcnt vmcnt(8)
	s_waitcnt lgkmcnt(0)
	s_barrier
	v_mfma_f32_16x16x32_bf16 v[140:143], v[88:91], v[160:163], v[140:143]
	v_mfma_f32_16x16x32_bf16 v[136:139], v[96:99], v[160:163], v[136:139]
	v_mfma_f32_16x16x32_bf16 v[124:127], v[88:91], v[168:171], v[124:127]
	v_mfma_f32_16x16x32_bf16 v[120:123], v[96:99], v[168:171], v[120:123]
	v_mfma_f32_16x16x32_bf16 v[108:111], v[88:91], v[176:179], v[108:111]
	v_mfma_f32_16x16x32_bf16 v[104:107], v[96:99], v[176:179], v[104:107]
	v_mfma_f32_16x16x32_bf16 v[76:79], v[88:91], v[194:197], v[76:79]
	v_mfma_f32_16x16x32_bf16 v[72:75], v[96:99], v[194:197], v[72:75]
	v_mfma_f32_16x16x32_bf16 v[140:143], v[92:95], v[164:167], v[140:143]
	v_mfma_f32_16x16x32_bf16 v[136:139], v[100:103], v[164:167], v[136:139]
	v_mfma_f32_16x16x32_bf16 v[124:127], v[92:95], v[172:175], v[124:127]
	v_mfma_f32_16x16x32_bf16 v[120:123], v[100:103], v[172:175], v[120:123]
	v_mfma_f32_16x16x32_bf16 v[108:111], v[92:95], v[190:193], v[108:111]
	v_mfma_f32_16x16x32_bf16 v[104:107], v[100:103], v[190:193], v[104:107]
	v_mfma_f32_16x16x32_bf16 v[76:79], v[92:95], v[198:201], v[76:79]
	v_mfma_f32_16x16x32_bf16 v[72:75], v[100:103], v[198:201], v[72:75]
	v_mfma_f32_16x16x32_bf16 v[132:135], v[144:147], v[160:163], v[132:135]
	v_mfma_f32_16x16x32_bf16 v[128:131], v[152:155], v[160:163], v[128:131]
	v_mfma_f32_16x16x32_bf16 v[116:119], v[144:147], v[168:171], v[116:119]
	v_mfma_f32_16x16x32_bf16 v[112:115], v[152:155], v[168:171], v[112:115]
	v_mfma_f32_16x16x32_bf16 v[84:87], v[144:147], v[176:179], v[84:87]
	v_mfma_f32_16x16x32_bf16 v[80:83], v[152:155], v[176:179], v[80:83]
	v_mfma_f32_16x16x32_bf16 v[68:71], v[144:147], v[194:197], v[68:71]
	v_mfma_f32_16x16x32_bf16 v[64:67], v[152:155], v[194:197], v[64:67]
	v_mfma_f32_16x16x32_bf16 v[132:135], v[148:151], v[164:167], v[132:135]
	v_mfma_f32_16x16x32_bf16 v[128:131], v[156:159], v[164:167], v[128:131]
	v_mfma_f32_16x16x32_bf16 v[116:119], v[148:151], v[172:175], v[116:119]
	v_mfma_f32_16x16x32_bf16 v[112:115], v[156:159], v[172:175], v[112:115]
	v_mfma_f32_16x16x32_bf16 v[84:87], v[148:151], v[190:193], v[84:87]
	v_mfma_f32_16x16x32_bf16 v[80:83], v[156:159], v[190:193], v[80:83]
	v_mfma_f32_16x16x32_bf16 v[68:71], v[148:151], v[198:201], v[68:71]
	v_mfma_f32_16x16x32_bf16 v[64:67], v[156:159], v[198:201], v[64:67]
	s_barrier
	s_add_i32 s61, s61, s77
	v_lshl_add_u64 v[202:203], s[34:35], 0, v[232:233]
	s_mov_b32 m0, s61
	ds_read_b128 v[160:163], v221 offset:16384
	ds_read_b128 v[164:167], v221 offset:17408
	ds_read_b128 v[168:171], v221 offset:18432
	ds_read_b128 v[172:175], v221 offset:19456
	ds_read_b128 v[176:179], v221 offset:20480
	ds_read_b128 v[190:193], v221 offset:21504
	ds_read_b128 v[194:197], v221 offset:22528
	ds_read_b128 v[198:201], v221 offset:23552
	global_load_lds_dwordx4 v[202:203], off
	s_add_i32 m0, s61, 0x2000
	s_add_u32 s62, s34, 0x100000
	v_lshl_add_u64 v[204:205], s[34:35], 0, v[184:185]
	s_addc_u32 s63, s35, 0
	s_add_i32 s61, s64, s77
	global_load_lds_dwordx4 v[204:205], off
	v_lshl_add_u64 v[206:207], s[62:63], 0, v[232:233]
	s_mov_b32 m0, s61
	v_lshl_add_u64 v[208:209], s[36:37], 0, v[182:183]
	global_load_lds_dwordx4 v[206:207], off
	v_lshl_add_u64 v[206:207], s[62:63], 0, v[184:185]
	s_add_i32 m0, s61, 0x2000
	s_nop 0
	global_load_lds_dwordx4 v[206:207], off
	v_lshl_add_u64 v[206:207], s[36:37], 0, v[180:181]
	s_waitcnt vmcnt(6)
	s_waitcnt lgkmcnt(0)
	s_barrier
	v_mfma_f32_16x16x32_bf16 v[60:63], v[88:91], v[160:163], v[60:63]
	v_mfma_f32_16x16x32_bf16 v[56:59], v[96:99], v[160:163], v[56:59]
	v_mfma_f32_16x16x32_bf16 v[44:47], v[88:91], v[168:171], v[44:47]
	v_mfma_f32_16x16x32_bf16 v[40:43], v[96:99], v[168:171], v[40:43]
	v_mfma_f32_16x16x32_bf16 v[28:31], v[88:91], v[176:179], v[28:31]
	v_mfma_f32_16x16x32_bf16 v[24:27], v[96:99], v[176:179], v[24:27]
	v_mfma_f32_16x16x32_bf16 v[12:15], v[88:91], v[194:197], v[12:15]
	v_mfma_f32_16x16x32_bf16 v[8:11], v[96:99], v[194:197], v[8:11]
	v_mfma_f32_16x16x32_bf16 v[60:63], v[92:95], v[164:167], v[60:63]
	v_mfma_f32_16x16x32_bf16 v[56:59], v[100:103], v[164:167], v[56:59]
	v_mfma_f32_16x16x32_bf16 v[44:47], v[92:95], v[172:175], v[44:47]
	v_mfma_f32_16x16x32_bf16 v[40:43], v[100:103], v[172:175], v[40:43]
	v_mfma_f32_16x16x32_bf16 v[28:31], v[92:95], v[190:193], v[28:31]
	v_mfma_f32_16x16x32_bf16 v[24:27], v[100:103], v[190:193], v[24:27]
	v_mfma_f32_16x16x32_bf16 v[12:15], v[92:95], v[198:201], v[12:15]
	v_mfma_f32_16x16x32_bf16 v[8:11], v[100:103], v[198:201], v[8:11]
	v_mfma_f32_16x16x32_bf16 v[52:55], v[144:147], v[160:163], v[52:55]
	v_mfma_f32_16x16x32_bf16 v[48:51], v[152:155], v[160:163], v[48:51]
	v_mfma_f32_16x16x32_bf16 v[36:39], v[144:147], v[168:171], v[36:39]
	v_mfma_f32_16x16x32_bf16 v[32:35], v[152:155], v[168:171], v[32:35]
	v_mfma_f32_16x16x32_bf16 v[20:23], v[144:147], v[176:179], v[20:23]
	v_mfma_f32_16x16x32_bf16 v[16:19], v[152:155], v[176:179], v[16:19]
	v_mfma_f32_16x16x32_bf16 v[4:7], v[144:147], v[194:197], v[4:7]
	v_mfma_f32_16x16x32_bf16 v[0:3], v[152:155], v[194:197], v[0:3]
	v_mfma_f32_16x16x32_bf16 v[52:55], v[148:151], v[164:167], v[52:55]
	v_mfma_f32_16x16x32_bf16 v[48:51], v[156:159], v[164:167], v[48:51]
	v_mfma_f32_16x16x32_bf16 v[36:39], v[148:151], v[172:175], v[36:39]
	v_mfma_f32_16x16x32_bf16 v[32:35], v[156:159], v[172:175], v[32:35]
	v_mfma_f32_16x16x32_bf16 v[20:23], v[148:151], v[190:193], v[20:23]
	v_mfma_f32_16x16x32_bf16 v[16:19], v[156:159], v[190:193], v[16:19]
	v_mfma_f32_16x16x32_bf16 v[4:7], v[148:151], v[198:201], v[4:7]
	v_mfma_f32_16x16x32_bf16 v[0:3], v[156:159], v[198:201], v[0:3]
	s_barrier
.Lzmid_6:
	s_add_i32 s61, 0, 0x18000
	s_add_i32 s62, 0, 0x1c000
	v_add_u32_e32 v100, s61, v220
	v_add_u32_e32 v156, s62, v220
	ds_read_b128 v[88:91], v100
	ds_read_b128 v[92:95], v100 offset:1024
	ds_read_b128 v[96:99], v100 offset:2048
	ds_read_b128 v[100:103], v100 offset:3072
	ds_read_b128 v[144:147], v156
	ds_read_b128 v[148:151], v156 offset:1024
	ds_read_b128 v[152:155], v156 offset:2048
	ds_read_b128 v[156:159], v156 offset:3072
	s_add_u32 s36, s36, 0x100000
	s_addc_u32 s37, s37, 0
	s_mov_b32 m0, s78
	s_nop 0
	global_load_lds_dwordx4 v[206:207], off
	s_mov_b32 m0, s79
	s_nop 0
	global_load_lds_dwordx4 v[208:209], off
	s_mov_b32 m0, s80
	v_lshl_add_u64 v[210:211], s[36:37], 0, v[180:181]
	ds_read_b128 v[160:163], v221 offset:32768
	ds_read_b128 v[164:167], v221 offset:33792
	ds_read_b128 v[168:171], v221 offset:34816
	ds_read_b128 v[172:175], v221 offset:35840
	ds_read_b128 v[176:179], v221 offset:36864
	ds_read_b128 v[190:193], v221 offset:37888
	ds_read_b128 v[194:197], v221 offset:38912
	ds_read_b128 v[198:201], v221 offset:39936
	global_load_lds_dwordx4 v[210:211], off
	v_lshl_add_u64 v[210:211], s[36:37], 0, v[182:183]
	s_mov_b32 m0, s81
	s_nop 0
	global_load_lds_dwordx4 v[210:211], off
	s_waitcnt vmcnt(8)
	s_waitcnt lgkmcnt(0)
	s_barrier
	v_mfma_f32_16x16x32_bf16 v[140:143], v[88:91], v[160:163], v[140:143]
	v_mfma_f32_16x16x32_bf16 v[136:139], v[96:99], v[160:163], v[136:139]
	v_mfma_f32_16x16x32_bf16 v[124:127], v[88:91], v[168:171], v[124:127]
	v_mfma_f32_16x16x32_bf16 v[120:123], v[96:99], v[168:171], v[120:123]
	v_mfma_f32_16x16x32_bf16 v[108:111], v[88:91], v[176:179], v[108:111]
	v_mfma_f32_16x16x32_bf16 v[104:107], v[96:99], v[176:179], v[104:107]
	v_mfma_f32_16x16x32_bf16 v[76:79], v[88:91], v[194:197], v[76:79]
	v_mfma_f32_16x16x32_bf16 v[72:75], v[96:99], v[194:197], v[72:75]
	v_mfma_f32_16x16x32_bf16 v[140:143], v[92:95], v[164:167], v[140:143]
	v_mfma_f32_16x16x32_bf16 v[136:139], v[100:103], v[164:167], v[136:139]
	v_mfma_f32_16x16x32_bf16 v[124:127], v[92:95], v[172:175], v[124:127]
	v_mfma_f32_16x16x32_bf16 v[120:123], v[100:103], v[172:175], v[120:123]
	v_mfma_f32_16x16x32_bf16 v[108:111], v[92:95], v[190:193], v[108:111]
	v_mfma_f32_16x16x32_bf16 v[104:107], v[100:103], v[190:193], v[104:107]
	v_mfma_f32_16x16x32_bf16 v[76:79], v[92:95], v[198:201], v[76:79]
	v_mfma_f32_16x16x32_bf16 v[72:75], v[100:103], v[198:201], v[72:75]
	v_mfma_f32_16x16x32_bf16 v[132:135], v[144:147], v[160:163], v[132:135]
	v_mfma_f32_16x16x32_bf16 v[128:131], v[152:155], v[160:163], v[128:131]
	v_mfma_f32_16x16x32_bf16 v[116:119], v[144:147], v[168:171], v[116:119]
	v_mfma_f32_16x16x32_bf16 v[112:115], v[152:155], v[168:171], v[112:115]
	v_mfma_f32_16x16x32_bf16 v[84:87], v[144:147], v[176:179], v[84:87]
	v_mfma_f32_16x16x32_bf16 v[80:83], v[152:155], v[176:179], v[80:83]
	v_mfma_f32_16x16x32_bf16 v[68:71], v[144:147], v[194:197], v[68:71]
	v_mfma_f32_16x16x32_bf16 v[64:67], v[152:155], v[194:197], v[64:67]
	v_mfma_f32_16x16x32_bf16 v[132:135], v[148:151], v[164:167], v[132:135]
	v_mfma_f32_16x16x32_bf16 v[128:131], v[156:159], v[164:167], v[128:131]
	v_mfma_f32_16x16x32_bf16 v[116:119], v[148:151], v[172:175], v[116:119]
	v_mfma_f32_16x16x32_bf16 v[112:115], v[156:159], v[172:175], v[112:115]
	v_mfma_f32_16x16x32_bf16 v[84:87], v[148:151], v[190:193], v[84:87]
	v_mfma_f32_16x16x32_bf16 v[80:83], v[156:159], v[190:193], v[80:83]
	v_mfma_f32_16x16x32_bf16 v[68:71], v[148:151], v[198:201], v[68:71]
	v_mfma_f32_16x16x32_bf16 v[64:67], v[156:159], v[198:201], v[64:67]
	s_barrier
	s_add_i32 s36, s61, s77
	v_lshl_add_u64 v[202:203], v[202:203], 0, s[94:95]
	s_mov_b32 m0, s36
	ds_read_b128 v[160:163], v221 offset:49152
	ds_read_b128 v[164:167], v221 offset:50176
	ds_read_b128 v[168:171], v221 offset:51200
	ds_read_b128 v[172:175], v221 offset:52224
	ds_read_b128 v[176:179], v221 offset:53248
	ds_read_b128 v[190:193], v221 offset:54272
	ds_read_b128 v[194:197], v221 offset:55296
	ds_read_b128 v[198:201], v221 offset:56320
	global_load_lds_dwordx4 v[202:203], off
	s_add_i32 m0, s36, 0x2000
	s_add_u32 s34, s34, 0x100080
	v_lshl_add_u64 v[202:203], v[204:205], 0, s[94:95]
	s_addc_u32 s35, s35, 0
	s_add_i32 s36, s62, s77
	global_load_lds_dwordx4 v[202:203], off
	v_lshl_add_u64 v[202:203], s[34:35], 0, v[232:233]
	s_mov_b32 m0, s36
	s_nop 0
	global_load_lds_dwordx4 v[202:203], off
	v_lshl_add_u64 v[202:203], s[34:35], 0, v[184:185]
	s_add_i32 m0, s36, 0x2000
	s_nop 0
	global_load_lds_dwordx4 v[202:203], off
	v_lshl_add_u64 v[202:203], v[206:207], 0, s[94:95]
	s_mov_b32 m0, s52
	s_nop 0
	global_load_lds_dwordx4 v[202:203], off
	v_lshl_add_u64 v[202:203], v[208:209], 0, s[94:95]
	s_mov_b32 m0, s53
	s_nop 0
	global_load_lds_dwordx4 v[202:203], off
	s_waitcnt vmcnt(8)
	s_waitcnt lgkmcnt(0)
	s_barrier
	v_mfma_f32_16x16x32_bf16 v[60:63], v[88:91], v[160:163], v[60:63]
	v_mfma_f32_16x16x32_bf16 v[56:59], v[96:99], v[160:163], v[56:59]
	v_mfma_f32_16x16x32_bf16 v[44:47], v[88:91], v[168:171], v[44:47]
	v_mfma_f32_16x16x32_bf16 v[40:43], v[96:99], v[168:171], v[40:43]
	v_mfma_f32_16x16x32_bf16 v[28:31], v[88:91], v[176:179], v[28:31]
	v_mfma_f32_16x16x32_bf16 v[24:27], v[96:99], v[176:179], v[24:27]
	v_mfma_f32_16x16x32_bf16 v[12:15], v[88:91], v[194:197], v[12:15]
	v_mfma_f32_16x16x32_bf16 v[8:11], v[96:99], v[194:197], v[8:11]
	v_mfma_f32_16x16x32_bf16 v[60:63], v[92:95], v[164:167], v[60:63]
	v_mfma_f32_16x16x32_bf16 v[56:59], v[100:103], v[164:167], v[56:59]
	v_mfma_f32_16x16x32_bf16 v[44:47], v[92:95], v[172:175], v[44:47]
	v_mfma_f32_16x16x32_bf16 v[40:43], v[100:103], v[172:175], v[40:43]
	v_mfma_f32_16x16x32_bf16 v[28:31], v[92:95], v[190:193], v[28:31]
	v_mfma_f32_16x16x32_bf16 v[24:27], v[100:103], v[190:193], v[24:27]
	v_mfma_f32_16x16x32_bf16 v[12:15], v[92:95], v[198:201], v[12:15]
	v_mfma_f32_16x16x32_bf16 v[8:11], v[100:103], v[198:201], v[8:11]
	v_mfma_f32_16x16x32_bf16 v[52:55], v[144:147], v[160:163], v[52:55]
	v_mfma_f32_16x16x32_bf16 v[48:51], v[152:155], v[160:163], v[48:51]
	v_mfma_f32_16x16x32_bf16 v[36:39], v[144:147], v[168:171], v[36:39]
	v_mfma_f32_16x16x32_bf16 v[32:35], v[152:155], v[168:171], v[32:35]
	v_mfma_f32_16x16x32_bf16 v[20:23], v[144:147], v[176:179], v[20:23]
	v_mfma_f32_16x16x32_bf16 v[16:19], v[152:155], v[176:179], v[16:19]
	v_mfma_f32_16x16x32_bf16 v[4:7], v[144:147], v[194:197], v[4:7]
	v_mfma_f32_16x16x32_bf16 v[0:3], v[152:155], v[194:197], v[0:3]
	v_mfma_f32_16x16x32_bf16 v[52:55], v[148:151], v[164:167], v[52:55]
	v_mfma_f32_16x16x32_bf16 v[48:51], v[156:159], v[164:167], v[48:51]
	v_mfma_f32_16x16x32_bf16 v[36:39], v[148:151], v[172:175], v[36:39]
	v_mfma_f32_16x16x32_bf16 v[32:35], v[156:159], v[172:175], v[32:35]
	v_mfma_f32_16x16x32_bf16 v[20:23], v[148:151], v[190:193], v[20:23]
	v_mfma_f32_16x16x32_bf16 v[16:19], v[156:159], v[190:193], v[16:19]
	v_mfma_f32_16x16x32_bf16 v[4:7], v[148:151], v[198:201], v[4:7]
	v_mfma_f32_16x16x32_bf16 v[0:3], v[156:159], v[198:201], v[0:3]
	s_barrier
	s_add_i32 s60, s60, 2
	s_add_u32 s58, s58, 0x100
	s_addc_u32 s59, s59, 0
	s_add_u32 s30, s30, 0x100
	s_addc_u32 s31, s31, 0
	s_cmp_gt_u32 s60, 61
	s_cbranch_scc0 .LBB0_1492
	s_and_b64 vcc, exec, s[18:19]
	s_cbranch_vccz .LBB0_1495
	s_barrier
